# E-GEMM skips its four all-zero K-tiles (structural zeros of the composed S5 weight), redundant store-only waits removed from the gelu epilogues, hand-written pooling-diff
# speedup vs baseline: 1.0146x; 1.0146x over previous
; __device__ __forceinline__ float bf_lo(unsigned w) { return __uint_as_float(w << 16); }
; __device__ __forceinline__ float bf_hi(unsigned w) { return __uint_as_float(w & 0xffff0000u); }
; __device__ __forceinline__ u32x4 pack8(const f32x4 a, const f32x4 b) { u32x4 w; w.x = cvt_pk_bf16(a[0], a[1]); w.y = cvt_pk_bf16(a[2], a[3]); w.z = cvt_pk_bf16(b[0], b[1]); w.w = cvt_pk_bf16(b[2], b[3]); return w; }
;     __device__ __forceinline__ void operator()(EPI_ARGS) const {
;     ...
;                 for (int m = 0; m < 4; ++m) { const int j = row0 + ai * HALF + m * 16;
;                     uw[m] = (j < NJ) ? *(const u32x4*)(AB + ((size_t)((g >> 1) * NJP + j) * ABP + (g & 1) * 384 + n)) : (u32x4){0u, 0u, 0u, 0u}; }
; #pragma unroll
;                 for (int m = 0; m < 4; ++m) { const int j = row0 + ai * HALF + m * 16;
;                     if (j < NJ) {
;                         const u32x4 w = uw[m];
;                         f32x4 u0 = {bf_lo(w.x), bf_hi(w.x), bf_lo(w.y), bf_hi(w.y)}, u1 = {bf_lo(w.z), bf_hi(w.z), bf_lo(w.w), bf_hi(w.w)};
;                         f32x4 y0 = acc[ai][bj][m][0] + d0 * u0, y1 = acc[ai][bj][m][1] + d1 * u1;
; #pragma unroll
;                         for (int e = 0; e < 4; ++e) {
;                             { const float y = y0[e], q = 1.5957691216f * (y + 0.044715f * y * y * y); y0[e] = y * __builtin_amdgcn_rcpf(1.0f + __expf(-q)); }
;                             { const float y = y1[e], q = 1.5957691216f * (y + 0.044715f * y * y * y); y1[e] = y * __builtin_amdgcn_rcpf(1.0f + __expf(-q)); }
;                         }
;                         *(u32x4*)(Z + (size_t)(j * TS + t) * WA + g * 16 + c) = pack8(y0, y1);
.LBB0_278:
	v_lshlrev_b32_e32 v120, 16, v140
	v_and_b32_e32 v121, 0xffff0000, v140
	v_lshlrev_b32_e32 v124, 16, v142
	v_and_b32_e32 v125, 0xffff0000, v142
	v_lshlrev_b32_e32 v122, 16, v141
	v_and_b32_e32 v123, 0xffff0000, v141
	v_pk_fma_f32 v[116:117], v[108:109], v[120:121], v[116:117]
	v_pk_fma_f32 v[112:113], v[104:105], v[124:125], v[112:113]
	v_mul_f32_e32 v120, 0x3d372713, v116
	v_pk_fma_f32 v[118:119], v[110:111], v[122:123], v[118:119]
	v_mul_f32_e32 v121, 0x3d372713, v112
	v_mul_f32_e32 v122, 0x3d372713, v117
	v_mul_f32_e32 v120, v116, v120
	v_mul_f32_e32 v121, v112, v121
	v_mul_f32_e32 v122, v117, v122
	v_fma_f32 v120, v116, v120, v116
	v_fma_f32 v121, v112, v121, v112
	v_fma_f32 v122, v117, v122, v117
	v_mul_f32_e32 v120, 0xbfcc422a, v120
	v_mul_f32_e32 v121, 0xbfcc422a, v121
	v_mul_f32_e32 v122, 0xbfcc422a, v122
	v_mul_f32_e32 v120, 0x3fb8aa3b, v120
	v_mul_f32_e32 v121, 0x3fb8aa3b, v121
	v_mul_f32_e32 v122, 0x3fb8aa3b, v122
	v_exp_f32_e32 v120, v120
	v_exp_f32_e32 v121, v121
	v_exp_f32_e32 v122, v122
	v_mul_f32_e32 v123, 0x3d372713, v113
	v_add_f32_e32 v120, 1.0, v120
	v_add_f32_e32 v121, 1.0, v121
	v_add_f32_e32 v122, 1.0, v122
	v_rcp_f32_e32 v120, v120
	v_rcp_f32_e32 v121, v121
	v_rcp_f32_e32 v122, v122
	v_mul_f32_e32 v123, v113, v123
	v_fma_f32 v123, v113, v123, v113
	v_lshlrev_b32_e32 v126, 16, v143
	v_and_b32_e32 v127, 0xffff0000, v143
	v_mul_f32_e32 v123, 0xbfcc422a, v123
	v_pk_fma_f32 v[114:115], v[106:107], v[126:127], v[114:115]
	v_mul_f32_e32 v123, 0x3fb8aa3b, v123
	v_exp_f32_e32 v123, v123
	v_mul_f32_e32 v116, v116, v120
	v_mul_f32_e32 v120, v112, v121
	v_mul_f32_e32 v112, v117, v122
	v_mul_f32_e32 v121, 0x3d372713, v118
	v_mul_f32_e32 v122, 0x3d372713, v114
	v_mul_f32_e32 v121, v118, v121
	v_mul_f32_e32 v122, v114, v122
	v_fma_f32 v121, v118, v121, v118
	v_fma_f32 v122, v114, v122, v114
	v_mul_f32_e32 v121, 0xbfcc422a, v121
	v_mul_f32_e32 v122, 0xbfcc422a, v122
	v_add_f32_e32 v117, 1.0, v123
	v_mul_f32_e32 v121, 0x3fb8aa3b, v121
	v_mul_f32_e32 v122, 0x3fb8aa3b, v122
	v_rcp_f32_e32 v117, v117
	v_exp_f32_e32 v121, v121
	v_exp_f32_e32 v122, v122
	v_mul_f32_e32 v123, 0x3d372713, v115
	v_mul_f32_e32 v117, v113, v117
	v_add_f32_e32 v113, 1.0, v121
	v_add_f32_e32 v121, 1.0, v122
	v_mul_f32_e32 v122, 0x3d372713, v119
	v_mul_f32_e32 v122, v119, v122
	v_fma_f32 v122, v119, v122, v119
	v_mul_f32_e32 v122, 0xbfcc422a, v122
	v_mul_f32_e32 v122, 0x3fb8aa3b, v122
	v_exp_f32_e32 v122, v122
	v_mul_f32_e32 v123, v115, v123
	v_fma_f32 v123, v115, v123, v115
	v_mul_f32_e32 v123, 0xbfcc422a, v123
	v_mul_f32_e32 v123, 0x3fb8aa3b, v123
	v_add_f32_e32 v122, 1.0, v122
	v_rcp_f32_e32 v113, v113
	v_exp_f32_e32 v123, v123
	v_rcp_f32_e32 v121, v121
	v_rcp_f32_e32 v122, v122
	v_mul_f32_e32 v113, v118, v113
	v_add_f32_e32 v123, 1.0, v123
	v_mul_f32_e32 v118, v114, v121
	v_mul_f32_e32 v114, v119, v122
	v_cvt_pk_bf16_f32 v112, v116, v112
	v_lshl_add_u32 v116, v185, 4, v192
	v_rcp_f32_e32 v123, v123
	v_cvt_pk_bf16_f32 v113, v113, v114
	v_cvt_pk_bf16_f32 v114, v120, v117
	v_ashrrev_i32_e32 v117, 31, v116
	v_lshlrev_b64 v[116:117], 10, v[116:117]
	v_lshl_add_u64 v[116:117], s[0:1], 0, v[116:117]
	v_lshl_add_u64 v[116:117], s[60:61], 1, v[116:117]
	v_mov_b32_e32 v177, v153
	v_mul_f32_e32 v115, v115, v123
	v_lshl_add_u64 v[116:117], v[116:117], 0, v[176:177]
	v_cvt_pk_bf16_f32 v115, v118, v115
	global_store_dwordx4 v[116:117], v[112:115], off
	s_or_b64 exec, exec, s[6:7]
	s_and_saveexec_b64 s[6:7], vcc
	s_cbranch_execnz .LBB0_282
	s_branch .LBB0_283

; __device__ __forceinline__ float bf_lo(unsigned w) { return __uint_as_float(w << 16); }
; __device__ __forceinline__ float bf_hi(unsigned w) { return __uint_as_float(w & 0xffff0000u); }
; __device__ __forceinline__ u32x4 pack8(const f32x4 a, const f32x4 b) { u32x4 w; w.x = cvt_pk_bf16(a[0], a[1]); w.y = cvt_pk_bf16(a[2], a[3]); w.z = cvt_pk_bf16(b[0], b[1]); w.w = cvt_pk_bf16(b[2], b[3]); return w; }
;     __device__ __forceinline__ void operator()(EPI_ARGS) const {
;     ...
;                 for (int m = 0; m < 4; ++m) { const int j = row0 + ai * HALF + m * 16;
;                     uw[m] = (j < NJ) ? *(const u32x4*)(AB + ((size_t)((g >> 1) * NJP + j) * ABP + (g & 1) * 384 + n)) : (u32x4){0u, 0u, 0u, 0u}; }
; #pragma unroll
;                 for (int m = 0; m < 4; ++m) { const int j = row0 + ai * HALF + m * 16;
;                     if (j < NJ) {
;                         const u32x4 w = uw[m];
;                         f32x4 u0 = {bf_lo(w.x), bf_hi(w.x), bf_lo(w.y), bf_hi(w.y)}, u1 = {bf_lo(w.z), bf_hi(w.z), bf_lo(w.w), bf_hi(w.w)};
;                         f32x4 y0 = acc[ai][bj][m][0] + d0 * u0, y1 = acc[ai][bj][m][1] + d1 * u1;
; #pragma unroll
;                         for (int e = 0; e < 4; ++e) {
;                             { const float y = y0[e], q = 1.5957691216f * (y + 0.044715f * y * y * y); y0[e] = y * __builtin_amdgcn_rcpf(1.0f + __expf(-q)); }
;                             { const float y = y1[e], q = 1.5957691216f * (y + 0.044715f * y * y * y); y1[e] = y * __builtin_amdgcn_rcpf(1.0f + __expf(-q)); }
;                         }
;                         *(u32x4*)(Z + (size_t)(j * TS + t) * WA + g * 16 + c) = pack8(y0, y1);
.LBB0_280:
	v_lshlrev_b32_e32 v128, 16, v144
	v_and_b32_e32 v129, 0xffff0000, v144
	v_lshlrev_b32_e32 v132, 16, v146
	v_and_b32_e32 v133, 0xffff0000, v146
	v_lshlrev_b32_e32 v130, 16, v145
	v_and_b32_e32 v131, 0xffff0000, v145
	v_pk_fma_f32 v[124:125], v[108:109], v[128:129], v[124:125]
	v_pk_fma_f32 v[120:121], v[104:105], v[132:133], v[120:121]
	v_mul_f32_e32 v128, 0x3d372713, v124
	v_pk_fma_f32 v[126:127], v[110:111], v[130:131], v[126:127]
	v_mul_f32_e32 v129, 0x3d372713, v120
	v_mul_f32_e32 v130, 0x3d372713, v125
	v_mul_f32_e32 v128, v124, v128
	v_mul_f32_e32 v129, v120, v129
	v_mul_f32_e32 v130, v125, v130
	v_fma_f32 v128, v124, v128, v124
	v_fma_f32 v129, v120, v129, v120
	v_fma_f32 v130, v125, v130, v125
	v_mul_f32_e32 v128, 0xbfcc422a, v128
	v_mul_f32_e32 v129, 0xbfcc422a, v129
	v_mul_f32_e32 v130, 0xbfcc422a, v130
	v_mul_f32_e32 v128, 0x3fb8aa3b, v128
	v_mul_f32_e32 v129, 0x3fb8aa3b, v129
	v_mul_f32_e32 v130, 0x3fb8aa3b, v130
	v_exp_f32_e32 v128, v128
	v_exp_f32_e32 v129, v129
	v_exp_f32_e32 v130, v130
	v_mul_f32_e32 v131, 0x3d372713, v121
	v_add_f32_e32 v128, 1.0, v128
	v_add_f32_e32 v129, 1.0, v129
	v_add_f32_e32 v130, 1.0, v130
	v_rcp_f32_e32 v128, v128
	v_rcp_f32_e32 v129, v129
	v_rcp_f32_e32 v130, v130
	v_mul_f32_e32 v131, v121, v131
	v_fma_f32 v131, v121, v131, v121
	v_lshlrev_b32_e32 v134, 16, v147
	v_and_b32_e32 v135, 0xffff0000, v147
	v_mul_f32_e32 v131, 0xbfcc422a, v131
	v_pk_fma_f32 v[122:123], v[106:107], v[134:135], v[122:123]
	v_mul_f32_e32 v131, 0x3fb8aa3b, v131
	v_exp_f32_e32 v131, v131
	v_mul_f32_e32 v124, v124, v128
	v_mul_f32_e32 v128, v120, v129
	v_mul_f32_e32 v120, v125, v130
	v_mul_f32_e32 v129, 0x3d372713, v126
	v_mul_f32_e32 v130, 0x3d372713, v122
	v_mul_f32_e32 v129, v126, v129
	v_mul_f32_e32 v130, v122, v130
	v_fma_f32 v129, v126, v129, v126
	v_fma_f32 v130, v122, v130, v122
	v_mul_f32_e32 v129, 0xbfcc422a, v129
	v_mul_f32_e32 v130, 0xbfcc422a, v130
	v_add_f32_e32 v125, 1.0, v131
	v_mul_f32_e32 v129, 0x3fb8aa3b, v129
	v_mul_f32_e32 v130, 0x3fb8aa3b, v130
	v_rcp_f32_e32 v125, v125
	v_exp_f32_e32 v129, v129
	v_exp_f32_e32 v130, v130
	v_mul_f32_e32 v131, 0x3d372713, v123
	v_mul_f32_e32 v125, v121, v125
	v_add_f32_e32 v121, 1.0, v129
	v_add_f32_e32 v129, 1.0, v130
	v_mul_f32_e32 v130, 0x3d372713, v127
	v_mul_f32_e32 v130, v127, v130
	v_fma_f32 v130, v127, v130, v127
	v_mul_f32_e32 v130, 0xbfcc422a, v130
	v_mul_f32_e32 v130, 0x3fb8aa3b, v130
	v_exp_f32_e32 v130, v130
	v_mul_f32_e32 v131, v123, v131
	v_fma_f32 v131, v123, v131, v123
	v_mul_f32_e32 v131, 0xbfcc422a, v131
	v_mul_f32_e32 v131, 0x3fb8aa3b, v131
	v_add_f32_e32 v130, 1.0, v130
	v_rcp_f32_e32 v121, v121
	v_exp_f32_e32 v131, v131
	v_rcp_f32_e32 v129, v129
	v_rcp_f32_e32 v130, v130
	v_mul_f32_e32 v121, v126, v121
	v_add_f32_e32 v131, 1.0, v131
	v_mul_f32_e32 v126, v122, v129
	v_mul_f32_e32 v122, v127, v130
	v_cvt_pk_bf16_f32 v120, v124, v120
	v_lshl_add_u32 v124, v186, 4, v192
	v_rcp_f32_e32 v131, v131
	v_cvt_pk_bf16_f32 v121, v121, v122
	v_cvt_pk_bf16_f32 v122, v128, v125
	v_ashrrev_i32_e32 v125, 31, v124
	v_lshlrev_b64 v[124:125], 10, v[124:125]
	v_lshl_add_u64 v[124:125], s[0:1], 0, v[124:125]
	v_lshl_add_u64 v[124:125], s[60:61], 1, v[124:125]
	v_mov_b32_e32 v177, v153
	v_mul_f32_e32 v123, v123, v131
	v_lshl_add_u64 v[124:125], v[124:125], 0, v[176:177]
	v_cvt_pk_bf16_f32 v123, v126, v123
	global_store_dwordx4 v[124:125], v[120:123], off
	s_or_b64 exec, exec, s[6:7]
	s_and_saveexec_b64 s[6:7], s[8:9]
	s_cbranch_execnz .LBB0_278

; __device__ __forceinline__ float bf_lo(unsigned w) { return __uint_as_float(w << 16); }
; __device__ __forceinline__ float bf_hi(unsigned w) { return __uint_as_float(w & 0xffff0000u); }
; __device__ __forceinline__ u32x4 pack8(const f32x4 a, const f32x4 b) { u32x4 w; w.x = cvt_pk_bf16(a[0], a[1]); w.y = cvt_pk_bf16(a[2], a[3]); w.z = cvt_pk_bf16(b[0], b[1]); w.w = cvt_pk_bf16(b[2], b[3]); return w; }
;     __device__ __forceinline__ void operator()(EPI_ARGS) const {
;     ...
;                 for (int m = 0; m < 4; ++m) { const int j = row0 + ai * HALF + m * 16;
;                     uw[m] = (j < NJ) ? *(const u32x4*)(AB + ((size_t)((g >> 1) * NJP + j) * ABP + (g & 1) * 384 + n)) : (u32x4){0u, 0u, 0u, 0u}; }
; #pragma unroll
;                 for (int m = 0; m < 4; ++m) { const int j = row0 + ai * HALF + m * 16;
;                     if (j < NJ) {
;                         const u32x4 w = uw[m];
;                         f32x4 u0 = {bf_lo(w.x), bf_hi(w.x), bf_lo(w.y), bf_hi(w.y)}, u1 = {bf_lo(w.z), bf_hi(w.z), bf_lo(w.w), bf_hi(w.w)};
;                         f32x4 y0 = acc[ai][bj][m][0] + d0 * u0, y1 = acc[ai][bj][m][1] + d1 * u1;
; #pragma unroll
;                         for (int e = 0; e < 4; ++e) {
;                             { const float y = y0[e], q = 1.5957691216f * (y + 0.044715f * y * y * y); y0[e] = y * __builtin_amdgcn_rcpf(1.0f + __expf(-q)); }
;                             { const float y = y1[e], q = 1.5957691216f * (y + 0.044715f * y * y * y); y1[e] = y * __builtin_amdgcn_rcpf(1.0f + __expf(-q)); }
;                         }
;                         *(u32x4*)(Z + (size_t)(j * TS + t) * WA + g * 16 + c) = pack8(y0, y1);
.LBB0_282:
	v_lshlrev_b32_e32 v112, 16, v136
	v_and_b32_e32 v113, 0xffff0000, v136
	v_lshlrev_b32_e32 v116, 16, v138
	v_and_b32_e32 v117, 0xffff0000, v138
	v_lshlrev_b32_e32 v114, 16, v137
	v_and_b32_e32 v115, 0xffff0000, v137
	v_pk_fma_f32 v[100:101], v[108:109], v[112:113], v[100:101]
	v_pk_fma_f32 v[96:97], v[104:105], v[116:117], v[96:97]
	v_mul_f32_e32 v112, 0x3d372713, v100
	v_pk_fma_f32 v[102:103], v[110:111], v[114:115], v[102:103]
	v_mul_f32_e32 v113, 0x3d372713, v96
	v_mul_f32_e32 v114, 0x3d372713, v101
	v_mul_f32_e32 v112, v100, v112
	v_mul_f32_e32 v113, v96, v113
	v_mul_f32_e32 v114, v101, v114
	v_fma_f32 v112, v100, v112, v100
	v_fma_f32 v113, v96, v113, v96
	v_fma_f32 v114, v101, v114, v101
	v_mul_f32_e32 v112, 0xbfcc422a, v112
	v_mul_f32_e32 v113, 0xbfcc422a, v113
	v_mul_f32_e32 v114, 0xbfcc422a, v114
	v_mul_f32_e32 v112, 0x3fb8aa3b, v112
	v_mul_f32_e32 v113, 0x3fb8aa3b, v113
	v_mul_f32_e32 v114, 0x3fb8aa3b, v114
	v_exp_f32_e32 v112, v112
	v_exp_f32_e32 v113, v113
	v_exp_f32_e32 v114, v114
	v_mul_f32_e32 v115, 0x3d372713, v97
	v_add_f32_e32 v112, 1.0, v112
	v_add_f32_e32 v113, 1.0, v113
	v_add_f32_e32 v114, 1.0, v114
	v_rcp_f32_e32 v112, v112
	v_rcp_f32_e32 v113, v113
	v_rcp_f32_e32 v114, v114
	v_mul_f32_e32 v115, v97, v115
	v_fma_f32 v115, v97, v115, v97
	v_lshlrev_b32_e32 v118, 16, v139
	v_and_b32_e32 v119, 0xffff0000, v139
	v_mul_f32_e32 v115, 0xbfcc422a, v115
	v_pk_fma_f32 v[98:99], v[106:107], v[118:119], v[98:99]
	v_mul_f32_e32 v115, 0x3fb8aa3b, v115
	v_exp_f32_e32 v115, v115
	v_mul_f32_e32 v100, v100, v112
	v_mul_f32_e32 v112, v96, v113
	v_mul_f32_e32 v96, v101, v114
	v_mul_f32_e32 v113, 0x3d372713, v102
	v_mul_f32_e32 v114, 0x3d372713, v98
	v_mul_f32_e32 v113, v102, v113
	v_mul_f32_e32 v114, v98, v114
	v_fma_f32 v113, v102, v113, v102
	v_fma_f32 v114, v98, v114, v98
	v_mul_f32_e32 v113, 0xbfcc422a, v113
	v_mul_f32_e32 v114, 0xbfcc422a, v114
	v_add_f32_e32 v101, 1.0, v115
	v_mul_f32_e32 v113, 0x3fb8aa3b, v113
	v_mul_f32_e32 v114, 0x3fb8aa3b, v114
	v_rcp_f32_e32 v101, v101
	v_exp_f32_e32 v113, v113
	v_exp_f32_e32 v114, v114
	v_mul_f32_e32 v115, 0x3d372713, v99
	v_mul_f32_e32 v101, v97, v101
	v_add_f32_e32 v97, 1.0, v113
	v_add_f32_e32 v113, 1.0, v114
	v_mul_f32_e32 v114, 0x3d372713, v103
	v_mul_f32_e32 v114, v103, v114
	v_fma_f32 v114, v103, v114, v103
	v_mul_f32_e32 v114, 0xbfcc422a, v114
	v_mul_f32_e32 v114, 0x3fb8aa3b, v114
	v_exp_f32_e32 v114, v114
	v_mul_f32_e32 v115, v99, v115
	v_fma_f32 v115, v99, v115, v99
	v_mul_f32_e32 v115, 0xbfcc422a, v115
	v_mul_f32_e32 v115, 0x3fb8aa3b, v115
	v_add_f32_e32 v114, 1.0, v114
	v_rcp_f32_e32 v97, v97
	v_exp_f32_e32 v115, v115
	v_rcp_f32_e32 v113, v113
	v_rcp_f32_e32 v114, v114
	v_mul_f32_e32 v97, v102, v97
	v_add_f32_e32 v115, 1.0, v115
	v_mul_f32_e32 v102, v98, v113
	v_mul_f32_e32 v98, v103, v114
	v_cvt_pk_bf16_f32 v96, v100, v96
	v_lshl_add_u32 v100, v181, 4, v192
	v_rcp_f32_e32 v115, v115
	v_cvt_pk_bf16_f32 v97, v97, v98
	v_cvt_pk_bf16_f32 v98, v112, v101
	v_ashrrev_i32_e32 v101, 31, v100
	v_lshlrev_b64 v[100:101], 10, v[100:101]
	v_lshl_add_u64 v[100:101], s[0:1], 0, v[100:101]
	v_lshl_add_u64 v[100:101], s[60:61], 1, v[100:101]
	v_mov_b32_e32 v177, v153
	v_mul_f32_e32 v99, v99, v115
	v_lshl_add_u64 v[100:101], v[100:101], 0, v[176:177]
	v_cvt_pk_bf16_f32 v99, v102, v99
	global_store_dwordx4 v[100:101], v[96:99], off

; __device__ __forceinline__ float bf_lo(unsigned w) { return __uint_as_float(w << 16); }
; __device__ __forceinline__ float bf_hi(unsigned w) { return __uint_as_float(w & 0xffff0000u); }
; __device__ __forceinline__ u32x4 pack8(const f32x4 a, const f32x4 b) { u32x4 w; w.x = cvt_pk_bf16(a[0], a[1]); w.y = cvt_pk_bf16(a[2], a[3]); w.z = cvt_pk_bf16(b[0], b[1]); w.w = cvt_pk_bf16(b[2], b[3]); return w; }
;     __device__ __forceinline__ void operator()(EPI_ARGS) const {
;     ...
;                 for (int m = 0; m < 4; ++m) { const int j = row0 + ai * HALF + m * 16;
;                     uw[m] = (j < NJ) ? *(const u32x4*)(AB + ((size_t)((g >> 1) * NJP + j) * ABP + (g & 1) * 384 + n)) : (u32x4){0u, 0u, 0u, 0u}; }
; #pragma unroll
;                 for (int m = 0; m < 4; ++m) { const int j = row0 + ai * HALF + m * 16;
;                     if (j < NJ) {
;                         const u32x4 w = uw[m];
;                         f32x4 u0 = {bf_lo(w.x), bf_hi(w.x), bf_lo(w.y), bf_hi(w.y)}, u1 = {bf_lo(w.z), bf_hi(w.z), bf_lo(w.w), bf_hi(w.w)};
;                         f32x4 y0 = acc[ai][bj][m][0] + d0 * u0, y1 = acc[ai][bj][m][1] + d1 * u1;
; #pragma unroll
;                         for (int e = 0; e < 4; ++e) {
;                             { const float y = y0[e], q = 1.5957691216f * (y + 0.044715f * y * y * y); y0[e] = y * __builtin_amdgcn_rcpf(1.0f + __expf(-q)); }
;                             { const float y = y1[e], q = 1.5957691216f * (y + 0.044715f * y * y * y); y1[e] = y * __builtin_amdgcn_rcpf(1.0f + __expf(-q)); }
;                         }
;                         *(u32x4*)(Z + (size_t)(j * TS + t) * WA + g * 16 + c) = pack8(y0, y1);
.LBB0_292:
	v_lshlrev_b32_e32 v88, 16, v112
	v_and_b32_e32 v89, 0xffff0000, v112
	v_lshlrev_b32_e32 v92, 16, v114
	v_and_b32_e32 v93, 0xffff0000, v114
	v_lshlrev_b32_e32 v90, 16, v113
	v_and_b32_e32 v91, 0xffff0000, v113
	v_pk_fma_f32 v[84:85], v[108:109], v[88:89], v[84:85]
	v_pk_fma_f32 v[80:81], v[104:105], v[92:93], v[80:81]
	v_mul_f32_e32 v88, 0x3d372713, v84
	v_pk_fma_f32 v[86:87], v[110:111], v[90:91], v[86:87]
	v_mul_f32_e32 v89, 0x3d372713, v80
	v_mul_f32_e32 v90, 0x3d372713, v85
	v_mul_f32_e32 v88, v84, v88
	v_mul_f32_e32 v89, v80, v89
	v_mul_f32_e32 v90, v85, v90
	v_fma_f32 v88, v84, v88, v84
	v_fma_f32 v89, v80, v89, v80
	v_fma_f32 v90, v85, v90, v85
	v_mul_f32_e32 v88, 0xbfcc422a, v88
	v_mul_f32_e32 v89, 0xbfcc422a, v89
	v_mul_f32_e32 v90, 0xbfcc422a, v90
	v_mul_f32_e32 v88, 0x3fb8aa3b, v88
	v_mul_f32_e32 v89, 0x3fb8aa3b, v89
	v_mul_f32_e32 v90, 0x3fb8aa3b, v90
	v_exp_f32_e32 v88, v88
	v_exp_f32_e32 v89, v89
	v_exp_f32_e32 v90, v90
	v_mul_f32_e32 v91, 0x3d372713, v81
	v_add_f32_e32 v88, 1.0, v88
	v_add_f32_e32 v89, 1.0, v89
	v_add_f32_e32 v90, 1.0, v90
	v_rcp_f32_e32 v88, v88
	v_rcp_f32_e32 v89, v89
	v_rcp_f32_e32 v90, v90
	v_mul_f32_e32 v91, v81, v91
	v_fma_f32 v91, v81, v91, v81
	v_lshlrev_b32_e32 v94, 16, v115
	v_and_b32_e32 v95, 0xffff0000, v115
	v_mul_f32_e32 v91, 0xbfcc422a, v91
	v_pk_fma_f32 v[82:83], v[106:107], v[94:95], v[82:83]
	v_mul_f32_e32 v91, 0x3fb8aa3b, v91
	v_exp_f32_e32 v91, v91
	v_mul_f32_e32 v84, v84, v88
	v_mul_f32_e32 v88, v80, v89
	v_mul_f32_e32 v80, v85, v90
	v_mul_f32_e32 v89, 0x3d372713, v86
	v_mul_f32_e32 v90, 0x3d372713, v82
	v_mul_f32_e32 v89, v86, v89
	v_mul_f32_e32 v90, v82, v90
	v_fma_f32 v89, v86, v89, v86
	v_fma_f32 v90, v82, v90, v82
	v_mul_f32_e32 v89, 0xbfcc422a, v89
	v_mul_f32_e32 v90, 0xbfcc422a, v90
	v_add_f32_e32 v85, 1.0, v91
	v_mul_f32_e32 v89, 0x3fb8aa3b, v89
	v_mul_f32_e32 v90, 0x3fb8aa3b, v90
	v_rcp_f32_e32 v85, v85
	v_exp_f32_e32 v89, v89
	v_exp_f32_e32 v90, v90
	v_mul_f32_e32 v91, 0x3d372713, v83
	v_mul_f32_e32 v85, v81, v85
	v_add_f32_e32 v81, 1.0, v89
	v_add_f32_e32 v89, 1.0, v90
	v_mul_f32_e32 v90, 0x3d372713, v87
	v_mul_f32_e32 v90, v87, v90
	v_fma_f32 v90, v87, v90, v87
	v_mul_f32_e32 v90, 0xbfcc422a, v90
	v_mul_f32_e32 v90, 0x3fb8aa3b, v90
	v_exp_f32_e32 v90, v90
	v_mul_f32_e32 v91, v83, v91
	v_fma_f32 v91, v83, v91, v83
	v_mul_f32_e32 v91, 0xbfcc422a, v91
	v_mul_f32_e32 v91, 0x3fb8aa3b, v91
	v_add_f32_e32 v90, 1.0, v90
	v_rcp_f32_e32 v81, v81
	v_exp_f32_e32 v91, v91
	v_rcp_f32_e32 v89, v89
	v_rcp_f32_e32 v90, v90
	v_mul_f32_e32 v81, v86, v81
	v_add_f32_e32 v91, 1.0, v91
	v_mul_f32_e32 v86, v82, v89
	v_mul_f32_e32 v82, v87, v90
	v_cvt_pk_bf16_f32 v80, v84, v80
	v_lshl_add_u32 v84, v122, 4, v192
	v_rcp_f32_e32 v91, v91
	v_cvt_pk_bf16_f32 v81, v81, v82
	v_cvt_pk_bf16_f32 v82, v88, v85
	v_ashrrev_i32_e32 v85, 31, v84
	v_lshlrev_b64 v[84:85], 10, v[84:85]
	v_lshl_add_u64 v[84:85], s[0:1], 0, v[84:85]
	v_lshl_add_u64 v[84:85], s[60:61], 1, v[84:85]
	v_mov_b32_e32 v177, v153
	v_mul_f32_e32 v83, v83, v91
	v_lshl_add_u64 v[84:85], v[84:85], 0, v[176:177]
	v_cvt_pk_bf16_f32 v83, v86, v83
	global_store_dwordx4 v[84:85], v[80:83], off
	s_or_b64 exec, exec, s[64:65]
	s_and_saveexec_b64 s[64:65], s[10:11]
	s_cbranch_execnz .LBB0_310

; __device__ __forceinline__ float bf_lo(unsigned w) { return __uint_as_float(w << 16); }
; __device__ __forceinline__ float bf_hi(unsigned w) { return __uint_as_float(w & 0xffff0000u); }
; __device__ __forceinline__ u32x4 pack8(const f32x4 a, const f32x4 b) { u32x4 w; w.x = cvt_pk_bf16(a[0], a[1]); w.y = cvt_pk_bf16(a[2], a[3]); w.z = cvt_pk_bf16(b[0], b[1]); w.w = cvt_pk_bf16(b[2], b[3]); return w; }
;     __device__ __forceinline__ void operator()(EPI_ARGS) const {
;     ...
;                 for (int m = 0; m < 4; ++m) { const int j = row0 + ai * HALF + m * 16;
;                     uw[m] = (j < NJ) ? *(const u32x4*)(AB + ((size_t)((g >> 1) * NJP + j) * ABP + (g & 1) * 384 + n)) : (u32x4){0u, 0u, 0u, 0u}; }
; #pragma unroll
;                 for (int m = 0; m < 4; ++m) { const int j = row0 + ai * HALF + m * 16;
;                     if (j < NJ) {
;                         const u32x4 w = uw[m];
;                         f32x4 u0 = {bf_lo(w.x), bf_hi(w.x), bf_lo(w.y), bf_hi(w.y)}, u1 = {bf_lo(w.z), bf_hi(w.z), bf_lo(w.w), bf_hi(w.w)};
;                         f32x4 y0 = acc[ai][bj][m][0] + d0 * u0, y1 = acc[ai][bj][m][1] + d1 * u1;
; #pragma unroll
;                         for (int e = 0; e < 4; ++e) {
;                             { const float y = y0[e], q = 1.5957691216f * (y + 0.044715f * y * y * y); y0[e] = y * __builtin_amdgcn_rcpf(1.0f + __expf(-q)); }
;                             { const float y = y1[e], q = 1.5957691216f * (y + 0.044715f * y * y * y); y1[e] = y * __builtin_amdgcn_rcpf(1.0f + __expf(-q)); }
;                         }
;                         *(u32x4*)(Z + (size_t)(j * TS + t) * WA + g * 16 + c) = pack8(y0, y1);
.LBB0_294:
	v_lshlrev_b32_e32 v72, 16, v96
	v_and_b32_e32 v73, 0xffff0000, v96
	v_lshlrev_b32_e32 v76, 16, v98
	v_and_b32_e32 v77, 0xffff0000, v98
	v_lshlrev_b32_e32 v74, 16, v97
	v_and_b32_e32 v75, 0xffff0000, v97
	v_pk_fma_f32 v[68:69], v[108:109], v[72:73], v[68:69]
	v_pk_fma_f32 v[64:65], v[104:105], v[76:77], v[64:65]
	v_mul_f32_e32 v72, 0x3d372713, v68
	v_pk_fma_f32 v[70:71], v[110:111], v[74:75], v[70:71]
	v_mul_f32_e32 v73, 0x3d372713, v64
	v_mul_f32_e32 v74, 0x3d372713, v69
	v_mul_f32_e32 v72, v68, v72
	v_mul_f32_e32 v73, v64, v73
	v_mul_f32_e32 v74, v69, v74
	v_fma_f32 v72, v68, v72, v68
	v_fma_f32 v73, v64, v73, v64
	v_fma_f32 v74, v69, v74, v69
	v_mul_f32_e32 v72, 0xbfcc422a, v72
	v_mul_f32_e32 v73, 0xbfcc422a, v73
	v_mul_f32_e32 v74, 0xbfcc422a, v74
	v_mul_f32_e32 v72, 0x3fb8aa3b, v72
	v_mul_f32_e32 v73, 0x3fb8aa3b, v73
	v_mul_f32_e32 v74, 0x3fb8aa3b, v74
	v_exp_f32_e32 v72, v72
	v_exp_f32_e32 v73, v73
	v_exp_f32_e32 v74, v74
	v_mul_f32_e32 v75, 0x3d372713, v65
	v_add_f32_e32 v72, 1.0, v72
	v_add_f32_e32 v73, 1.0, v73
	v_add_f32_e32 v74, 1.0, v74
	v_rcp_f32_e32 v72, v72
	v_rcp_f32_e32 v73, v73
	v_rcp_f32_e32 v74, v74
	v_mul_f32_e32 v75, v65, v75
	v_fma_f32 v75, v65, v75, v65
	v_lshlrev_b32_e32 v78, 16, v99
	v_and_b32_e32 v79, 0xffff0000, v99
	v_mul_f32_e32 v75, 0xbfcc422a, v75
	v_pk_fma_f32 v[66:67], v[106:107], v[78:79], v[66:67]
	v_mul_f32_e32 v75, 0x3fb8aa3b, v75
	v_exp_f32_e32 v75, v75
	v_mul_f32_e32 v68, v68, v72
	v_mul_f32_e32 v72, v64, v73
	v_mul_f32_e32 v64, v69, v74
	v_mul_f32_e32 v73, 0x3d372713, v70
	v_mul_f32_e32 v74, 0x3d372713, v66
	v_mul_f32_e32 v73, v70, v73
	v_mul_f32_e32 v74, v66, v74
	v_fma_f32 v73, v70, v73, v70
	v_fma_f32 v74, v66, v74, v66
	v_mul_f32_e32 v73, 0xbfcc422a, v73
	v_mul_f32_e32 v74, 0xbfcc422a, v74
	v_add_f32_e32 v69, 1.0, v75
	v_mul_f32_e32 v73, 0x3fb8aa3b, v73
	v_mul_f32_e32 v74, 0x3fb8aa3b, v74
	v_rcp_f32_e32 v69, v69
	v_exp_f32_e32 v73, v73
	v_exp_f32_e32 v74, v74
	v_mul_f32_e32 v75, 0x3d372713, v67
	v_mul_f32_e32 v69, v65, v69
	v_add_f32_e32 v65, 1.0, v73
	v_add_f32_e32 v73, 1.0, v74
	v_mul_f32_e32 v74, 0x3d372713, v71
	v_mul_f32_e32 v74, v71, v74
	v_fma_f32 v74, v71, v74, v71
	v_mul_f32_e32 v74, 0xbfcc422a, v74
	v_mul_f32_e32 v74, 0x3fb8aa3b, v74
	v_exp_f32_e32 v74, v74
	v_mul_f32_e32 v75, v67, v75
	v_fma_f32 v75, v67, v75, v67
	v_mul_f32_e32 v75, 0xbfcc422a, v75
	v_mul_f32_e32 v75, 0x3fb8aa3b, v75
	v_add_f32_e32 v74, 1.0, v74
	v_rcp_f32_e32 v65, v65
	v_exp_f32_e32 v75, v75
	v_rcp_f32_e32 v73, v73
	v_rcp_f32_e32 v74, v74
	v_mul_f32_e32 v65, v70, v65
	v_add_f32_e32 v75, 1.0, v75
	v_mul_f32_e32 v70, v66, v73
	v_mul_f32_e32 v66, v71, v74
	v_cvt_pk_bf16_f32 v64, v68, v64
	v_lshl_add_u32 v68, v120, 4, v192
	v_rcp_f32_e32 v75, v75
	v_cvt_pk_bf16_f32 v65, v65, v66
	v_cvt_pk_bf16_f32 v66, v72, v69
	v_ashrrev_i32_e32 v69, 31, v68
	v_lshlrev_b64 v[68:69], 10, v[68:69]
	v_lshl_add_u64 v[68:69], s[0:1], 0, v[68:69]
	v_lshl_add_u64 v[68:69], s[60:61], 1, v[68:69]
	v_mov_b32_e32 v177, v153
	v_mul_f32_e32 v67, v67, v75
	v_lshl_add_u64 v[68:69], v[68:69], 0, v[176:177]
	v_cvt_pk_bf16_f32 v67, v70, v67
	global_store_dwordx4 v[68:69], v[64:67], off

; __device__ __forceinline__ float bf_lo(unsigned w) { return __uint_as_float(w << 16); }
; __device__ __forceinline__ float bf_hi(unsigned w) { return __uint_as_float(w & 0xffff0000u); }
; __device__ __forceinline__ u32x4 pack8(const f32x4 a, const f32x4 b) { u32x4 w; w.x = cvt_pk_bf16(a[0], a[1]); w.y = cvt_pk_bf16(a[2], a[3]); w.z = cvt_pk_bf16(b[0], b[1]); w.w = cvt_pk_bf16(b[2], b[3]); return w; }
;     __device__ __forceinline__ void operator()(EPI_ARGS) const {
;     ...
;                 for (int m = 0; m < 4; ++m) { const int j = row0 + ai * HALF + m * 16;
;                     uw[m] = (j < NJ) ? *(const u32x4*)(AB + ((size_t)((g >> 1) * NJP + j) * ABP + (g & 1) * 384 + n)) : (u32x4){0u, 0u, 0u, 0u}; }
; #pragma unroll
;                 for (int m = 0; m < 4; ++m) { const int j = row0 + ai * HALF + m * 16;
;                     if (j < NJ) {
;                         const u32x4 w = uw[m];
;                         f32x4 u0 = {bf_lo(w.x), bf_hi(w.x), bf_lo(w.y), bf_hi(w.y)}, u1 = {bf_lo(w.z), bf_hi(w.z), bf_lo(w.w), bf_hi(w.w)};
;                         f32x4 y0 = acc[ai][bj][m][0] + d0 * u0, y1 = acc[ai][bj][m][1] + d1 * u1;
; #pragma unroll
;                         for (int e = 0; e < 4; ++e) {
;                             { const float y = y0[e], q = 1.5957691216f * (y + 0.044715f * y * y * y); y0[e] = y * __builtin_amdgcn_rcpf(1.0f + __expf(-q)); }
;                             { const float y = y1[e], q = 1.5957691216f * (y + 0.044715f * y * y * y); y1[e] = y * __builtin_amdgcn_rcpf(1.0f + __expf(-q)); }
;                         }
;                         *(u32x4*)(Z + (size_t)(j * TS + t) * WA + g * 16 + c) = pack8(y0, y1);
.LBB0_306:
	v_lshlrev_b32_e32 v48, 16, v76
	v_and_b32_e32 v49, 0xffff0000, v76
	v_lshlrev_b32_e32 v52, 16, v78
	v_and_b32_e32 v53, 0xffff0000, v78
	v_lshlrev_b32_e32 v50, 16, v77
	v_and_b32_e32 v51, 0xffff0000, v77
	v_pk_fma_f32 v[44:45], v[68:69], v[48:49], v[44:45]
	v_pk_fma_f32 v[40:41], v[64:65], v[52:53], v[40:41]
	v_mul_f32_e32 v48, 0x3d372713, v44
	v_pk_fma_f32 v[46:47], v[70:71], v[50:51], v[46:47]
	v_mul_f32_e32 v49, 0x3d372713, v40
	v_mul_f32_e32 v50, 0x3d372713, v45
	v_mul_f32_e32 v48, v44, v48
	v_mul_f32_e32 v49, v40, v49
	v_mul_f32_e32 v50, v45, v50
	v_fma_f32 v48, v44, v48, v44
	v_fma_f32 v49, v40, v49, v40
	v_fma_f32 v50, v45, v50, v45
	v_mul_f32_e32 v48, 0xbfcc422a, v48
	v_mul_f32_e32 v49, 0xbfcc422a, v49
	v_mul_f32_e32 v50, 0xbfcc422a, v50
	v_mul_f32_e32 v48, 0x3fb8aa3b, v48
	v_mul_f32_e32 v49, 0x3fb8aa3b, v49
	v_mul_f32_e32 v50, 0x3fb8aa3b, v50
	v_exp_f32_e32 v48, v48
	v_exp_f32_e32 v49, v49
	v_exp_f32_e32 v50, v50
	v_mul_f32_e32 v51, 0x3d372713, v41
	v_add_f32_e32 v48, 1.0, v48
	v_add_f32_e32 v49, 1.0, v49
	v_add_f32_e32 v50, 1.0, v50
	v_rcp_f32_e32 v48, v48
	v_rcp_f32_e32 v49, v49
	v_rcp_f32_e32 v50, v50
	v_mul_f32_e32 v51, v41, v51
	v_fma_f32 v51, v41, v51, v41
	v_lshlrev_b32_e32 v54, 16, v79
	v_and_b32_e32 v55, 0xffff0000, v79
	v_mul_f32_e32 v51, 0xbfcc422a, v51
	v_pk_fma_f32 v[42:43], v[66:67], v[54:55], v[42:43]
	v_mul_f32_e32 v51, 0x3fb8aa3b, v51
	v_exp_f32_e32 v51, v51
	v_mul_f32_e32 v44, v44, v48
	v_mul_f32_e32 v48, v40, v49
	v_mul_f32_e32 v40, v45, v50
	v_mul_f32_e32 v49, 0x3d372713, v46
	v_mul_f32_e32 v50, 0x3d372713, v42
	v_mul_f32_e32 v49, v46, v49
	v_mul_f32_e32 v50, v42, v50
	v_fma_f32 v49, v46, v49, v46
	v_fma_f32 v50, v42, v50, v42
	v_mul_f32_e32 v49, 0xbfcc422a, v49
	v_mul_f32_e32 v50, 0xbfcc422a, v50
	v_add_f32_e32 v45, 1.0, v51
	v_mul_f32_e32 v49, 0x3fb8aa3b, v49
	v_mul_f32_e32 v50, 0x3fb8aa3b, v50
	v_rcp_f32_e32 v45, v45
	v_exp_f32_e32 v49, v49
	v_exp_f32_e32 v50, v50
	v_mul_f32_e32 v51, 0x3d372713, v43
	v_mul_f32_e32 v45, v41, v45
	v_add_f32_e32 v41, 1.0, v49
	v_add_f32_e32 v49, 1.0, v50
	v_mul_f32_e32 v50, 0x3d372713, v47
	v_mul_f32_e32 v50, v47, v50
	v_fma_f32 v50, v47, v50, v47
	v_mul_f32_e32 v50, 0xbfcc422a, v50
	v_mul_f32_e32 v50, 0x3fb8aa3b, v50
	v_exp_f32_e32 v50, v50
	v_mul_f32_e32 v51, v43, v51
	v_fma_f32 v51, v43, v51, v43
	v_mul_f32_e32 v51, 0xbfcc422a, v51
	v_mul_f32_e32 v51, 0x3fb8aa3b, v51
	v_add_f32_e32 v50, 1.0, v50
	v_rcp_f32_e32 v41, v41
	v_exp_f32_e32 v51, v51
	v_rcp_f32_e32 v49, v49
	v_rcp_f32_e32 v50, v50
	v_mul_f32_e32 v41, v46, v41
	v_add_f32_e32 v51, 1.0, v51
	v_mul_f32_e32 v46, v42, v49
	v_mul_f32_e32 v42, v47, v50
	v_cvt_pk_bf16_f32 v40, v44, v40
	v_lshl_add_u32 v44, v185, 4, v88
	v_rcp_f32_e32 v51, v51
	v_cvt_pk_bf16_f32 v41, v41, v42
	v_cvt_pk_bf16_f32 v42, v48, v45
	v_ashrrev_i32_e32 v45, 31, v44
	v_lshlrev_b64 v[44:45], 10, v[44:45]
	v_lshl_add_u64 v[44:45], s[0:1], 0, v[44:45]
	v_lshl_add_u64 v[44:45], s[60:61], 1, v[44:45]
	v_mov_b32_e32 v177, v153
	v_mul_f32_e32 v43, v43, v51
	v_lshl_add_u64 v[44:45], v[44:45], 0, v[176:177]
	v_cvt_pk_bf16_f32 v43, v46, v43
	global_store_dwordx4 v[44:45], v[40:43], off
	s_or_b64 exec, exec, s[12:13]
	s_and_saveexec_b64 s[8:9], vcc
	s_cbranch_execnz .LBB0_314
	s_branch .LBB0_315

; __device__ __forceinline__ float bf_lo(unsigned w) { return __uint_as_float(w << 16); }
; __device__ __forceinline__ float bf_hi(unsigned w) { return __uint_as_float(w & 0xffff0000u); }
; __device__ __forceinline__ u32x4 pack8(const f32x4 a, const f32x4 b) { u32x4 w; w.x = cvt_pk_bf16(a[0], a[1]); w.y = cvt_pk_bf16(a[2], a[3]); w.z = cvt_pk_bf16(b[0], b[1]); w.w = cvt_pk_bf16(b[2], b[3]); return w; }
;     __device__ __forceinline__ void operator()(EPI_ARGS) const {
;     ...
;                 for (int m = 0; m < 4; ++m) { const int j = row0 + ai * HALF + m * 16;
;                     uw[m] = (j < NJ) ? *(const u32x4*)(AB + ((size_t)((g >> 1) * NJP + j) * ABP + (g & 1) * 384 + n)) : (u32x4){0u, 0u, 0u, 0u}; }
; #pragma unroll
;                 for (int m = 0; m < 4; ++m) { const int j = row0 + ai * HALF + m * 16;
;                     if (j < NJ) {
;                         const u32x4 w = uw[m];
;                         f32x4 u0 = {bf_lo(w.x), bf_hi(w.x), bf_lo(w.y), bf_hi(w.y)}, u1 = {bf_lo(w.z), bf_hi(w.z), bf_lo(w.w), bf_hi(w.w)};
;                         f32x4 y0 = acc[ai][bj][m][0] + d0 * u0, y1 = acc[ai][bj][m][1] + d1 * u1;
; #pragma unroll
;                         for (int e = 0; e < 4; ++e) {
;                             { const float y = y0[e], q = 1.5957691216f * (y + 0.044715f * y * y * y); y0[e] = y * __builtin_amdgcn_rcpf(1.0f + __expf(-q)); }
;                             { const float y = y1[e], q = 1.5957691216f * (y + 0.044715f * y * y * y); y1[e] = y * __builtin_amdgcn_rcpf(1.0f + __expf(-q)); }
;                         }
;                         *(u32x4*)(Z + (size_t)(j * TS + t) * WA + g * 16 + c) = pack8(y0, y1);
.LBB0_310:
	v_lshlrev_b32_e32 v80, 16, v100
	v_and_b32_e32 v81, 0xffff0000, v100
	v_lshlrev_b32_e32 v84, 16, v102
	v_and_b32_e32 v85, 0xffff0000, v102
	v_lshlrev_b32_e32 v82, 16, v101
	v_and_b32_e32 v83, 0xffff0000, v101
	v_pk_fma_f32 v[76:77], v[108:109], v[80:81], v[76:77]
	v_pk_fma_f32 v[72:73], v[104:105], v[84:85], v[72:73]
	v_mul_f32_e32 v80, 0x3d372713, v76
	v_pk_fma_f32 v[78:79], v[110:111], v[82:83], v[78:79]
	v_mul_f32_e32 v81, 0x3d372713, v72
	v_mul_f32_e32 v82, 0x3d372713, v77
	v_mul_f32_e32 v80, v76, v80
	v_mul_f32_e32 v81, v72, v81
	v_mul_f32_e32 v82, v77, v82
	v_fma_f32 v80, v76, v80, v76
	v_fma_f32 v81, v72, v81, v72
	v_fma_f32 v82, v77, v82, v77
	v_mul_f32_e32 v80, 0xbfcc422a, v80
	v_mul_f32_e32 v81, 0xbfcc422a, v81
	v_mul_f32_e32 v82, 0xbfcc422a, v82
	v_mul_f32_e32 v80, 0x3fb8aa3b, v80
	v_mul_f32_e32 v81, 0x3fb8aa3b, v81
	v_mul_f32_e32 v82, 0x3fb8aa3b, v82
	v_exp_f32_e32 v80, v80
	v_exp_f32_e32 v81, v81
	v_exp_f32_e32 v82, v82
	v_mul_f32_e32 v83, 0x3d372713, v73
	v_add_f32_e32 v80, 1.0, v80
	v_add_f32_e32 v81, 1.0, v81
	v_add_f32_e32 v82, 1.0, v82
	v_rcp_f32_e32 v80, v80
	v_rcp_f32_e32 v81, v81
	v_rcp_f32_e32 v82, v82
	v_mul_f32_e32 v83, v73, v83
	v_fma_f32 v83, v73, v83, v73
	v_lshlrev_b32_e32 v86, 16, v103
	v_and_b32_e32 v87, 0xffff0000, v103
	v_mul_f32_e32 v83, 0xbfcc422a, v83
	v_pk_fma_f32 v[74:75], v[106:107], v[86:87], v[74:75]
	v_mul_f32_e32 v83, 0x3fb8aa3b, v83
	v_exp_f32_e32 v83, v83
	v_mul_f32_e32 v76, v76, v80
	v_mul_f32_e32 v80, v72, v81
	v_mul_f32_e32 v72, v77, v82
	v_mul_f32_e32 v81, 0x3d372713, v78
	v_mul_f32_e32 v82, 0x3d372713, v74
	v_mul_f32_e32 v81, v78, v81
	v_mul_f32_e32 v82, v74, v82
	v_fma_f32 v81, v78, v81, v78
	v_fma_f32 v82, v74, v82, v74
	v_mul_f32_e32 v81, 0xbfcc422a, v81
	v_mul_f32_e32 v82, 0xbfcc422a, v82
	v_add_f32_e32 v77, 1.0, v83
	v_mul_f32_e32 v81, 0x3fb8aa3b, v81
	v_mul_f32_e32 v82, 0x3fb8aa3b, v82
	v_rcp_f32_e32 v77, v77
	v_exp_f32_e32 v81, v81
	v_exp_f32_e32 v82, v82
	v_mul_f32_e32 v83, 0x3d372713, v75
	v_mul_f32_e32 v77, v73, v77
	v_add_f32_e32 v73, 1.0, v81
	v_add_f32_e32 v81, 1.0, v82
	v_mul_f32_e32 v82, 0x3d372713, v79
	v_mul_f32_e32 v82, v79, v82
	v_fma_f32 v82, v79, v82, v79
	v_mul_f32_e32 v82, 0xbfcc422a, v82
	v_mul_f32_e32 v82, 0x3fb8aa3b, v82
	v_exp_f32_e32 v82, v82
	v_mul_f32_e32 v83, v75, v83
	v_fma_f32 v83, v75, v83, v75
	v_mul_f32_e32 v83, 0xbfcc422a, v83
	v_mul_f32_e32 v83, 0x3fb8aa3b, v83
	v_add_f32_e32 v82, 1.0, v82
	v_rcp_f32_e32 v73, v73
	v_exp_f32_e32 v83, v83
	v_rcp_f32_e32 v81, v81
	v_rcp_f32_e32 v82, v82
	v_mul_f32_e32 v73, v78, v73
	v_add_f32_e32 v83, 1.0, v83
	v_mul_f32_e32 v78, v74, v81
	v_mul_f32_e32 v74, v79, v82
	v_cvt_pk_bf16_f32 v72, v76, v72
	v_lshl_add_u32 v76, v121, 4, v192
	v_rcp_f32_e32 v83, v83
	v_cvt_pk_bf16_f32 v73, v73, v74
	v_cvt_pk_bf16_f32 v74, v80, v77
	v_ashrrev_i32_e32 v77, 31, v76
	v_lshlrev_b64 v[76:77], 10, v[76:77]
	v_lshl_add_u64 v[76:77], s[0:1], 0, v[76:77]
	v_lshl_add_u64 v[76:77], s[60:61], 1, v[76:77]
	v_mov_b32_e32 v177, v153
	v_mul_f32_e32 v75, v75, v83
	v_lshl_add_u64 v[76:77], v[76:77], 0, v[176:177]
	v_cvt_pk_bf16_f32 v75, v78, v75
	global_store_dwordx4 v[76:77], v[72:75], off
	s_or_b64 exec, exec, s[64:65]
	s_and_saveexec_b64 s[64:65], s[6:7]
	s_cbranch_execnz .LBB0_294
	s_branch .LBB0_295

; __device__ __forceinline__ float bf_lo(unsigned w) { return __uint_as_float(w << 16); }
; __device__ __forceinline__ float bf_hi(unsigned w) { return __uint_as_float(w & 0xffff0000u); }
; __device__ __forceinline__ u32x4 pack8(const f32x4 a, const f32x4 b) { u32x4 w; w.x = cvt_pk_bf16(a[0], a[1]); w.y = cvt_pk_bf16(a[2], a[3]); w.z = cvt_pk_bf16(b[0], b[1]); w.w = cvt_pk_bf16(b[2], b[3]); return w; }
;     __device__ __forceinline__ void operator()(EPI_ARGS) const {
;     ...
;                 for (int m = 0; m < 4; ++m) { const int j = row0 + ai * HALF + m * 16;
;                     uw[m] = (j < NJ) ? *(const u32x4*)(AB + ((size_t)((g >> 1) * NJP + j) * ABP + (g & 1) * 384 + n)) : (u32x4){0u, 0u, 0u, 0u}; }
; #pragma unroll
;                 for (int m = 0; m < 4; ++m) { const int j = row0 + ai * HALF + m * 16;
;                     if (j < NJ) {
;                         const u32x4 w = uw[m];
;                         f32x4 u0 = {bf_lo(w.x), bf_hi(w.x), bf_lo(w.y), bf_hi(w.y)}, u1 = {bf_lo(w.z), bf_hi(w.z), bf_lo(w.w), bf_hi(w.w)};
;                         f32x4 y0 = acc[ai][bj][m][0] + d0 * u0, y1 = acc[ai][bj][m][1] + d1 * u1;
; #pragma unroll
;                         for (int e = 0; e < 4; ++e) {
;                             { const float y = y0[e], q = 1.5957691216f * (y + 0.044715f * y * y * y); y0[e] = y * __builtin_amdgcn_rcpf(1.0f + __expf(-q)); }
;                             { const float y = y1[e], q = 1.5957691216f * (y + 0.044715f * y * y * y); y1[e] = y * __builtin_amdgcn_rcpf(1.0f + __expf(-q)); }
;                         }
;                         *(u32x4*)(Z + (size_t)(j * TS + t) * WA + g * 16 + c) = pack8(y0, y1);
.LBB0_312:
	v_lshlrev_b32_e32 v56, 16, v80
	v_and_b32_e32 v57, 0xffff0000, v80
	v_lshlrev_b32_e32 v60, 16, v82
	v_and_b32_e32 v61, 0xffff0000, v82
	v_lshlrev_b32_e32 v58, 16, v81
	v_and_b32_e32 v59, 0xffff0000, v81
	v_pk_fma_f32 v[52:53], v[68:69], v[56:57], v[52:53]
	v_pk_fma_f32 v[48:49], v[64:65], v[60:61], v[48:49]
	v_mul_f32_e32 v56, 0x3d372713, v52
	v_pk_fma_f32 v[54:55], v[70:71], v[58:59], v[54:55]
	v_mul_f32_e32 v57, 0x3d372713, v48
	v_mul_f32_e32 v58, 0x3d372713, v53
	v_mul_f32_e32 v56, v52, v56
	v_mul_f32_e32 v57, v48, v57
	v_mul_f32_e32 v58, v53, v58
	v_fma_f32 v56, v52, v56, v52
	v_fma_f32 v57, v48, v57, v48
	v_fma_f32 v58, v53, v58, v53
	v_mul_f32_e32 v56, 0xbfcc422a, v56
	v_mul_f32_e32 v57, 0xbfcc422a, v57
	v_mul_f32_e32 v58, 0xbfcc422a, v58
	v_mul_f32_e32 v56, 0x3fb8aa3b, v56
	v_mul_f32_e32 v57, 0x3fb8aa3b, v57
	v_mul_f32_e32 v58, 0x3fb8aa3b, v58
	v_exp_f32_e32 v56, v56
	v_exp_f32_e32 v57, v57
	v_exp_f32_e32 v58, v58
	v_mul_f32_e32 v59, 0x3d372713, v49
	v_add_f32_e32 v56, 1.0, v56
	v_add_f32_e32 v57, 1.0, v57
	v_add_f32_e32 v58, 1.0, v58
	v_rcp_f32_e32 v56, v56
	v_rcp_f32_e32 v57, v57
	v_rcp_f32_e32 v58, v58
	v_mul_f32_e32 v59, v49, v59
	v_fma_f32 v59, v49, v59, v49
	v_lshlrev_b32_e32 v62, 16, v83
	v_and_b32_e32 v63, 0xffff0000, v83
	v_mul_f32_e32 v59, 0xbfcc422a, v59
	v_pk_fma_f32 v[50:51], v[66:67], v[62:63], v[50:51]
	v_mul_f32_e32 v59, 0x3fb8aa3b, v59
	v_exp_f32_e32 v59, v59
	v_mul_f32_e32 v52, v52, v56
	v_mul_f32_e32 v56, v48, v57
	v_mul_f32_e32 v48, v53, v58
	v_mul_f32_e32 v57, 0x3d372713, v54
	v_mul_f32_e32 v58, 0x3d372713, v50
	v_mul_f32_e32 v57, v54, v57
	v_mul_f32_e32 v58, v50, v58
	v_fma_f32 v57, v54, v57, v54
	v_fma_f32 v58, v50, v58, v50
	v_mul_f32_e32 v57, 0xbfcc422a, v57
	v_mul_f32_e32 v58, 0xbfcc422a, v58
	v_add_f32_e32 v53, 1.0, v59
	v_mul_f32_e32 v57, 0x3fb8aa3b, v57
	v_mul_f32_e32 v58, 0x3fb8aa3b, v58
	v_rcp_f32_e32 v53, v53
	v_exp_f32_e32 v57, v57
	v_exp_f32_e32 v58, v58
	v_mul_f32_e32 v59, 0x3d372713, v51
	v_mul_f32_e32 v53, v49, v53
	v_add_f32_e32 v49, 1.0, v57
	v_add_f32_e32 v57, 1.0, v58
	v_mul_f32_e32 v58, 0x3d372713, v55
	v_mul_f32_e32 v58, v55, v58
	v_fma_f32 v58, v55, v58, v55
	v_mul_f32_e32 v58, 0xbfcc422a, v58
	v_mul_f32_e32 v58, 0x3fb8aa3b, v58
	v_exp_f32_e32 v58, v58
	v_mul_f32_e32 v59, v51, v59
	v_fma_f32 v59, v51, v59, v51
	v_mul_f32_e32 v59, 0xbfcc422a, v59
	v_mul_f32_e32 v59, 0x3fb8aa3b, v59
	v_add_f32_e32 v58, 1.0, v58
	v_rcp_f32_e32 v49, v49
	v_exp_f32_e32 v59, v59
	v_rcp_f32_e32 v57, v57
	v_rcp_f32_e32 v58, v58
	v_mul_f32_e32 v49, v54, v49
	v_add_f32_e32 v59, 1.0, v59
	v_mul_f32_e32 v54, v50, v57
	v_mul_f32_e32 v50, v55, v58
	v_cvt_pk_bf16_f32 v48, v52, v48
	v_lshl_add_u32 v52, v186, 4, v88
	v_rcp_f32_e32 v59, v59
	v_cvt_pk_bf16_f32 v49, v49, v50
	v_cvt_pk_bf16_f32 v50, v56, v53
	v_ashrrev_i32_e32 v53, 31, v52
	v_lshlrev_b64 v[52:53], 10, v[52:53]
	v_lshl_add_u64 v[52:53], s[0:1], 0, v[52:53]
	v_lshl_add_u64 v[52:53], s[60:61], 1, v[52:53]
	v_mov_b32_e32 v177, v153
	v_mul_f32_e32 v51, v51, v59
	v_lshl_add_u64 v[52:53], v[52:53], 0, v[176:177]
	v_cvt_pk_bf16_f32 v51, v54, v51
	global_store_dwordx4 v[52:53], v[48:51], off
	s_or_b64 exec, exec, s[16:17]
	s_and_saveexec_b64 s[12:13], s[8:9]
	s_cbranch_execnz .LBB0_306

; __device__ __forceinline__ float bf_lo(unsigned w) { return __uint_as_float(w << 16); }
; __device__ __forceinline__ float bf_hi(unsigned w) { return __uint_as_float(w & 0xffff0000u); }
; __device__ __forceinline__ u32x4 pack8(const f32x4 a, const f32x4 b) { u32x4 w; w.x = cvt_pk_bf16(a[0], a[1]); w.y = cvt_pk_bf16(a[2], a[3]); w.z = cvt_pk_bf16(b[0], b[1]); w.w = cvt_pk_bf16(b[2], b[3]); return w; }
;     __device__ __forceinline__ void operator()(EPI_ARGS) const {
;     ...
;                 for (int m = 0; m < 4; ++m) { const int j = row0 + ai * HALF + m * 16;
;                     uw[m] = (j < NJ) ? *(const u32x4*)(AB + ((size_t)((g >> 1) * NJP + j) * ABP + (g & 1) * 384 + n)) : (u32x4){0u, 0u, 0u, 0u}; }
; #pragma unroll
;                 for (int m = 0; m < 4; ++m) { const int j = row0 + ai * HALF + m * 16;
;                     if (j < NJ) {
;                         const u32x4 w = uw[m];
;                         f32x4 u0 = {bf_lo(w.x), bf_hi(w.x), bf_lo(w.y), bf_hi(w.y)}, u1 = {bf_lo(w.z), bf_hi(w.z), bf_lo(w.w), bf_hi(w.w)};
;                         f32x4 y0 = acc[ai][bj][m][0] + d0 * u0, y1 = acc[ai][bj][m][1] + d1 * u1;
; #pragma unroll
;                         for (int e = 0; e < 4; ++e) {
;                             { const float y = y0[e], q = 1.5957691216f * (y + 0.044715f * y * y * y); y0[e] = y * __builtin_amdgcn_rcpf(1.0f + __expf(-q)); }
;                             { const float y = y1[e], q = 1.5957691216f * (y + 0.044715f * y * y * y); y1[e] = y * __builtin_amdgcn_rcpf(1.0f + __expf(-q)); }
;                         }
;                         *(u32x4*)(Z + (size_t)(j * TS + t) * WA + g * 16 + c) = pack8(y0, y1);
.LBB0_314:
	v_lshlrev_b32_e32 v40, 16, v72
	v_and_b32_e32 v41, 0xffff0000, v72
	v_lshlrev_b32_e32 v44, 16, v74
	v_and_b32_e32 v45, 0xffff0000, v74
	v_lshlrev_b32_e32 v42, 16, v73
	v_and_b32_e32 v43, 0xffff0000, v73
	v_pk_fma_f32 v[36:37], v[68:69], v[40:41], v[36:37]
	v_pk_fma_f32 v[32:33], v[64:65], v[44:45], v[32:33]
	v_mul_f32_e32 v40, 0x3d372713, v36
	v_pk_fma_f32 v[38:39], v[70:71], v[42:43], v[38:39]
	v_mul_f32_e32 v41, 0x3d372713, v32
	v_mul_f32_e32 v42, 0x3d372713, v37
	v_mul_f32_e32 v40, v36, v40
	v_mul_f32_e32 v41, v32, v41
	v_mul_f32_e32 v42, v37, v42
	v_fma_f32 v40, v36, v40, v36
	v_fma_f32 v41, v32, v41, v32
	v_fma_f32 v42, v37, v42, v37
	v_mul_f32_e32 v40, 0xbfcc422a, v40
	v_mul_f32_e32 v41, 0xbfcc422a, v41
	v_mul_f32_e32 v42, 0xbfcc422a, v42
	v_mul_f32_e32 v40, 0x3fb8aa3b, v40
	v_mul_f32_e32 v41, 0x3fb8aa3b, v41
	v_mul_f32_e32 v42, 0x3fb8aa3b, v42
	v_exp_f32_e32 v40, v40
	v_exp_f32_e32 v41, v41
	v_exp_f32_e32 v42, v42
	v_mul_f32_e32 v43, 0x3d372713, v33
	v_add_f32_e32 v40, 1.0, v40
	v_add_f32_e32 v41, 1.0, v41
	v_add_f32_e32 v42, 1.0, v42
	v_rcp_f32_e32 v40, v40
	v_rcp_f32_e32 v41, v41
	v_rcp_f32_e32 v42, v42
	v_mul_f32_e32 v43, v33, v43
	v_fma_f32 v43, v33, v43, v33
	v_lshlrev_b32_e32 v46, 16, v75
	v_and_b32_e32 v47, 0xffff0000, v75
	v_mul_f32_e32 v43, 0xbfcc422a, v43
	v_pk_fma_f32 v[34:35], v[66:67], v[46:47], v[34:35]
	v_mul_f32_e32 v43, 0x3fb8aa3b, v43
	v_exp_f32_e32 v43, v43
	v_mul_f32_e32 v36, v36, v40
	v_mul_f32_e32 v40, v32, v41
	v_mul_f32_e32 v32, v37, v42
	v_mul_f32_e32 v41, 0x3d372713, v38
	v_mul_f32_e32 v42, 0x3d372713, v34
	v_mul_f32_e32 v41, v38, v41
	v_mul_f32_e32 v42, v34, v42
	v_fma_f32 v41, v38, v41, v38
	v_fma_f32 v42, v34, v42, v34
	v_mul_f32_e32 v41, 0xbfcc422a, v41
	v_mul_f32_e32 v42, 0xbfcc422a, v42
	v_add_f32_e32 v37, 1.0, v43
	v_mul_f32_e32 v41, 0x3fb8aa3b, v41
	v_mul_f32_e32 v42, 0x3fb8aa3b, v42
	v_rcp_f32_e32 v37, v37
	v_exp_f32_e32 v41, v41
	v_exp_f32_e32 v42, v42
	v_mul_f32_e32 v43, 0x3d372713, v35
	v_mul_f32_e32 v37, v33, v37
	v_add_f32_e32 v33, 1.0, v41
	v_add_f32_e32 v41, 1.0, v42
	v_mul_f32_e32 v42, 0x3d372713, v39
	v_mul_f32_e32 v42, v39, v42
	v_fma_f32 v42, v39, v42, v39
	v_mul_f32_e32 v42, 0xbfcc422a, v42
	v_mul_f32_e32 v42, 0x3fb8aa3b, v42
	v_exp_f32_e32 v42, v42
	v_mul_f32_e32 v43, v35, v43
	v_fma_f32 v43, v35, v43, v35
	v_mul_f32_e32 v43, 0xbfcc422a, v43
	v_mul_f32_e32 v43, 0x3fb8aa3b, v43
	v_add_f32_e32 v42, 1.0, v42
	v_rcp_f32_e32 v33, v33
	v_exp_f32_e32 v43, v43
	v_rcp_f32_e32 v41, v41
	v_rcp_f32_e32 v42, v42
	v_mul_f32_e32 v33, v38, v33
	v_add_f32_e32 v43, 1.0, v43
	v_mul_f32_e32 v38, v34, v41
	v_mul_f32_e32 v34, v39, v42
	v_cvt_pk_bf16_f32 v32, v36, v32
	v_lshl_add_u32 v36, v181, 4, v88
	v_rcp_f32_e32 v43, v43
	v_cvt_pk_bf16_f32 v33, v33, v34
	v_cvt_pk_bf16_f32 v34, v40, v37
	v_ashrrev_i32_e32 v37, 31, v36
	v_lshlrev_b64 v[36:37], 10, v[36:37]
	v_lshl_add_u64 v[36:37], s[0:1], 0, v[36:37]
	v_lshl_add_u64 v[36:37], s[60:61], 1, v[36:37]
	v_mov_b32_e32 v177, v153
	v_mul_f32_e32 v35, v35, v43
	v_lshl_add_u64 v[36:37], v[36:37], 0, v[176:177]
	v_cvt_pk_bf16_f32 v35, v38, v35
	global_store_dwordx4 v[36:37], v[32:35], off

; __device__ __forceinline__ float bf_lo(unsigned w) { return __uint_as_float(w << 16); }
; __device__ __forceinline__ float bf_hi(unsigned w) { return __uint_as_float(w & 0xffff0000u); }
; __device__ __forceinline__ u32x4 pack8(const f32x4 a, const f32x4 b) { u32x4 w; w.x = cvt_pk_bf16(a[0], a[1]); w.y = cvt_pk_bf16(a[2], a[3]); w.z = cvt_pk_bf16(b[0], b[1]); w.w = cvt_pk_bf16(b[2], b[3]); return w; }
;     __device__ __forceinline__ void operator()(EPI_ARGS) const {
;     ...
;                 for (int m = 0; m < 4; ++m) { const int j = row0 + ai * HALF + m * 16;
;                     uw[m] = (j < NJ) ? *(const u32x4*)(AB + ((size_t)((g >> 1) * NJP + j) * ABP + (g & 1) * 384 + n)) : (u32x4){0u, 0u, 0u, 0u}; }
; #pragma unroll
;                 for (int m = 0; m < 4; ++m) { const int j = row0 + ai * HALF + m * 16;
;                     if (j < NJ) {
;                         const u32x4 w = uw[m];
;                         f32x4 u0 = {bf_lo(w.x), bf_hi(w.x), bf_lo(w.y), bf_hi(w.y)}, u1 = {bf_lo(w.z), bf_hi(w.z), bf_lo(w.w), bf_hi(w.w)};
;                         f32x4 y0 = acc[ai][bj][m][0] + d0 * u0, y1 = acc[ai][bj][m][1] + d1 * u1;
; #pragma unroll
;                         for (int e = 0; e < 4; ++e) {
;                             { const float y = y0[e], q = 1.5957691216f * (y + 0.044715f * y * y * y); y0[e] = y * __builtin_amdgcn_rcpf(1.0f + __expf(-q)); }
;                             { const float y = y1[e], q = 1.5957691216f * (y + 0.044715f * y * y * y); y1[e] = y * __builtin_amdgcn_rcpf(1.0f + __expf(-q)); }
;                         }
;                         *(u32x4*)(Z + (size_t)(j * TS + t) * WA + g * 16 + c) = pack8(y0, y1);
.LBB0_324:
	v_lshlrev_b32_e32 v24, 16, v40
	v_and_b32_e32 v25, 0xffff0000, v40
	v_lshlrev_b32_e32 v28, 16, v42
	v_and_b32_e32 v29, 0xffff0000, v42
	v_lshlrev_b32_e32 v26, 16, v41
	v_and_b32_e32 v27, 0xffff0000, v41
	v_pk_fma_f32 v[20:21], v[68:69], v[24:25], v[20:21]
	v_pk_fma_f32 v[16:17], v[64:65], v[28:29], v[16:17]
	v_mul_f32_e32 v24, 0x3d372713, v20
	v_pk_fma_f32 v[22:23], v[70:71], v[26:27], v[22:23]
	v_mul_f32_e32 v25, 0x3d372713, v16
	v_mul_f32_e32 v26, 0x3d372713, v21
	v_mul_f32_e32 v24, v20, v24
	v_mul_f32_e32 v25, v16, v25
	v_mul_f32_e32 v26, v21, v26
	v_fma_f32 v24, v20, v24, v20
	v_fma_f32 v25, v16, v25, v16
	v_fma_f32 v26, v21, v26, v21
	v_mul_f32_e32 v24, 0xbfcc422a, v24
	v_mul_f32_e32 v25, 0xbfcc422a, v25
	v_mul_f32_e32 v26, 0xbfcc422a, v26
	v_mul_f32_e32 v24, 0x3fb8aa3b, v24
	v_mul_f32_e32 v25, 0x3fb8aa3b, v25
	v_mul_f32_e32 v26, 0x3fb8aa3b, v26
	v_exp_f32_e32 v24, v24
	v_exp_f32_e32 v25, v25
	v_exp_f32_e32 v26, v26
	v_mul_f32_e32 v27, 0x3d372713, v17
	v_add_f32_e32 v24, 1.0, v24
	v_add_f32_e32 v25, 1.0, v25
	v_add_f32_e32 v26, 1.0, v26
	v_rcp_f32_e32 v24, v24
	v_rcp_f32_e32 v25, v25
	v_rcp_f32_e32 v26, v26
	v_mul_f32_e32 v27, v17, v27
	v_fma_f32 v27, v17, v27, v17
	v_lshlrev_b32_e32 v30, 16, v43
	v_and_b32_e32 v31, 0xffff0000, v43
	v_mul_f32_e32 v27, 0xbfcc422a, v27
	v_pk_fma_f32 v[18:19], v[66:67], v[30:31], v[18:19]
	v_mul_f32_e32 v27, 0x3fb8aa3b, v27
	v_exp_f32_e32 v27, v27
	v_mul_f32_e32 v20, v20, v24
	v_mul_f32_e32 v24, v16, v25
	v_mul_f32_e32 v16, v21, v26
	v_mul_f32_e32 v25, 0x3d372713, v22
	v_mul_f32_e32 v26, 0x3d372713, v18
	v_mul_f32_e32 v25, v22, v25
	v_mul_f32_e32 v26, v18, v26
	v_fma_f32 v25, v22, v25, v22
	v_fma_f32 v26, v18, v26, v18
	v_mul_f32_e32 v25, 0xbfcc422a, v25
	v_mul_f32_e32 v26, 0xbfcc422a, v26
	v_add_f32_e32 v21, 1.0, v27
	v_mul_f32_e32 v25, 0x3fb8aa3b, v25
	v_mul_f32_e32 v26, 0x3fb8aa3b, v26
	v_rcp_f32_e32 v21, v21
	v_exp_f32_e32 v25, v25
	v_exp_f32_e32 v26, v26
	v_mul_f32_e32 v27, 0x3d372713, v19
	v_mul_f32_e32 v21, v17, v21
	v_add_f32_e32 v17, 1.0, v25
	v_add_f32_e32 v25, 1.0, v26
	v_mul_f32_e32 v26, 0x3d372713, v23
	v_mul_f32_e32 v26, v23, v26
	v_fma_f32 v26, v23, v26, v23
	v_mul_f32_e32 v26, 0xbfcc422a, v26
	v_mul_f32_e32 v26, 0x3fb8aa3b, v26
	v_exp_f32_e32 v26, v26
	v_mul_f32_e32 v27, v19, v27
	v_fma_f32 v27, v19, v27, v19
	v_mul_f32_e32 v27, 0xbfcc422a, v27
	v_mul_f32_e32 v27, 0x3fb8aa3b, v27
	v_add_f32_e32 v26, 1.0, v26
	v_rcp_f32_e32 v17, v17
	v_exp_f32_e32 v27, v27
	v_rcp_f32_e32 v25, v25
	v_rcp_f32_e32 v26, v26
	v_mul_f32_e32 v17, v22, v17
	v_add_f32_e32 v27, 1.0, v27
	v_mul_f32_e32 v22, v18, v25
	v_mul_f32_e32 v18, v23, v26
	v_cvt_pk_bf16_f32 v16, v20, v16
	v_lshl_add_u32 v20, v122, 4, v88
	v_rcp_f32_e32 v27, v27
	v_cvt_pk_bf16_f32 v17, v17, v18
	v_cvt_pk_bf16_f32 v18, v24, v21
	v_ashrrev_i32_e32 v21, 31, v20
	v_lshlrev_b64 v[20:21], 10, v[20:21]
	v_lshl_add_u64 v[20:21], s[0:1], 0, v[20:21]
	v_lshl_add_u64 v[20:21], s[60:61], 1, v[20:21]
	v_mov_b32_e32 v177, v153
	v_mul_f32_e32 v19, v19, v27
	v_lshl_add_u64 v[20:21], v[20:21], 0, v[176:177]
	v_cvt_pk_bf16_f32 v19, v22, v19
	global_store_dwordx4 v[20:21], v[16:19], off
	s_or_b64 exec, exec, s[8:9]
	s_and_saveexec_b64 s[8:9], s[10:11]
	s_cbranch_execnz .LBB0_330

; __device__ __forceinline__ float bf_lo(unsigned w) { return __uint_as_float(w << 16); }
; __device__ __forceinline__ float bf_hi(unsigned w) { return __uint_as_float(w & 0xffff0000u); }
; __device__ __forceinline__ u32x4 pack8(const f32x4 a, const f32x4 b) { u32x4 w; w.x = cvt_pk_bf16(a[0], a[1]); w.y = cvt_pk_bf16(a[2], a[3]); w.z = cvt_pk_bf16(b[0], b[1]); w.w = cvt_pk_bf16(b[2], b[3]); return w; }
;     __device__ __forceinline__ void operator()(EPI_ARGS) const {
;     ...
;                 for (int m = 0; m < 4; ++m) { const int j = row0 + ai * HALF + m * 16;
;                     uw[m] = (j < NJ) ? *(const u32x4*)(AB + ((size_t)((g >> 1) * NJP + j) * ABP + (g & 1) * 384 + n)) : (u32x4){0u, 0u, 0u, 0u}; }
; #pragma unroll
;                 for (int m = 0; m < 4; ++m) { const int j = row0 + ai * HALF + m * 16;
;                     if (j < NJ) {
;                         const u32x4 w = uw[m];
;                         f32x4 u0 = {bf_lo(w.x), bf_hi(w.x), bf_lo(w.y), bf_hi(w.y)}, u1 = {bf_lo(w.z), bf_hi(w.z), bf_lo(w.w), bf_hi(w.w)};
;                         f32x4 y0 = acc[ai][bj][m][0] + d0 * u0, y1 = acc[ai][bj][m][1] + d1 * u1;
; #pragma unroll
;                         for (int e = 0; e < 4; ++e) {
;                             { const float y = y0[e], q = 1.5957691216f * (y + 0.044715f * y * y * y); y0[e] = y * __builtin_amdgcn_rcpf(1.0f + __expf(-q)); }
;                             { const float y = y1[e], q = 1.5957691216f * (y + 0.044715f * y * y * y); y1[e] = y * __builtin_amdgcn_rcpf(1.0f + __expf(-q)); }
;                         }
;                         *(u32x4*)(Z + (size_t)(j * TS + t) * WA + g * 16 + c) = pack8(y0, y1);
.LBB0_326:
	v_lshlrev_b32_e32 v8, 16, v32
	v_and_b32_e32 v9, 0xffff0000, v32
	v_lshlrev_b32_e32 v12, 16, v34
	v_and_b32_e32 v13, 0xffff0000, v34
	v_lshlrev_b32_e32 v10, 16, v33
	v_and_b32_e32 v11, 0xffff0000, v33
	v_pk_fma_f32 v[4:5], v[68:69], v[8:9], v[4:5]
	v_pk_fma_f32 v[0:1], v[64:65], v[12:13], v[0:1]
	v_mul_f32_e32 v8, 0x3d372713, v4
	v_pk_fma_f32 v[6:7], v[70:71], v[10:11], v[6:7]
	v_mul_f32_e32 v9, 0x3d372713, v0
	v_mul_f32_e32 v10, 0x3d372713, v5
	v_mul_f32_e32 v8, v4, v8
	v_mul_f32_e32 v9, v0, v9
	v_mul_f32_e32 v10, v5, v10
	v_fma_f32 v8, v4, v8, v4
	v_fma_f32 v9, v0, v9, v0
	v_fma_f32 v10, v5, v10, v5
	v_mul_f32_e32 v8, 0xbfcc422a, v8
	v_mul_f32_e32 v9, 0xbfcc422a, v9
	v_mul_f32_e32 v10, 0xbfcc422a, v10
	v_mul_f32_e32 v8, 0x3fb8aa3b, v8
	v_mul_f32_e32 v9, 0x3fb8aa3b, v9
	v_mul_f32_e32 v10, 0x3fb8aa3b, v10
	v_exp_f32_e32 v8, v8
	v_exp_f32_e32 v9, v9
	v_exp_f32_e32 v10, v10
	v_mul_f32_e32 v11, 0x3d372713, v1
	v_add_f32_e32 v8, 1.0, v8
	v_add_f32_e32 v9, 1.0, v9
	v_add_f32_e32 v10, 1.0, v10
	v_rcp_f32_e32 v8, v8
	v_rcp_f32_e32 v9, v9
	v_rcp_f32_e32 v10, v10
	v_mul_f32_e32 v11, v1, v11
	v_fma_f32 v11, v1, v11, v1
	v_lshlrev_b32_e32 v14, 16, v35
	v_and_b32_e32 v15, 0xffff0000, v35
	v_mul_f32_e32 v11, 0xbfcc422a, v11
	v_pk_fma_f32 v[2:3], v[66:67], v[14:15], v[2:3]
	v_mul_f32_e32 v11, 0x3fb8aa3b, v11
	v_exp_f32_e32 v11, v11
	v_mul_f32_e32 v4, v4, v8
	v_mul_f32_e32 v8, v0, v9
	v_mul_f32_e32 v0, v5, v10
	v_mul_f32_e32 v9, 0x3d372713, v6
	v_mul_f32_e32 v10, 0x3d372713, v2
	v_mul_f32_e32 v9, v6, v9
	v_mul_f32_e32 v10, v2, v10
	v_fma_f32 v9, v6, v9, v6
	v_fma_f32 v10, v2, v10, v2
	v_mul_f32_e32 v9, 0xbfcc422a, v9
	v_mul_f32_e32 v10, 0xbfcc422a, v10
	v_add_f32_e32 v5, 1.0, v11
	v_mul_f32_e32 v9, 0x3fb8aa3b, v9
	v_mul_f32_e32 v10, 0x3fb8aa3b, v10
	v_rcp_f32_e32 v5, v5
	v_exp_f32_e32 v9, v9
	v_exp_f32_e32 v10, v10
	v_mul_f32_e32 v11, 0x3d372713, v3
	v_mul_f32_e32 v5, v1, v5
	v_add_f32_e32 v1, 1.0, v9
	v_add_f32_e32 v9, 1.0, v10
	v_mul_f32_e32 v10, 0x3d372713, v7
	v_mul_f32_e32 v10, v7, v10
	v_fma_f32 v10, v7, v10, v7
	v_mul_f32_e32 v10, 0xbfcc422a, v10
	v_mul_f32_e32 v10, 0x3fb8aa3b, v10
	v_exp_f32_e32 v10, v10
	v_mul_f32_e32 v11, v3, v11
	v_fma_f32 v11, v3, v11, v3
	v_mul_f32_e32 v11, 0xbfcc422a, v11
	v_mul_f32_e32 v11, 0x3fb8aa3b, v11
	v_add_f32_e32 v10, 1.0, v10
	v_rcp_f32_e32 v1, v1
	v_exp_f32_e32 v11, v11
	v_rcp_f32_e32 v9, v9
	v_rcp_f32_e32 v10, v10
	v_mul_f32_e32 v1, v6, v1
	v_add_f32_e32 v11, 1.0, v11
	v_mul_f32_e32 v6, v2, v9
	v_mul_f32_e32 v2, v7, v10
	v_cvt_pk_bf16_f32 v0, v4, v0
	v_lshl_add_u32 v4, v120, 4, v88
	v_rcp_f32_e32 v11, v11
	v_cvt_pk_bf16_f32 v1, v1, v2
	v_cvt_pk_bf16_f32 v2, v8, v5
	v_ashrrev_i32_e32 v5, 31, v4
	v_lshlrev_b64 v[4:5], 10, v[4:5]
	v_lshl_add_u64 v[4:5], s[0:1], 0, v[4:5]
	v_lshl_add_u64 v[4:5], s[60:61], 1, v[4:5]
	v_mov_b32_e32 v177, v153
	v_mul_f32_e32 v3, v3, v11
	v_lshl_add_u64 v[4:5], v[4:5], 0, v[176:177]
	v_cvt_pk_bf16_f32 v3, v6, v3
	global_store_dwordx4 v[4:5], v[0:3], off
	s_or_b64 exec, exec, s[8:9]
	s_and_b64 vcc, exec, s[4:5]
	s_mov_b64 s[4:5], -1
	s_cbranch_vccnz .LBB0_252
	s_branch .LBB0_332

; __device__ __forceinline__ float bf_lo(unsigned w) { return __uint_as_float(w << 16); }
; __device__ __forceinline__ float bf_hi(unsigned w) { return __uint_as_float(w & 0xffff0000u); }
; __device__ __forceinline__ u32x4 pack8(const f32x4 a, const f32x4 b) { u32x4 w; w.x = cvt_pk_bf16(a[0], a[1]); w.y = cvt_pk_bf16(a[2], a[3]); w.z = cvt_pk_bf16(b[0], b[1]); w.w = cvt_pk_bf16(b[2], b[3]); return w; }
;     __device__ __forceinline__ void operator()(EPI_ARGS) const {
;     ...
;                 for (int m = 0; m < 4; ++m) { const int j = row0 + ai * HALF + m * 16;
;                     uw[m] = (j < NJ) ? *(const u32x4*)(AB + ((size_t)((g >> 1) * NJP + j) * ABP + (g & 1) * 384 + n)) : (u32x4){0u, 0u, 0u, 0u}; }
; #pragma unroll
;                 for (int m = 0; m < 4; ++m) { const int j = row0 + ai * HALF + m * 16;
;                     if (j < NJ) {
;                         const u32x4 w = uw[m];
;                         f32x4 u0 = {bf_lo(w.x), bf_hi(w.x), bf_lo(w.y), bf_hi(w.y)}, u1 = {bf_lo(w.z), bf_hi(w.z), bf_lo(w.w), bf_hi(w.w)};
;                         f32x4 y0 = acc[ai][bj][m][0] + d0 * u0, y1 = acc[ai][bj][m][1] + d1 * u1;
; #pragma unroll
;                         for (int e = 0; e < 4; ++e) {
;                             { const float y = y0[e], q = 1.5957691216f * (y + 0.044715f * y * y * y); y0[e] = y * __builtin_amdgcn_rcpf(1.0f + __expf(-q)); }
;                             { const float y = y1[e], q = 1.5957691216f * (y + 0.044715f * y * y * y); y1[e] = y * __builtin_amdgcn_rcpf(1.0f + __expf(-q)); }
;                         }
;                         *(u32x4*)(Z + (size_t)(j * TS + t) * WA + g * 16 + c) = pack8(y0, y1);
.LBB0_330:
	v_lshlrev_b32_e32 v16, 16, v36
	v_and_b32_e32 v17, 0xffff0000, v36
	v_lshlrev_b32_e32 v20, 16, v38
	v_and_b32_e32 v21, 0xffff0000, v38
	v_lshlrev_b32_e32 v18, 16, v37
	v_and_b32_e32 v19, 0xffff0000, v37
	v_pk_fma_f32 v[12:13], v[68:69], v[16:17], v[12:13]
	v_pk_fma_f32 v[8:9], v[64:65], v[20:21], v[8:9]
	v_mul_f32_e32 v16, 0x3d372713, v12
	v_pk_fma_f32 v[14:15], v[70:71], v[18:19], v[14:15]
	v_mul_f32_e32 v17, 0x3d372713, v8
	v_mul_f32_e32 v18, 0x3d372713, v13
	v_mul_f32_e32 v16, v12, v16
	v_mul_f32_e32 v17, v8, v17
	v_mul_f32_e32 v18, v13, v18
	v_fma_f32 v16, v12, v16, v12
	v_fma_f32 v17, v8, v17, v8
	v_fma_f32 v18, v13, v18, v13
	v_mul_f32_e32 v16, 0xbfcc422a, v16
	v_mul_f32_e32 v17, 0xbfcc422a, v17
	v_mul_f32_e32 v18, 0xbfcc422a, v18
	v_mul_f32_e32 v16, 0x3fb8aa3b, v16
	v_mul_f32_e32 v17, 0x3fb8aa3b, v17
	v_mul_f32_e32 v18, 0x3fb8aa3b, v18
	v_exp_f32_e32 v16, v16
	v_exp_f32_e32 v17, v17
	v_exp_f32_e32 v18, v18
	v_mul_f32_e32 v19, 0x3d372713, v9
	v_add_f32_e32 v16, 1.0, v16
	v_add_f32_e32 v17, 1.0, v17
	v_add_f32_e32 v18, 1.0, v18
	v_rcp_f32_e32 v16, v16
	v_rcp_f32_e32 v17, v17
	v_rcp_f32_e32 v18, v18
	v_mul_f32_e32 v19, v9, v19
	v_fma_f32 v19, v9, v19, v9
	v_lshlrev_b32_e32 v22, 16, v39
	v_and_b32_e32 v23, 0xffff0000, v39
	v_mul_f32_e32 v19, 0xbfcc422a, v19
	v_pk_fma_f32 v[10:11], v[66:67], v[22:23], v[10:11]
	v_mul_f32_e32 v19, 0x3fb8aa3b, v19
	v_exp_f32_e32 v19, v19
	v_mul_f32_e32 v12, v12, v16
	v_mul_f32_e32 v16, v8, v17
	v_mul_f32_e32 v8, v13, v18
	v_mul_f32_e32 v17, 0x3d372713, v14
	v_mul_f32_e32 v18, 0x3d372713, v10
	v_mul_f32_e32 v17, v14, v17
	v_mul_f32_e32 v18, v10, v18
	v_fma_f32 v17, v14, v17, v14
	v_fma_f32 v18, v10, v18, v10
	v_mul_f32_e32 v17, 0xbfcc422a, v17
	v_mul_f32_e32 v18, 0xbfcc422a, v18
	v_add_f32_e32 v13, 1.0, v19
	v_mul_f32_e32 v17, 0x3fb8aa3b, v17
	v_mul_f32_e32 v18, 0x3fb8aa3b, v18
	v_rcp_f32_e32 v13, v13
	v_exp_f32_e32 v17, v17
	v_exp_f32_e32 v18, v18
	v_mul_f32_e32 v19, 0x3d372713, v11
	v_mul_f32_e32 v13, v9, v13
	v_add_f32_e32 v9, 1.0, v17
	v_add_f32_e32 v17, 1.0, v18
	v_mul_f32_e32 v18, 0x3d372713, v15
	v_mul_f32_e32 v18, v15, v18
	v_fma_f32 v18, v15, v18, v15
	v_mul_f32_e32 v18, 0xbfcc422a, v18
	v_mul_f32_e32 v18, 0x3fb8aa3b, v18
	v_exp_f32_e32 v18, v18
	v_mul_f32_e32 v19, v11, v19
	v_fma_f32 v19, v11, v19, v11
	v_mul_f32_e32 v19, 0xbfcc422a, v19
	v_mul_f32_e32 v19, 0x3fb8aa3b, v19
	v_add_f32_e32 v18, 1.0, v18
	v_rcp_f32_e32 v9, v9
	v_exp_f32_e32 v19, v19
	v_rcp_f32_e32 v17, v17
	v_rcp_f32_e32 v18, v18
	v_mul_f32_e32 v9, v14, v9
	v_add_f32_e32 v19, 1.0, v19
	v_mul_f32_e32 v14, v10, v17
	v_mul_f32_e32 v10, v15, v18
	v_cvt_pk_bf16_f32 v8, v12, v8
	v_lshl_add_u32 v12, v121, 4, v88
	v_rcp_f32_e32 v19, v19
	v_cvt_pk_bf16_f32 v9, v9, v10
	v_cvt_pk_bf16_f32 v10, v16, v13
	v_ashrrev_i32_e32 v13, 31, v12
	v_lshlrev_b64 v[12:13], 10, v[12:13]
	v_lshl_add_u64 v[12:13], s[0:1], 0, v[12:13]
	v_lshl_add_u64 v[12:13], s[60:61], 1, v[12:13]
	v_mov_b32_e32 v177, v153
	v_mul_f32_e32 v11, v11, v19
	v_lshl_add_u64 v[12:13], v[12:13], 0, v[176:177]
	v_cvt_pk_bf16_f32 v11, v14, v11
	global_store_dwordx4 v[12:13], v[8:11], off
	s_or_b64 exec, exec, s[8:9]
	s_and_saveexec_b64 s[8:9], s[6:7]
	s_cbranch_execnz .LBB0_326

; __device__ __forceinline__ float bf_lo(unsigned w) { return __uint_as_float(w << 16); }
; __device__ __forceinline__ float bf_hi(unsigned w) { return __uint_as_float(w & 0xffff0000u); }
; __device__ __forceinline__ u32x4 pack8(const f32x4 a, const f32x4 b) { u32x4 w; w.x = cvt_pk_bf16(a[0], a[1]); w.y = cvt_pk_bf16(a[2], a[3]); w.z = cvt_pk_bf16(b[0], b[1]); w.w = cvt_pk_bf16(b[2], b[3]); return w; }
;     __device__ __forceinline__ void operator()(EPI_ARGS) const {
;     ...
;                 for (int m = 0; m < 4; ++m) { const int j = row0 + ai * HALF + m * 16;
;                     uw[m] = (j < NJ) ? *(const u32x4*)(AB + ((size_t)((g >> 1) * NJP + j) * ABP + (g & 1) * 384 + n)) : (u32x4){0u, 0u, 0u, 0u}; }
; #pragma unroll
;                 for (int m = 0; m < 4; ++m) { const int j = row0 + ai * HALF + m * 16;
;                     if (j < NJ) {
;                         const u32x4 w = uw[m];
;                         f32x4 u0 = {bf_lo(w.x), bf_hi(w.x), bf_lo(w.y), bf_hi(w.y)}, u1 = {bf_lo(w.z), bf_hi(w.z), bf_lo(w.w), bf_hi(w.w)};
;                         f32x4 y0 = acc[ai][bj][m][0] + d0 * u0, y1 = acc[ai][bj][m][1] + d1 * u1;
; #pragma unroll
;                         for (int e = 0; e < 4; ++e) {
;                             { const float y = y0[e], q = 1.5957691216f * (y + 0.044715f * y * y * y); y0[e] = y * __builtin_amdgcn_rcpf(1.0f + __expf(-q)); }
;                             { const float y = y1[e], q = 1.5957691216f * (y + 0.044715f * y * y * y); y1[e] = y * __builtin_amdgcn_rcpf(1.0f + __expf(-q)); }
;                         }
;                         *(u32x4*)(Z + (size_t)(j * TS + t) * WA + g * 16 + c) = pack8(y0, y1);
.LBB0_375:
	v_lshlrev_b32_e32 v120, 16, v140
	v_and_b32_e32 v121, 0xffff0000, v140
	v_lshlrev_b32_e32 v124, 16, v142
	v_and_b32_e32 v125, 0xffff0000, v142
	v_lshlrev_b32_e32 v122, 16, v141
	v_and_b32_e32 v123, 0xffff0000, v141
	v_pk_fma_f32 v[116:117], v[108:109], v[120:121], v[116:117]
	v_pk_fma_f32 v[112:113], v[104:105], v[124:125], v[112:113]
	v_mul_f32_e32 v120, 0x3d372713, v116
	v_pk_fma_f32 v[118:119], v[110:111], v[122:123], v[118:119]
	v_mul_f32_e32 v121, 0x3d372713, v112
	v_mul_f32_e32 v122, 0x3d372713, v117
	v_mul_f32_e32 v120, v116, v120
	v_mul_f32_e32 v121, v112, v121
	v_mul_f32_e32 v122, v117, v122
	v_fma_f32 v120, v116, v120, v116
	v_fma_f32 v121, v112, v121, v112
	v_fma_f32 v122, v117, v122, v117
	v_mul_f32_e32 v120, 0xbfcc422a, v120
	v_mul_f32_e32 v121, 0xbfcc422a, v121
	v_mul_f32_e32 v122, 0xbfcc422a, v122
	v_mul_f32_e32 v120, 0x3fb8aa3b, v120
	v_mul_f32_e32 v121, 0x3fb8aa3b, v121
	v_mul_f32_e32 v122, 0x3fb8aa3b, v122
	v_exp_f32_e32 v120, v120
	v_exp_f32_e32 v121, v121
	v_exp_f32_e32 v122, v122
	v_mul_f32_e32 v123, 0x3d372713, v113
	v_add_f32_e32 v120, 1.0, v120
	v_add_f32_e32 v121, 1.0, v121
	v_add_f32_e32 v122, 1.0, v122
	v_rcp_f32_e32 v120, v120
	v_rcp_f32_e32 v121, v121
	v_rcp_f32_e32 v122, v122
	v_mul_f32_e32 v123, v113, v123
	v_fma_f32 v123, v113, v123, v113
	v_lshlrev_b32_e32 v126, 16, v143
	v_and_b32_e32 v127, 0xffff0000, v143
	v_mul_f32_e32 v123, 0xbfcc422a, v123
	v_pk_fma_f32 v[114:115], v[106:107], v[126:127], v[114:115]
	v_mul_f32_e32 v123, 0x3fb8aa3b, v123
	v_exp_f32_e32 v123, v123
	v_mul_f32_e32 v116, v116, v120
	v_mul_f32_e32 v120, v112, v121
	v_mul_f32_e32 v112, v117, v122
	v_mul_f32_e32 v121, 0x3d372713, v118
	v_mul_f32_e32 v122, 0x3d372713, v114
	v_mul_f32_e32 v121, v118, v121
	v_mul_f32_e32 v122, v114, v122
	v_fma_f32 v121, v118, v121, v118
	v_fma_f32 v122, v114, v122, v114
	v_mul_f32_e32 v121, 0xbfcc422a, v121
	v_mul_f32_e32 v122, 0xbfcc422a, v122
	v_add_f32_e32 v117, 1.0, v123
	v_mul_f32_e32 v121, 0x3fb8aa3b, v121
	v_mul_f32_e32 v122, 0x3fb8aa3b, v122
	v_rcp_f32_e32 v117, v117
	v_exp_f32_e32 v121, v121
	v_exp_f32_e32 v122, v122
	v_mul_f32_e32 v123, 0x3d372713, v115
	v_mul_f32_e32 v117, v113, v117
	v_add_f32_e32 v113, 1.0, v121
	v_add_f32_e32 v121, 1.0, v122
	v_mul_f32_e32 v122, 0x3d372713, v119
	v_mul_f32_e32 v122, v119, v122
	v_fma_f32 v122, v119, v122, v119
	v_mul_f32_e32 v122, 0xbfcc422a, v122
	v_mul_f32_e32 v122, 0x3fb8aa3b, v122
	v_exp_f32_e32 v122, v122
	v_mul_f32_e32 v123, v115, v123
	v_fma_f32 v123, v115, v123, v115
	v_mul_f32_e32 v123, 0xbfcc422a, v123
	v_mul_f32_e32 v123, 0x3fb8aa3b, v123
	v_add_f32_e32 v122, 1.0, v122
	v_rcp_f32_e32 v113, v113
	v_exp_f32_e32 v123, v123
	v_rcp_f32_e32 v121, v121
	v_rcp_f32_e32 v122, v122
	v_mul_f32_e32 v113, v118, v113
	v_add_f32_e32 v123, 1.0, v123
	v_mul_f32_e32 v118, v114, v121
	v_mul_f32_e32 v114, v119, v122
	v_cvt_pk_bf16_f32 v112, v116, v112
	v_lshl_add_u32 v116, v192, 4, v214
	v_rcp_f32_e32 v123, v123
	v_cvt_pk_bf16_f32 v113, v113, v114
	v_cvt_pk_bf16_f32 v114, v120, v117
	v_ashrrev_i32_e32 v117, 31, v116
	v_lshlrev_b64 v[116:117], 10, v[116:117]
	v_lshl_add_u64 v[116:117], v[174:175], 0, v[116:117]
	v_lshl_add_u64 v[116:117], s[56:57], 1, v[116:117]
	v_mov_b32_e32 v183, v153
	v_mul_f32_e32 v115, v115, v123
	v_lshl_add_u64 v[116:117], v[116:117], 0, v[182:183]
	v_cvt_pk_bf16_f32 v115, v118, v115
	global_store_dwordx4 v[116:117], v[112:115], off
	s_or_b64 exec, exec, s[6:7]
	s_and_saveexec_b64 s[6:7], vcc
	s_cbranch_execnz .LBB0_379
	s_branch .LBB0_380

; __device__ __forceinline__ float bf_lo(unsigned w) { return __uint_as_float(w << 16); }
; __device__ __forceinline__ float bf_hi(unsigned w) { return __uint_as_float(w & 0xffff0000u); }
; __device__ __forceinline__ u32x4 pack8(const f32x4 a, const f32x4 b) { u32x4 w; w.x = cvt_pk_bf16(a[0], a[1]); w.y = cvt_pk_bf16(a[2], a[3]); w.z = cvt_pk_bf16(b[0], b[1]); w.w = cvt_pk_bf16(b[2], b[3]); return w; }
;     __device__ __forceinline__ void operator()(EPI_ARGS) const {
;     ...
;                 for (int m = 0; m < 4; ++m) { const int j = row0 + ai * HALF + m * 16;
;                     uw[m] = (j < NJ) ? *(const u32x4*)(AB + ((size_t)((g >> 1) * NJP + j) * ABP + (g & 1) * 384 + n)) : (u32x4){0u, 0u, 0u, 0u}; }
; #pragma unroll
;                 for (int m = 0; m < 4; ++m) { const int j = row0 + ai * HALF + m * 16;
;                     if (j < NJ) {
;                         const u32x4 w = uw[m];
;                         f32x4 u0 = {bf_lo(w.x), bf_hi(w.x), bf_lo(w.y), bf_hi(w.y)}, u1 = {bf_lo(w.z), bf_hi(w.z), bf_lo(w.w), bf_hi(w.w)};
;                         f32x4 y0 = acc[ai][bj][m][0] + d0 * u0, y1 = acc[ai][bj][m][1] + d1 * u1;
; #pragma unroll
;                         for (int e = 0; e < 4; ++e) {
;                             { const float y = y0[e], q = 1.5957691216f * (y + 0.044715f * y * y * y); y0[e] = y * __builtin_amdgcn_rcpf(1.0f + __expf(-q)); }
;                             { const float y = y1[e], q = 1.5957691216f * (y + 0.044715f * y * y * y); y1[e] = y * __builtin_amdgcn_rcpf(1.0f + __expf(-q)); }
;                         }
;                         *(u32x4*)(Z + (size_t)(j * TS + t) * WA + g * 16 + c) = pack8(y0, y1);
.LBB0_377:
	v_lshlrev_b32_e32 v128, 16, v144
	v_and_b32_e32 v129, 0xffff0000, v144
	v_lshlrev_b32_e32 v132, 16, v146
	v_and_b32_e32 v133, 0xffff0000, v146
	v_lshlrev_b32_e32 v130, 16, v145
	v_and_b32_e32 v131, 0xffff0000, v145
	v_pk_fma_f32 v[124:125], v[108:109], v[128:129], v[124:125]
	v_pk_fma_f32 v[120:121], v[104:105], v[132:133], v[120:121]
	v_mul_f32_e32 v128, 0x3d372713, v124
	v_pk_fma_f32 v[126:127], v[110:111], v[130:131], v[126:127]
	v_mul_f32_e32 v129, 0x3d372713, v120
	v_mul_f32_e32 v130, 0x3d372713, v125
	v_mul_f32_e32 v128, v124, v128
	v_mul_f32_e32 v129, v120, v129
	v_mul_f32_e32 v130, v125, v130
	v_fma_f32 v128, v124, v128, v124
	v_fma_f32 v129, v120, v129, v120
	v_fma_f32 v130, v125, v130, v125
	v_mul_f32_e32 v128, 0xbfcc422a, v128
	v_mul_f32_e32 v129, 0xbfcc422a, v129
	v_mul_f32_e32 v130, 0xbfcc422a, v130
	v_mul_f32_e32 v128, 0x3fb8aa3b, v128
	v_mul_f32_e32 v129, 0x3fb8aa3b, v129
	v_mul_f32_e32 v130, 0x3fb8aa3b, v130
	v_exp_f32_e32 v128, v128
	v_exp_f32_e32 v129, v129
	v_exp_f32_e32 v130, v130
	v_mul_f32_e32 v131, 0x3d372713, v121
	v_add_f32_e32 v128, 1.0, v128
	v_add_f32_e32 v129, 1.0, v129
	v_add_f32_e32 v130, 1.0, v130
	v_rcp_f32_e32 v128, v128
	v_rcp_f32_e32 v129, v129
	v_rcp_f32_e32 v130, v130
	v_mul_f32_e32 v131, v121, v131
	v_fma_f32 v131, v121, v131, v121
	v_lshlrev_b32_e32 v134, 16, v147
	v_and_b32_e32 v135, 0xffff0000, v147
	v_mul_f32_e32 v131, 0xbfcc422a, v131
	v_pk_fma_f32 v[122:123], v[106:107], v[134:135], v[122:123]
	v_mul_f32_e32 v131, 0x3fb8aa3b, v131
	v_exp_f32_e32 v131, v131
	v_mul_f32_e32 v124, v124, v128
	v_mul_f32_e32 v128, v120, v129
	v_mul_f32_e32 v120, v125, v130
	v_mul_f32_e32 v129, 0x3d372713, v126
	v_mul_f32_e32 v130, 0x3d372713, v122
	v_mul_f32_e32 v129, v126, v129
	v_mul_f32_e32 v130, v122, v130
	v_fma_f32 v129, v126, v129, v126
	v_fma_f32 v130, v122, v130, v122
	v_mul_f32_e32 v129, 0xbfcc422a, v129
	v_mul_f32_e32 v130, 0xbfcc422a, v130
	v_add_f32_e32 v125, 1.0, v131
	v_mul_f32_e32 v129, 0x3fb8aa3b, v129
	v_mul_f32_e32 v130, 0x3fb8aa3b, v130
	v_rcp_f32_e32 v125, v125
	v_exp_f32_e32 v129, v129
	v_exp_f32_e32 v130, v130
	v_mul_f32_e32 v131, 0x3d372713, v123
	v_mul_f32_e32 v125, v121, v125
	v_add_f32_e32 v121, 1.0, v129
	v_add_f32_e32 v129, 1.0, v130
	v_mul_f32_e32 v130, 0x3d372713, v127
	v_mul_f32_e32 v130, v127, v130
	v_fma_f32 v130, v127, v130, v127
	v_mul_f32_e32 v130, 0xbfcc422a, v130
	v_mul_f32_e32 v130, 0x3fb8aa3b, v130
	v_exp_f32_e32 v130, v130
	v_mul_f32_e32 v131, v123, v131
	v_fma_f32 v131, v123, v131, v123
	v_mul_f32_e32 v131, 0xbfcc422a, v131
	v_mul_f32_e32 v131, 0x3fb8aa3b, v131
	v_add_f32_e32 v130, 1.0, v130
	v_rcp_f32_e32 v121, v121
	v_exp_f32_e32 v131, v131
	v_rcp_f32_e32 v129, v129
	v_rcp_f32_e32 v130, v130
	v_mul_f32_e32 v121, v126, v121
	v_add_f32_e32 v131, 1.0, v131
	v_mul_f32_e32 v126, v122, v129
	v_mul_f32_e32 v122, v127, v130
	v_cvt_pk_bf16_f32 v120, v124, v120
	v_lshl_add_u32 v124, v193, 4, v214
	v_rcp_f32_e32 v131, v131
	v_cvt_pk_bf16_f32 v121, v121, v122
	v_cvt_pk_bf16_f32 v122, v128, v125
	v_ashrrev_i32_e32 v125, 31, v124
	v_lshlrev_b64 v[124:125], 10, v[124:125]
	v_lshl_add_u64 v[124:125], v[174:175], 0, v[124:125]
	v_lshl_add_u64 v[124:125], s[56:57], 1, v[124:125]
	v_mov_b32_e32 v183, v153
	v_mul_f32_e32 v123, v123, v131
	v_lshl_add_u64 v[124:125], v[124:125], 0, v[182:183]
	v_cvt_pk_bf16_f32 v123, v126, v123
	global_store_dwordx4 v[124:125], v[120:123], off
	s_or_b64 exec, exec, s[6:7]
	s_and_saveexec_b64 s[6:7], s[8:9]
	s_cbranch_execnz .LBB0_375

; __device__ __forceinline__ float bf_lo(unsigned w) { return __uint_as_float(w << 16); }
; __device__ __forceinline__ float bf_hi(unsigned w) { return __uint_as_float(w & 0xffff0000u); }
; __device__ __forceinline__ u32x4 pack8(const f32x4 a, const f32x4 b) { u32x4 w; w.x = cvt_pk_bf16(a[0], a[1]); w.y = cvt_pk_bf16(a[2], a[3]); w.z = cvt_pk_bf16(b[0], b[1]); w.w = cvt_pk_bf16(b[2], b[3]); return w; }
;     __device__ __forceinline__ void operator()(EPI_ARGS) const {
;     ...
;                 for (int m = 0; m < 4; ++m) { const int j = row0 + ai * HALF + m * 16;
;                     uw[m] = (j < NJ) ? *(const u32x4*)(AB + ((size_t)((g >> 1) * NJP + j) * ABP + (g & 1) * 384 + n)) : (u32x4){0u, 0u, 0u, 0u}; }
; #pragma unroll
;                 for (int m = 0; m < 4; ++m) { const int j = row0 + ai * HALF + m * 16;
;                     if (j < NJ) {
;                         const u32x4 w = uw[m];
;                         f32x4 u0 = {bf_lo(w.x), bf_hi(w.x), bf_lo(w.y), bf_hi(w.y)}, u1 = {bf_lo(w.z), bf_hi(w.z), bf_lo(w.w), bf_hi(w.w)};
;                         f32x4 y0 = acc[ai][bj][m][0] + d0 * u0, y1 = acc[ai][bj][m][1] + d1 * u1;
; #pragma unroll
;                         for (int e = 0; e < 4; ++e) {
;                             { const float y = y0[e], q = 1.5957691216f * (y + 0.044715f * y * y * y); y0[e] = y * __builtin_amdgcn_rcpf(1.0f + __expf(-q)); }
;                             { const float y = y1[e], q = 1.5957691216f * (y + 0.044715f * y * y * y); y1[e] = y * __builtin_amdgcn_rcpf(1.0f + __expf(-q)); }
;                         }
;                         *(u32x4*)(Z + (size_t)(j * TS + t) * WA + g * 16 + c) = pack8(y0, y1);
.LBB0_379:
	v_lshlrev_b32_e32 v112, 16, v136
	v_and_b32_e32 v113, 0xffff0000, v136
	v_lshlrev_b32_e32 v116, 16, v138
	v_and_b32_e32 v117, 0xffff0000, v138
	v_lshlrev_b32_e32 v114, 16, v137
	v_and_b32_e32 v115, 0xffff0000, v137
	v_pk_fma_f32 v[100:101], v[108:109], v[112:113], v[100:101]
	v_pk_fma_f32 v[96:97], v[104:105], v[116:117], v[96:97]
	v_mul_f32_e32 v112, 0x3d372713, v100
	v_pk_fma_f32 v[102:103], v[110:111], v[114:115], v[102:103]
	v_mul_f32_e32 v113, 0x3d372713, v96
	v_mul_f32_e32 v114, 0x3d372713, v101
	v_mul_f32_e32 v112, v100, v112
	v_mul_f32_e32 v113, v96, v113
	v_mul_f32_e32 v114, v101, v114
	v_fma_f32 v112, v100, v112, v100
	v_fma_f32 v113, v96, v113, v96
	v_fma_f32 v114, v101, v114, v101
	v_mul_f32_e32 v112, 0xbfcc422a, v112
	v_mul_f32_e32 v113, 0xbfcc422a, v113
	v_mul_f32_e32 v114, 0xbfcc422a, v114
	v_mul_f32_e32 v112, 0x3fb8aa3b, v112
	v_mul_f32_e32 v113, 0x3fb8aa3b, v113
	v_mul_f32_e32 v114, 0x3fb8aa3b, v114
	v_exp_f32_e32 v112, v112
	v_exp_f32_e32 v113, v113
	v_exp_f32_e32 v114, v114
	v_mul_f32_e32 v115, 0x3d372713, v97
	v_add_f32_e32 v112, 1.0, v112
	v_add_f32_e32 v113, 1.0, v113
	v_add_f32_e32 v114, 1.0, v114
	v_rcp_f32_e32 v112, v112
	v_rcp_f32_e32 v113, v113
	v_rcp_f32_e32 v114, v114
	v_mul_f32_e32 v115, v97, v115
	v_fma_f32 v115, v97, v115, v97
	v_lshlrev_b32_e32 v118, 16, v139
	v_and_b32_e32 v119, 0xffff0000, v139
	v_mul_f32_e32 v115, 0xbfcc422a, v115
	v_pk_fma_f32 v[98:99], v[106:107], v[118:119], v[98:99]
	v_mul_f32_e32 v115, 0x3fb8aa3b, v115
	v_exp_f32_e32 v115, v115
	v_mul_f32_e32 v100, v100, v112
	v_mul_f32_e32 v112, v96, v113
	v_mul_f32_e32 v96, v101, v114
	v_mul_f32_e32 v113, 0x3d372713, v102
	v_mul_f32_e32 v114, 0x3d372713, v98
	v_mul_f32_e32 v113, v102, v113
	v_mul_f32_e32 v114, v98, v114
	v_fma_f32 v113, v102, v113, v102
	v_fma_f32 v114, v98, v114, v98
	v_mul_f32_e32 v113, 0xbfcc422a, v113
	v_mul_f32_e32 v114, 0xbfcc422a, v114
	v_add_f32_e32 v101, 1.0, v115
	v_mul_f32_e32 v113, 0x3fb8aa3b, v113
	v_mul_f32_e32 v114, 0x3fb8aa3b, v114
	v_rcp_f32_e32 v101, v101
	v_exp_f32_e32 v113, v113
	v_exp_f32_e32 v114, v114
	v_mul_f32_e32 v115, 0x3d372713, v99
	v_mul_f32_e32 v101, v97, v101
	v_add_f32_e32 v97, 1.0, v113
	v_add_f32_e32 v113, 1.0, v114
	v_mul_f32_e32 v114, 0x3d372713, v103
	v_mul_f32_e32 v114, v103, v114
	v_fma_f32 v114, v103, v114, v103
	v_mul_f32_e32 v114, 0xbfcc422a, v114
	v_mul_f32_e32 v114, 0x3fb8aa3b, v114
	v_exp_f32_e32 v114, v114
	v_mul_f32_e32 v115, v99, v115
	v_fma_f32 v115, v99, v115, v99
	v_mul_f32_e32 v115, 0xbfcc422a, v115
	v_mul_f32_e32 v115, 0x3fb8aa3b, v115
	v_add_f32_e32 v114, 1.0, v114
	v_rcp_f32_e32 v97, v97
	v_exp_f32_e32 v115, v115
	v_rcp_f32_e32 v113, v113
	v_rcp_f32_e32 v114, v114
	v_mul_f32_e32 v97, v102, v97
	v_add_f32_e32 v115, 1.0, v115
	v_mul_f32_e32 v102, v98, v113
	v_mul_f32_e32 v98, v103, v114
	v_cvt_pk_bf16_f32 v96, v100, v96
	v_lshl_add_u32 v100, v187, 4, v214
	v_rcp_f32_e32 v115, v115
	v_cvt_pk_bf16_f32 v97, v97, v98
	v_cvt_pk_bf16_f32 v98, v112, v101
	v_ashrrev_i32_e32 v101, 31, v100
	v_lshlrev_b64 v[100:101], 10, v[100:101]
	v_lshl_add_u64 v[100:101], v[174:175], 0, v[100:101]
	v_lshl_add_u64 v[100:101], s[56:57], 1, v[100:101]
	v_mov_b32_e32 v183, v153
	v_mul_f32_e32 v99, v99, v115
	v_lshl_add_u64 v[100:101], v[100:101], 0, v[182:183]
	v_cvt_pk_bf16_f32 v99, v102, v99
	global_store_dwordx4 v[100:101], v[96:99], off

; __device__ __forceinline__ float bf_lo(unsigned w) { return __uint_as_float(w << 16); }
; __device__ __forceinline__ float bf_hi(unsigned w) { return __uint_as_float(w & 0xffff0000u); }
; __device__ __forceinline__ u32x4 pack8(const f32x4 a, const f32x4 b) { u32x4 w; w.x = cvt_pk_bf16(a[0], a[1]); w.y = cvt_pk_bf16(a[2], a[3]); w.z = cvt_pk_bf16(b[0], b[1]); w.w = cvt_pk_bf16(b[2], b[3]); return w; }
;     __device__ __forceinline__ void operator()(EPI_ARGS) const {
;     ...
;                 for (int m = 0; m < 4; ++m) { const int j = row0 + ai * HALF + m * 16;
;                     uw[m] = (j < NJ) ? *(const u32x4*)(AB + ((size_t)((g >> 1) * NJP + j) * ABP + (g & 1) * 384 + n)) : (u32x4){0u, 0u, 0u, 0u}; }
; #pragma unroll
;                 for (int m = 0; m < 4; ++m) { const int j = row0 + ai * HALF + m * 16;
;                     if (j < NJ) {
;                         const u32x4 w = uw[m];
;                         f32x4 u0 = {bf_lo(w.x), bf_hi(w.x), bf_lo(w.y), bf_hi(w.y)}, u1 = {bf_lo(w.z), bf_hi(w.z), bf_lo(w.w), bf_hi(w.w)};
;                         f32x4 y0 = acc[ai][bj][m][0] + d0 * u0, y1 = acc[ai][bj][m][1] + d1 * u1;
; #pragma unroll
;                         for (int e = 0; e < 4; ++e) {
;                             { const float y = y0[e], q = 1.5957691216f * (y + 0.044715f * y * y * y); y0[e] = y * __builtin_amdgcn_rcpf(1.0f + __expf(-q)); }
;                             { const float y = y1[e], q = 1.5957691216f * (y + 0.044715f * y * y * y); y1[e] = y * __builtin_amdgcn_rcpf(1.0f + __expf(-q)); }
;                         }
;                         *(u32x4*)(Z + (size_t)(j * TS + t) * WA + g * 16 + c) = pack8(y0, y1);
.LBB0_389:
	v_lshlrev_b32_e32 v88, 16, v112
	v_and_b32_e32 v89, 0xffff0000, v112
	v_lshlrev_b32_e32 v92, 16, v114
	v_and_b32_e32 v93, 0xffff0000, v114
	v_lshlrev_b32_e32 v90, 16, v113
	v_and_b32_e32 v91, 0xffff0000, v113
	v_pk_fma_f32 v[84:85], v[108:109], v[88:89], v[84:85]
	v_pk_fma_f32 v[80:81], v[104:105], v[92:93], v[80:81]
	v_mul_f32_e32 v88, 0x3d372713, v84
	v_pk_fma_f32 v[86:87], v[110:111], v[90:91], v[86:87]
	v_mul_f32_e32 v89, 0x3d372713, v80
	v_mul_f32_e32 v90, 0x3d372713, v85
	v_mul_f32_e32 v88, v84, v88
	v_mul_f32_e32 v89, v80, v89
	v_mul_f32_e32 v90, v85, v90
	v_fma_f32 v88, v84, v88, v84
	v_fma_f32 v89, v80, v89, v80
	v_fma_f32 v90, v85, v90, v85
	v_mul_f32_e32 v88, 0xbfcc422a, v88
	v_mul_f32_e32 v89, 0xbfcc422a, v89
	v_mul_f32_e32 v90, 0xbfcc422a, v90
	v_mul_f32_e32 v88, 0x3fb8aa3b, v88
	v_mul_f32_e32 v89, 0x3fb8aa3b, v89
	v_mul_f32_e32 v90, 0x3fb8aa3b, v90
	v_exp_f32_e32 v88, v88
	v_exp_f32_e32 v89, v89
	v_exp_f32_e32 v90, v90
	v_mul_f32_e32 v91, 0x3d372713, v81
	v_add_f32_e32 v88, 1.0, v88
	v_add_f32_e32 v89, 1.0, v89
	v_add_f32_e32 v90, 1.0, v90
	v_rcp_f32_e32 v88, v88
	v_rcp_f32_e32 v89, v89
	v_rcp_f32_e32 v90, v90
	v_mul_f32_e32 v91, v81, v91
	v_fma_f32 v91, v81, v91, v81
	v_lshlrev_b32_e32 v94, 16, v115
	v_and_b32_e32 v95, 0xffff0000, v115
	v_mul_f32_e32 v91, 0xbfcc422a, v91
	v_pk_fma_f32 v[82:83], v[106:107], v[94:95], v[82:83]
	v_mul_f32_e32 v91, 0x3fb8aa3b, v91
	v_exp_f32_e32 v91, v91
	v_mul_f32_e32 v84, v84, v88
	v_mul_f32_e32 v88, v80, v89
	v_mul_f32_e32 v80, v85, v90
	v_mul_f32_e32 v89, 0x3d372713, v86
	v_mul_f32_e32 v90, 0x3d372713, v82
	v_mul_f32_e32 v89, v86, v89
	v_mul_f32_e32 v90, v82, v90
	v_fma_f32 v89, v86, v89, v86
	v_fma_f32 v90, v82, v90, v82
	v_mul_f32_e32 v89, 0xbfcc422a, v89
	v_mul_f32_e32 v90, 0xbfcc422a, v90
	v_add_f32_e32 v85, 1.0, v91
	v_mul_f32_e32 v89, 0x3fb8aa3b, v89
	v_mul_f32_e32 v90, 0x3fb8aa3b, v90
	v_rcp_f32_e32 v85, v85
	v_exp_f32_e32 v89, v89
	v_exp_f32_e32 v90, v90
	v_mul_f32_e32 v91, 0x3d372713, v83
	v_mul_f32_e32 v85, v81, v85
	v_add_f32_e32 v81, 1.0, v89
	v_add_f32_e32 v89, 1.0, v90
	v_mul_f32_e32 v90, 0x3d372713, v87
	v_mul_f32_e32 v90, v87, v90
	v_fma_f32 v90, v87, v90, v87
	v_mul_f32_e32 v90, 0xbfcc422a, v90
	v_mul_f32_e32 v90, 0x3fb8aa3b, v90
	v_exp_f32_e32 v90, v90
	v_mul_f32_e32 v91, v83, v91
	v_fma_f32 v91, v83, v91, v83
	v_mul_f32_e32 v91, 0xbfcc422a, v91
	v_mul_f32_e32 v91, 0x3fb8aa3b, v91
	v_add_f32_e32 v90, 1.0, v90
	v_rcp_f32_e32 v81, v81
	v_exp_f32_e32 v91, v91
	v_rcp_f32_e32 v89, v89
	v_rcp_f32_e32 v90, v90
	v_mul_f32_e32 v81, v86, v81
	v_add_f32_e32 v91, 1.0, v91
	v_mul_f32_e32 v86, v82, v89
	v_mul_f32_e32 v82, v87, v90
	v_cvt_pk_bf16_f32 v80, v84, v80
	v_lshl_add_u32 v84, v122, 4, v214
	v_rcp_f32_e32 v91, v91
	v_cvt_pk_bf16_f32 v81, v81, v82
	v_cvt_pk_bf16_f32 v82, v88, v85
	v_ashrrev_i32_e32 v85, 31, v84
	v_lshlrev_b64 v[84:85], 10, v[84:85]
	v_lshl_add_u64 v[84:85], v[174:175], 0, v[84:85]
	v_lshl_add_u64 v[84:85], s[56:57], 1, v[84:85]
	v_mov_b32_e32 v183, v153
	v_mul_f32_e32 v83, v83, v91
	v_lshl_add_u64 v[84:85], v[84:85], 0, v[182:183]
	v_cvt_pk_bf16_f32 v83, v86, v83
	global_store_dwordx4 v[84:85], v[80:83], off
	s_or_b64 exec, exec, s[60:61]
	s_and_saveexec_b64 s[60:61], s[10:11]
	s_cbranch_execnz .LBB0_407

; __device__ __forceinline__ float bf_lo(unsigned w) { return __uint_as_float(w << 16); }
; __device__ __forceinline__ float bf_hi(unsigned w) { return __uint_as_float(w & 0xffff0000u); }
; __device__ __forceinline__ u32x4 pack8(const f32x4 a, const f32x4 b) { u32x4 w; w.x = cvt_pk_bf16(a[0], a[1]); w.y = cvt_pk_bf16(a[2], a[3]); w.z = cvt_pk_bf16(b[0], b[1]); w.w = cvt_pk_bf16(b[2], b[3]); return w; }
;     __device__ __forceinline__ void operator()(EPI_ARGS) const {
;     ...
;                 for (int m = 0; m < 4; ++m) { const int j = row0 + ai * HALF + m * 16;
;                     uw[m] = (j < NJ) ? *(const u32x4*)(AB + ((size_t)((g >> 1) * NJP + j) * ABP + (g & 1) * 384 + n)) : (u32x4){0u, 0u, 0u, 0u}; }
; #pragma unroll
;                 for (int m = 0; m < 4; ++m) { const int j = row0 + ai * HALF + m * 16;
;                     if (j < NJ) {
;                         const u32x4 w = uw[m];
;                         f32x4 u0 = {bf_lo(w.x), bf_hi(w.x), bf_lo(w.y), bf_hi(w.y)}, u1 = {bf_lo(w.z), bf_hi(w.z), bf_lo(w.w), bf_hi(w.w)};
;                         f32x4 y0 = acc[ai][bj][m][0] + d0 * u0, y1 = acc[ai][bj][m][1] + d1 * u1;
; #pragma unroll
;                         for (int e = 0; e < 4; ++e) {
;                             { const float y = y0[e], q = 1.5957691216f * (y + 0.044715f * y * y * y); y0[e] = y * __builtin_amdgcn_rcpf(1.0f + __expf(-q)); }
;                             { const float y = y1[e], q = 1.5957691216f * (y + 0.044715f * y * y * y); y1[e] = y * __builtin_amdgcn_rcpf(1.0f + __expf(-q)); }
;                         }
;                         *(u32x4*)(Z + (size_t)(j * TS + t) * WA + g * 16 + c) = pack8(y0, y1);
.LBB0_391:
	v_lshlrev_b32_e32 v72, 16, v96
	v_and_b32_e32 v73, 0xffff0000, v96
	v_lshlrev_b32_e32 v76, 16, v98
	v_and_b32_e32 v77, 0xffff0000, v98
	v_lshlrev_b32_e32 v74, 16, v97
	v_and_b32_e32 v75, 0xffff0000, v97
	v_pk_fma_f32 v[68:69], v[108:109], v[72:73], v[68:69]
	v_pk_fma_f32 v[64:65], v[104:105], v[76:77], v[64:65]
	v_mul_f32_e32 v72, 0x3d372713, v68
	v_pk_fma_f32 v[70:71], v[110:111], v[74:75], v[70:71]
	v_mul_f32_e32 v73, 0x3d372713, v64
	v_mul_f32_e32 v74, 0x3d372713, v69
	v_mul_f32_e32 v72, v68, v72
	v_mul_f32_e32 v73, v64, v73
	v_mul_f32_e32 v74, v69, v74
	v_fma_f32 v72, v68, v72, v68
	v_fma_f32 v73, v64, v73, v64
	v_fma_f32 v74, v69, v74, v69
	v_mul_f32_e32 v72, 0xbfcc422a, v72
	v_mul_f32_e32 v73, 0xbfcc422a, v73
	v_mul_f32_e32 v74, 0xbfcc422a, v74
	v_mul_f32_e32 v72, 0x3fb8aa3b, v72
	v_mul_f32_e32 v73, 0x3fb8aa3b, v73
	v_mul_f32_e32 v74, 0x3fb8aa3b, v74
	v_exp_f32_e32 v72, v72
	v_exp_f32_e32 v73, v73
	v_exp_f32_e32 v74, v74
	v_mul_f32_e32 v75, 0x3d372713, v65
	v_add_f32_e32 v72, 1.0, v72
	v_add_f32_e32 v73, 1.0, v73
	v_add_f32_e32 v74, 1.0, v74
	v_rcp_f32_e32 v72, v72
	v_rcp_f32_e32 v73, v73
	v_rcp_f32_e32 v74, v74
	v_mul_f32_e32 v75, v65, v75
	v_fma_f32 v75, v65, v75, v65
	v_lshlrev_b32_e32 v78, 16, v99
	v_and_b32_e32 v79, 0xffff0000, v99
	v_mul_f32_e32 v75, 0xbfcc422a, v75
	v_pk_fma_f32 v[66:67], v[106:107], v[78:79], v[66:67]
	v_mul_f32_e32 v75, 0x3fb8aa3b, v75
	v_exp_f32_e32 v75, v75
	v_mul_f32_e32 v68, v68, v72
	v_mul_f32_e32 v72, v64, v73
	v_mul_f32_e32 v64, v69, v74
	v_mul_f32_e32 v73, 0x3d372713, v70
	v_mul_f32_e32 v74, 0x3d372713, v66
	v_mul_f32_e32 v73, v70, v73
	v_mul_f32_e32 v74, v66, v74
	v_fma_f32 v73, v70, v73, v70
	v_fma_f32 v74, v66, v74, v66
	v_mul_f32_e32 v73, 0xbfcc422a, v73
	v_mul_f32_e32 v74, 0xbfcc422a, v74
	v_add_f32_e32 v69, 1.0, v75
	v_mul_f32_e32 v73, 0x3fb8aa3b, v73
	v_mul_f32_e32 v74, 0x3fb8aa3b, v74
	v_rcp_f32_e32 v69, v69
	v_exp_f32_e32 v73, v73
	v_exp_f32_e32 v74, v74
	v_mul_f32_e32 v75, 0x3d372713, v67
	v_mul_f32_e32 v69, v65, v69
	v_add_f32_e32 v65, 1.0, v73
	v_add_f32_e32 v73, 1.0, v74
	v_mul_f32_e32 v74, 0x3d372713, v71
	v_mul_f32_e32 v74, v71, v74
	v_fma_f32 v74, v71, v74, v71
	v_mul_f32_e32 v74, 0xbfcc422a, v74
	v_mul_f32_e32 v74, 0x3fb8aa3b, v74
	v_exp_f32_e32 v74, v74
	v_mul_f32_e32 v75, v67, v75
	v_fma_f32 v75, v67, v75, v67
	v_mul_f32_e32 v75, 0xbfcc422a, v75
	v_mul_f32_e32 v75, 0x3fb8aa3b, v75
	v_add_f32_e32 v74, 1.0, v74
	v_rcp_f32_e32 v65, v65
	v_exp_f32_e32 v75, v75
	v_rcp_f32_e32 v73, v73
	v_rcp_f32_e32 v74, v74
	v_mul_f32_e32 v65, v70, v65
	v_add_f32_e32 v75, 1.0, v75
	v_mul_f32_e32 v70, v66, v73
	v_mul_f32_e32 v66, v71, v74
	v_cvt_pk_bf16_f32 v64, v68, v64
	v_lshl_add_u32 v68, v120, 4, v214
	v_rcp_f32_e32 v75, v75
	v_cvt_pk_bf16_f32 v65, v65, v66
	v_cvt_pk_bf16_f32 v66, v72, v69
	v_ashrrev_i32_e32 v69, 31, v68
	v_lshlrev_b64 v[68:69], 10, v[68:69]
	v_lshl_add_u64 v[68:69], v[174:175], 0, v[68:69]
	v_lshl_add_u64 v[68:69], s[56:57], 1, v[68:69]
	v_mov_b32_e32 v183, v153
	v_mul_f32_e32 v67, v67, v75
	v_lshl_add_u64 v[68:69], v[68:69], 0, v[182:183]
	v_cvt_pk_bf16_f32 v67, v70, v67
	global_store_dwordx4 v[68:69], v[64:67], off

; __device__ __forceinline__ float bf_lo(unsigned w) { return __uint_as_float(w << 16); }
; __device__ __forceinline__ float bf_hi(unsigned w) { return __uint_as_float(w & 0xffff0000u); }
; __device__ __forceinline__ u32x4 pack8(const f32x4 a, const f32x4 b) { u32x4 w; w.x = cvt_pk_bf16(a[0], a[1]); w.y = cvt_pk_bf16(a[2], a[3]); w.z = cvt_pk_bf16(b[0], b[1]); w.w = cvt_pk_bf16(b[2], b[3]); return w; }
;     __device__ __forceinline__ void operator()(EPI_ARGS) const {
;     ...
;                 for (int m = 0; m < 4; ++m) { const int j = row0 + ai * HALF + m * 16;
;                     uw[m] = (j < NJ) ? *(const u32x4*)(AB + ((size_t)((g >> 1) * NJP + j) * ABP + (g & 1) * 384 + n)) : (u32x4){0u, 0u, 0u, 0u}; }
; #pragma unroll
;                 for (int m = 0; m < 4; ++m) { const int j = row0 + ai * HALF + m * 16;
;                     if (j < NJ) {
;                         const u32x4 w = uw[m];
;                         f32x4 u0 = {bf_lo(w.x), bf_hi(w.x), bf_lo(w.y), bf_hi(w.y)}, u1 = {bf_lo(w.z), bf_hi(w.z), bf_lo(w.w), bf_hi(w.w)};
;                         f32x4 y0 = acc[ai][bj][m][0] + d0 * u0, y1 = acc[ai][bj][m][1] + d1 * u1;
; #pragma unroll
;                         for (int e = 0; e < 4; ++e) {
;                             { const float y = y0[e], q = 1.5957691216f * (y + 0.044715f * y * y * y); y0[e] = y * __builtin_amdgcn_rcpf(1.0f + __expf(-q)); }
;                             { const float y = y1[e], q = 1.5957691216f * (y + 0.044715f * y * y * y); y1[e] = y * __builtin_amdgcn_rcpf(1.0f + __expf(-q)); }
;                         }
;                         *(u32x4*)(Z + (size_t)(j * TS + t) * WA + g * 16 + c) = pack8(y0, y1);
.LBB0_403:
	v_lshlrev_b32_e32 v48, 16, v76
	v_and_b32_e32 v49, 0xffff0000, v76
	v_lshlrev_b32_e32 v52, 16, v78
	v_and_b32_e32 v53, 0xffff0000, v78
	v_lshlrev_b32_e32 v50, 16, v77
	v_and_b32_e32 v51, 0xffff0000, v77
	v_pk_fma_f32 v[44:45], v[68:69], v[48:49], v[44:45]
	v_pk_fma_f32 v[40:41], v[64:65], v[52:53], v[40:41]
	v_mul_f32_e32 v48, 0x3d372713, v44
	v_pk_fma_f32 v[46:47], v[70:71], v[50:51], v[46:47]
	v_mul_f32_e32 v49, 0x3d372713, v40
	v_mul_f32_e32 v50, 0x3d372713, v45
	v_mul_f32_e32 v48, v44, v48
	v_mul_f32_e32 v49, v40, v49
	v_mul_f32_e32 v50, v45, v50
	v_fma_f32 v48, v44, v48, v44
	v_fma_f32 v49, v40, v49, v40
	v_fma_f32 v50, v45, v50, v45
	v_mul_f32_e32 v48, 0xbfcc422a, v48
	v_mul_f32_e32 v49, 0xbfcc422a, v49
	v_mul_f32_e32 v50, 0xbfcc422a, v50
	v_mul_f32_e32 v48, 0x3fb8aa3b, v48
	v_mul_f32_e32 v49, 0x3fb8aa3b, v49
	v_mul_f32_e32 v50, 0x3fb8aa3b, v50
	v_exp_f32_e32 v48, v48
	v_exp_f32_e32 v49, v49
	v_exp_f32_e32 v50, v50
	v_mul_f32_e32 v51, 0x3d372713, v41
	v_add_f32_e32 v48, 1.0, v48
	v_add_f32_e32 v49, 1.0, v49
	v_add_f32_e32 v50, 1.0, v50
	v_rcp_f32_e32 v48, v48
	v_rcp_f32_e32 v49, v49
	v_rcp_f32_e32 v50, v50
	v_mul_f32_e32 v51, v41, v51
	v_fma_f32 v51, v41, v51, v41
	v_lshlrev_b32_e32 v54, 16, v79
	v_and_b32_e32 v55, 0xffff0000, v79
	v_mul_f32_e32 v51, 0xbfcc422a, v51
	v_pk_fma_f32 v[42:43], v[66:67], v[54:55], v[42:43]
	v_mul_f32_e32 v51, 0x3fb8aa3b, v51
	v_exp_f32_e32 v51, v51
	v_mul_f32_e32 v44, v44, v48
	v_mul_f32_e32 v48, v40, v49
	v_mul_f32_e32 v40, v45, v50
	v_mul_f32_e32 v49, 0x3d372713, v46
	v_mul_f32_e32 v50, 0x3d372713, v42
	v_mul_f32_e32 v49, v46, v49
	v_mul_f32_e32 v50, v42, v50
	v_fma_f32 v49, v46, v49, v46
	v_fma_f32 v50, v42, v50, v42
	v_mul_f32_e32 v49, 0xbfcc422a, v49
	v_mul_f32_e32 v50, 0xbfcc422a, v50
	v_add_f32_e32 v45, 1.0, v51
	v_mul_f32_e32 v49, 0x3fb8aa3b, v49
	v_mul_f32_e32 v50, 0x3fb8aa3b, v50
	v_rcp_f32_e32 v45, v45
	v_exp_f32_e32 v49, v49
	v_exp_f32_e32 v50, v50
	v_mul_f32_e32 v51, 0x3d372713, v43
	v_mul_f32_e32 v45, v41, v45
	v_add_f32_e32 v41, 1.0, v49
	v_add_f32_e32 v49, 1.0, v50
	v_mul_f32_e32 v50, 0x3d372713, v47
	v_mul_f32_e32 v50, v47, v50
	v_fma_f32 v50, v47, v50, v47
	v_mul_f32_e32 v50, 0xbfcc422a, v50
	v_mul_f32_e32 v50, 0x3fb8aa3b, v50
	v_exp_f32_e32 v50, v50
	v_mul_f32_e32 v51, v43, v51
	v_fma_f32 v51, v43, v51, v43
	v_mul_f32_e32 v51, 0xbfcc422a, v51
	v_mul_f32_e32 v51, 0x3fb8aa3b, v51
	v_add_f32_e32 v50, 1.0, v50
	v_rcp_f32_e32 v41, v41
	v_exp_f32_e32 v51, v51
	v_rcp_f32_e32 v49, v49
	v_rcp_f32_e32 v50, v50
	v_mul_f32_e32 v41, v46, v41
	v_add_f32_e32 v51, 1.0, v51
	v_mul_f32_e32 v46, v42, v49
	v_mul_f32_e32 v42, v47, v50
	v_cvt_pk_bf16_f32 v40, v44, v40
	v_lshl_add_u32 v44, v192, 4, v88
	v_rcp_f32_e32 v51, v51
	v_cvt_pk_bf16_f32 v41, v41, v42
	v_cvt_pk_bf16_f32 v42, v48, v45
	v_ashrrev_i32_e32 v45, 31, v44
	v_lshlrev_b64 v[44:45], 10, v[44:45]
	v_lshl_add_u64 v[44:45], v[174:175], 0, v[44:45]
	v_lshl_add_u64 v[44:45], s[56:57], 1, v[44:45]
	v_mov_b32_e32 v183, v153
	v_mul_f32_e32 v43, v43, v51
	v_lshl_add_u64 v[44:45], v[44:45], 0, v[182:183]
	v_cvt_pk_bf16_f32 v43, v46, v43
	global_store_dwordx4 v[44:45], v[40:43], off
	s_or_b64 exec, exec, s[12:13]
	s_and_saveexec_b64 s[8:9], vcc
	s_cbranch_execnz .LBB0_411
	s_branch .LBB0_412

; __device__ __forceinline__ float bf_lo(unsigned w) { return __uint_as_float(w << 16); }
; __device__ __forceinline__ float bf_hi(unsigned w) { return __uint_as_float(w & 0xffff0000u); }
; __device__ __forceinline__ u32x4 pack8(const f32x4 a, const f32x4 b) { u32x4 w; w.x = cvt_pk_bf16(a[0], a[1]); w.y = cvt_pk_bf16(a[2], a[3]); w.z = cvt_pk_bf16(b[0], b[1]); w.w = cvt_pk_bf16(b[2], b[3]); return w; }
;     __device__ __forceinline__ void operator()(EPI_ARGS) const {
;     ...
;                 for (int m = 0; m < 4; ++m) { const int j = row0 + ai * HALF + m * 16;
;                     uw[m] = (j < NJ) ? *(const u32x4*)(AB + ((size_t)((g >> 1) * NJP + j) * ABP + (g & 1) * 384 + n)) : (u32x4){0u, 0u, 0u, 0u}; }
; #pragma unroll
;                 for (int m = 0; m < 4; ++m) { const int j = row0 + ai * HALF + m * 16;
;                     if (j < NJ) {
;                         const u32x4 w = uw[m];
;                         f32x4 u0 = {bf_lo(w.x), bf_hi(w.x), bf_lo(w.y), bf_hi(w.y)}, u1 = {bf_lo(w.z), bf_hi(w.z), bf_lo(w.w), bf_hi(w.w)};
;                         f32x4 y0 = acc[ai][bj][m][0] + d0 * u0, y1 = acc[ai][bj][m][1] + d1 * u1;
; #pragma unroll
;                         for (int e = 0; e < 4; ++e) {
;                             { const float y = y0[e], q = 1.5957691216f * (y + 0.044715f * y * y * y); y0[e] = y * __builtin_amdgcn_rcpf(1.0f + __expf(-q)); }
;                             { const float y = y1[e], q = 1.5957691216f * (y + 0.044715f * y * y * y); y1[e] = y * __builtin_amdgcn_rcpf(1.0f + __expf(-q)); }
;                         }
;                         *(u32x4*)(Z + (size_t)(j * TS + t) * WA + g * 16 + c) = pack8(y0, y1);
.LBB0_407:
	v_lshlrev_b32_e32 v80, 16, v100
	v_and_b32_e32 v81, 0xffff0000, v100
	v_lshlrev_b32_e32 v84, 16, v102
	v_and_b32_e32 v85, 0xffff0000, v102
	v_lshlrev_b32_e32 v82, 16, v101
	v_and_b32_e32 v83, 0xffff0000, v101
	v_pk_fma_f32 v[76:77], v[108:109], v[80:81], v[76:77]
	v_pk_fma_f32 v[72:73], v[104:105], v[84:85], v[72:73]
	v_mul_f32_e32 v80, 0x3d372713, v76
	v_pk_fma_f32 v[78:79], v[110:111], v[82:83], v[78:79]
	v_mul_f32_e32 v81, 0x3d372713, v72
	v_mul_f32_e32 v82, 0x3d372713, v77
	v_mul_f32_e32 v80, v76, v80
	v_mul_f32_e32 v81, v72, v81
	v_mul_f32_e32 v82, v77, v82
	v_fma_f32 v80, v76, v80, v76
	v_fma_f32 v81, v72, v81, v72
	v_fma_f32 v82, v77, v82, v77
	v_mul_f32_e32 v80, 0xbfcc422a, v80
	v_mul_f32_e32 v81, 0xbfcc422a, v81
	v_mul_f32_e32 v82, 0xbfcc422a, v82
	v_mul_f32_e32 v80, 0x3fb8aa3b, v80
	v_mul_f32_e32 v81, 0x3fb8aa3b, v81
	v_mul_f32_e32 v82, 0x3fb8aa3b, v82
	v_exp_f32_e32 v80, v80
	v_exp_f32_e32 v81, v81
	v_exp_f32_e32 v82, v82
	v_mul_f32_e32 v83, 0x3d372713, v73
	v_add_f32_e32 v80, 1.0, v80
	v_add_f32_e32 v81, 1.0, v81
	v_add_f32_e32 v82, 1.0, v82
	v_rcp_f32_e32 v80, v80
	v_rcp_f32_e32 v81, v81
	v_rcp_f32_e32 v82, v82
	v_mul_f32_e32 v83, v73, v83
	v_fma_f32 v83, v73, v83, v73
	v_lshlrev_b32_e32 v86, 16, v103
	v_and_b32_e32 v87, 0xffff0000, v103
	v_mul_f32_e32 v83, 0xbfcc422a, v83
	v_pk_fma_f32 v[74:75], v[106:107], v[86:87], v[74:75]
	v_mul_f32_e32 v83, 0x3fb8aa3b, v83
	v_exp_f32_e32 v83, v83
	v_mul_f32_e32 v76, v76, v80
	v_mul_f32_e32 v80, v72, v81
	v_mul_f32_e32 v72, v77, v82
	v_mul_f32_e32 v81, 0x3d372713, v78
	v_mul_f32_e32 v82, 0x3d372713, v74
	v_mul_f32_e32 v81, v78, v81
	v_mul_f32_e32 v82, v74, v82
	v_fma_f32 v81, v78, v81, v78
	v_fma_f32 v82, v74, v82, v74
	v_mul_f32_e32 v81, 0xbfcc422a, v81
	v_mul_f32_e32 v82, 0xbfcc422a, v82
	v_add_f32_e32 v77, 1.0, v83
	v_mul_f32_e32 v81, 0x3fb8aa3b, v81
	v_mul_f32_e32 v82, 0x3fb8aa3b, v82
	v_rcp_f32_e32 v77, v77
	v_exp_f32_e32 v81, v81
	v_exp_f32_e32 v82, v82
	v_mul_f32_e32 v83, 0x3d372713, v75
	v_mul_f32_e32 v77, v73, v77
	v_add_f32_e32 v73, 1.0, v81
	v_add_f32_e32 v81, 1.0, v82
	v_mul_f32_e32 v82, 0x3d372713, v79
	v_mul_f32_e32 v82, v79, v82
	v_fma_f32 v82, v79, v82, v79
	v_mul_f32_e32 v82, 0xbfcc422a, v82
	v_mul_f32_e32 v82, 0x3fb8aa3b, v82
	v_exp_f32_e32 v82, v82
	v_mul_f32_e32 v83, v75, v83
	v_fma_f32 v83, v75, v83, v75
	v_mul_f32_e32 v83, 0xbfcc422a, v83
	v_mul_f32_e32 v83, 0x3fb8aa3b, v83
	v_add_f32_e32 v82, 1.0, v82
	v_rcp_f32_e32 v73, v73
	v_exp_f32_e32 v83, v83
	v_rcp_f32_e32 v81, v81
	v_rcp_f32_e32 v82, v82
	v_mul_f32_e32 v73, v78, v73
	v_add_f32_e32 v83, 1.0, v83
	v_mul_f32_e32 v78, v74, v81
	v_mul_f32_e32 v74, v79, v82
	v_cvt_pk_bf16_f32 v72, v76, v72
	v_lshl_add_u32 v76, v121, 4, v214
	v_rcp_f32_e32 v83, v83
	v_cvt_pk_bf16_f32 v73, v73, v74
	v_cvt_pk_bf16_f32 v74, v80, v77
	v_ashrrev_i32_e32 v77, 31, v76
	v_lshlrev_b64 v[76:77], 10, v[76:77]
	v_lshl_add_u64 v[76:77], v[174:175], 0, v[76:77]
	v_lshl_add_u64 v[76:77], s[56:57], 1, v[76:77]
	v_mov_b32_e32 v183, v153
	v_mul_f32_e32 v75, v75, v83
	v_lshl_add_u64 v[76:77], v[76:77], 0, v[182:183]
	v_cvt_pk_bf16_f32 v75, v78, v75
	global_store_dwordx4 v[76:77], v[72:75], off
	s_or_b64 exec, exec, s[60:61]
	s_and_saveexec_b64 s[60:61], s[6:7]
	s_cbranch_execnz .LBB0_391
	s_branch .LBB0_392

; __device__ __forceinline__ float bf_lo(unsigned w) { return __uint_as_float(w << 16); }
; __device__ __forceinline__ float bf_hi(unsigned w) { return __uint_as_float(w & 0xffff0000u); }
; __device__ __forceinline__ u32x4 pack8(const f32x4 a, const f32x4 b) { u32x4 w; w.x = cvt_pk_bf16(a[0], a[1]); w.y = cvt_pk_bf16(a[2], a[3]); w.z = cvt_pk_bf16(b[0], b[1]); w.w = cvt_pk_bf16(b[2], b[3]); return w; }
;     __device__ __forceinline__ void operator()(EPI_ARGS) const {
;     ...
;                 for (int m = 0; m < 4; ++m) { const int j = row0 + ai * HALF + m * 16;
;                     uw[m] = (j < NJ) ? *(const u32x4*)(AB + ((size_t)((g >> 1) * NJP + j) * ABP + (g & 1) * 384 + n)) : (u32x4){0u, 0u, 0u, 0u}; }
; #pragma unroll
;                 for (int m = 0; m < 4; ++m) { const int j = row0 + ai * HALF + m * 16;
;                     if (j < NJ) {
;                         const u32x4 w = uw[m];
;                         f32x4 u0 = {bf_lo(w.x), bf_hi(w.x), bf_lo(w.y), bf_hi(w.y)}, u1 = {bf_lo(w.z), bf_hi(w.z), bf_lo(w.w), bf_hi(w.w)};
;                         f32x4 y0 = acc[ai][bj][m][0] + d0 * u0, y1 = acc[ai][bj][m][1] + d1 * u1;
; #pragma unroll
;                         for (int e = 0; e < 4; ++e) {
;                             { const float y = y0[e], q = 1.5957691216f * (y + 0.044715f * y * y * y); y0[e] = y * __builtin_amdgcn_rcpf(1.0f + __expf(-q)); }
;                             { const float y = y1[e], q = 1.5957691216f * (y + 0.044715f * y * y * y); y1[e] = y * __builtin_amdgcn_rcpf(1.0f + __expf(-q)); }
;                         }
;                         *(u32x4*)(Z + (size_t)(j * TS + t) * WA + g * 16 + c) = pack8(y0, y1);
.LBB0_409:
	v_lshlrev_b32_e32 v56, 16, v80
	v_and_b32_e32 v57, 0xffff0000, v80
	v_lshlrev_b32_e32 v60, 16, v82
	v_and_b32_e32 v61, 0xffff0000, v82
	v_lshlrev_b32_e32 v58, 16, v81
	v_and_b32_e32 v59, 0xffff0000, v81
	v_pk_fma_f32 v[52:53], v[68:69], v[56:57], v[52:53]
	v_pk_fma_f32 v[48:49], v[64:65], v[60:61], v[48:49]
	v_mul_f32_e32 v56, 0x3d372713, v52
	v_pk_fma_f32 v[54:55], v[70:71], v[58:59], v[54:55]
	v_mul_f32_e32 v57, 0x3d372713, v48
	v_mul_f32_e32 v58, 0x3d372713, v53
	v_mul_f32_e32 v56, v52, v56
	v_mul_f32_e32 v57, v48, v57
	v_mul_f32_e32 v58, v53, v58
	v_fma_f32 v56, v52, v56, v52
	v_fma_f32 v57, v48, v57, v48
	v_fma_f32 v58, v53, v58, v53
	v_mul_f32_e32 v56, 0xbfcc422a, v56
	v_mul_f32_e32 v57, 0xbfcc422a, v57
	v_mul_f32_e32 v58, 0xbfcc422a, v58
	v_mul_f32_e32 v56, 0x3fb8aa3b, v56
	v_mul_f32_e32 v57, 0x3fb8aa3b, v57
	v_mul_f32_e32 v58, 0x3fb8aa3b, v58
	v_exp_f32_e32 v56, v56
	v_exp_f32_e32 v57, v57
	v_exp_f32_e32 v58, v58
	v_mul_f32_e32 v59, 0x3d372713, v49
	v_add_f32_e32 v56, 1.0, v56
	v_add_f32_e32 v57, 1.0, v57
	v_add_f32_e32 v58, 1.0, v58
	v_rcp_f32_e32 v56, v56
	v_rcp_f32_e32 v57, v57
	v_rcp_f32_e32 v58, v58
	v_mul_f32_e32 v59, v49, v59
	v_fma_f32 v59, v49, v59, v49
	v_lshlrev_b32_e32 v62, 16, v83
	v_and_b32_e32 v63, 0xffff0000, v83
	v_mul_f32_e32 v59, 0xbfcc422a, v59
	v_pk_fma_f32 v[50:51], v[66:67], v[62:63], v[50:51]
	v_mul_f32_e32 v59, 0x3fb8aa3b, v59
	v_exp_f32_e32 v59, v59
	v_mul_f32_e32 v52, v52, v56
	v_mul_f32_e32 v56, v48, v57
	v_mul_f32_e32 v48, v53, v58
	v_mul_f32_e32 v57, 0x3d372713, v54
	v_mul_f32_e32 v58, 0x3d372713, v50
	v_mul_f32_e32 v57, v54, v57
	v_mul_f32_e32 v58, v50, v58
	v_fma_f32 v57, v54, v57, v54
	v_fma_f32 v58, v50, v58, v50
	v_mul_f32_e32 v57, 0xbfcc422a, v57
	v_mul_f32_e32 v58, 0xbfcc422a, v58
	v_add_f32_e32 v53, 1.0, v59
	v_mul_f32_e32 v57, 0x3fb8aa3b, v57
	v_mul_f32_e32 v58, 0x3fb8aa3b, v58
	v_rcp_f32_e32 v53, v53
	v_exp_f32_e32 v57, v57
	v_exp_f32_e32 v58, v58
	v_mul_f32_e32 v59, 0x3d372713, v51
	v_mul_f32_e32 v53, v49, v53
	v_add_f32_e32 v49, 1.0, v57
	v_add_f32_e32 v57, 1.0, v58
	v_mul_f32_e32 v58, 0x3d372713, v55
	v_mul_f32_e32 v58, v55, v58
	v_fma_f32 v58, v55, v58, v55
	v_mul_f32_e32 v58, 0xbfcc422a, v58
	v_mul_f32_e32 v58, 0x3fb8aa3b, v58
	v_exp_f32_e32 v58, v58
	v_mul_f32_e32 v59, v51, v59
	v_fma_f32 v59, v51, v59, v51
	v_mul_f32_e32 v59, 0xbfcc422a, v59
	v_mul_f32_e32 v59, 0x3fb8aa3b, v59
	v_add_f32_e32 v58, 1.0, v58
	v_rcp_f32_e32 v49, v49
	v_exp_f32_e32 v59, v59
	v_rcp_f32_e32 v57, v57
	v_rcp_f32_e32 v58, v58
	v_mul_f32_e32 v49, v54, v49
	v_add_f32_e32 v59, 1.0, v59
	v_mul_f32_e32 v54, v50, v57
	v_mul_f32_e32 v50, v55, v58
	v_cvt_pk_bf16_f32 v48, v52, v48
	v_lshl_add_u32 v52, v193, 4, v88
	v_rcp_f32_e32 v59, v59
	v_cvt_pk_bf16_f32 v49, v49, v50
	v_cvt_pk_bf16_f32 v50, v56, v53
	v_ashrrev_i32_e32 v53, 31, v52
	v_lshlrev_b64 v[52:53], 10, v[52:53]
	v_lshl_add_u64 v[52:53], v[174:175], 0, v[52:53]
	v_lshl_add_u64 v[52:53], s[56:57], 1, v[52:53]
	v_mov_b32_e32 v183, v153
	v_mul_f32_e32 v51, v51, v59
	v_lshl_add_u64 v[52:53], v[52:53], 0, v[182:183]
	v_cvt_pk_bf16_f32 v51, v54, v51
	global_store_dwordx4 v[52:53], v[48:51], off
	s_or_b64 exec, exec, s[16:17]
	s_and_saveexec_b64 s[12:13], s[8:9]
	s_cbranch_execnz .LBB0_403

; __device__ __forceinline__ float bf_lo(unsigned w) { return __uint_as_float(w << 16); }
; __device__ __forceinline__ float bf_hi(unsigned w) { return __uint_as_float(w & 0xffff0000u); }
; __device__ __forceinline__ u32x4 pack8(const f32x4 a, const f32x4 b) { u32x4 w; w.x = cvt_pk_bf16(a[0], a[1]); w.y = cvt_pk_bf16(a[2], a[3]); w.z = cvt_pk_bf16(b[0], b[1]); w.w = cvt_pk_bf16(b[2], b[3]); return w; }
;     __device__ __forceinline__ void operator()(EPI_ARGS) const {
;     ...
;                 for (int m = 0; m < 4; ++m) { const int j = row0 + ai * HALF + m * 16;
;                     uw[m] = (j < NJ) ? *(const u32x4*)(AB + ((size_t)((g >> 1) * NJP + j) * ABP + (g & 1) * 384 + n)) : (u32x4){0u, 0u, 0u, 0u}; }
; #pragma unroll
;                 for (int m = 0; m < 4; ++m) { const int j = row0 + ai * HALF + m * 16;
;                     if (j < NJ) {
;                         const u32x4 w = uw[m];
;                         f32x4 u0 = {bf_lo(w.x), bf_hi(w.x), bf_lo(w.y), bf_hi(w.y)}, u1 = {bf_lo(w.z), bf_hi(w.z), bf_lo(w.w), bf_hi(w.w)};
;                         f32x4 y0 = acc[ai][bj][m][0] + d0 * u0, y1 = acc[ai][bj][m][1] + d1 * u1;
; #pragma unroll
;                         for (int e = 0; e < 4; ++e) {
;                             { const float y = y0[e], q = 1.5957691216f * (y + 0.044715f * y * y * y); y0[e] = y * __builtin_amdgcn_rcpf(1.0f + __expf(-q)); }
;                             { const float y = y1[e], q = 1.5957691216f * (y + 0.044715f * y * y * y); y1[e] = y * __builtin_amdgcn_rcpf(1.0f + __expf(-q)); }
;                         }
;                         *(u32x4*)(Z + (size_t)(j * TS + t) * WA + g * 16 + c) = pack8(y0, y1);
.LBB0_411:
	v_lshlrev_b32_e32 v40, 16, v72
	v_and_b32_e32 v41, 0xffff0000, v72
	v_lshlrev_b32_e32 v44, 16, v74
	v_and_b32_e32 v45, 0xffff0000, v74
	v_lshlrev_b32_e32 v42, 16, v73
	v_and_b32_e32 v43, 0xffff0000, v73
	v_pk_fma_f32 v[36:37], v[68:69], v[40:41], v[36:37]
	v_pk_fma_f32 v[32:33], v[64:65], v[44:45], v[32:33]
	v_mul_f32_e32 v40, 0x3d372713, v36
	v_pk_fma_f32 v[38:39], v[70:71], v[42:43], v[38:39]
	v_mul_f32_e32 v41, 0x3d372713, v32
	v_mul_f32_e32 v42, 0x3d372713, v37
	v_mul_f32_e32 v40, v36, v40
	v_mul_f32_e32 v41, v32, v41
	v_mul_f32_e32 v42, v37, v42
	v_fma_f32 v40, v36, v40, v36
	v_fma_f32 v41, v32, v41, v32
	v_fma_f32 v42, v37, v42, v37
	v_mul_f32_e32 v40, 0xbfcc422a, v40
	v_mul_f32_e32 v41, 0xbfcc422a, v41
	v_mul_f32_e32 v42, 0xbfcc422a, v42
	v_mul_f32_e32 v40, 0x3fb8aa3b, v40
	v_mul_f32_e32 v41, 0x3fb8aa3b, v41
	v_mul_f32_e32 v42, 0x3fb8aa3b, v42
	v_exp_f32_e32 v40, v40
	v_exp_f32_e32 v41, v41
	v_exp_f32_e32 v42, v42
	v_mul_f32_e32 v43, 0x3d372713, v33
	v_add_f32_e32 v40, 1.0, v40
	v_add_f32_e32 v41, 1.0, v41
	v_add_f32_e32 v42, 1.0, v42
	v_rcp_f32_e32 v40, v40
	v_rcp_f32_e32 v41, v41
	v_rcp_f32_e32 v42, v42
	v_mul_f32_e32 v43, v33, v43
	v_fma_f32 v43, v33, v43, v33
	v_lshlrev_b32_e32 v46, 16, v75
	v_and_b32_e32 v47, 0xffff0000, v75
	v_mul_f32_e32 v43, 0xbfcc422a, v43
	v_pk_fma_f32 v[34:35], v[66:67], v[46:47], v[34:35]
	v_mul_f32_e32 v43, 0x3fb8aa3b, v43
	v_exp_f32_e32 v43, v43
	v_mul_f32_e32 v36, v36, v40
	v_mul_f32_e32 v40, v32, v41
	v_mul_f32_e32 v32, v37, v42
	v_mul_f32_e32 v41, 0x3d372713, v38
	v_mul_f32_e32 v42, 0x3d372713, v34
	v_mul_f32_e32 v41, v38, v41
	v_mul_f32_e32 v42, v34, v42
	v_fma_f32 v41, v38, v41, v38
	v_fma_f32 v42, v34, v42, v34
	v_mul_f32_e32 v41, 0xbfcc422a, v41
	v_mul_f32_e32 v42, 0xbfcc422a, v42
	v_add_f32_e32 v37, 1.0, v43
	v_mul_f32_e32 v41, 0x3fb8aa3b, v41
	v_mul_f32_e32 v42, 0x3fb8aa3b, v42
	v_rcp_f32_e32 v37, v37
	v_exp_f32_e32 v41, v41
	v_exp_f32_e32 v42, v42
	v_mul_f32_e32 v43, 0x3d372713, v35
	v_mul_f32_e32 v37, v33, v37
	v_add_f32_e32 v33, 1.0, v41
	v_add_f32_e32 v41, 1.0, v42
	v_mul_f32_e32 v42, 0x3d372713, v39
	v_mul_f32_e32 v42, v39, v42
	v_fma_f32 v42, v39, v42, v39
	v_mul_f32_e32 v42, 0xbfcc422a, v42
	v_mul_f32_e32 v42, 0x3fb8aa3b, v42
	v_exp_f32_e32 v42, v42
	v_mul_f32_e32 v43, v35, v43
	v_fma_f32 v43, v35, v43, v35
	v_mul_f32_e32 v43, 0xbfcc422a, v43
	v_mul_f32_e32 v43, 0x3fb8aa3b, v43
	v_add_f32_e32 v42, 1.0, v42
	v_rcp_f32_e32 v33, v33
	v_exp_f32_e32 v43, v43
	v_rcp_f32_e32 v41, v41
	v_rcp_f32_e32 v42, v42
	v_mul_f32_e32 v33, v38, v33
	v_add_f32_e32 v43, 1.0, v43
	v_mul_f32_e32 v38, v34, v41
	v_mul_f32_e32 v34, v39, v42
	v_cvt_pk_bf16_f32 v32, v36, v32
	v_lshl_add_u32 v36, v187, 4, v88
	v_rcp_f32_e32 v43, v43
	v_cvt_pk_bf16_f32 v33, v33, v34
	v_cvt_pk_bf16_f32 v34, v40, v37
	v_ashrrev_i32_e32 v37, 31, v36
	v_lshlrev_b64 v[36:37], 10, v[36:37]
	v_lshl_add_u64 v[36:37], v[174:175], 0, v[36:37]
	v_lshl_add_u64 v[36:37], s[56:57], 1, v[36:37]
	v_mov_b32_e32 v183, v153
	v_mul_f32_e32 v35, v35, v43
	v_lshl_add_u64 v[36:37], v[36:37], 0, v[182:183]
	v_cvt_pk_bf16_f32 v35, v38, v35
	global_store_dwordx4 v[36:37], v[32:35], off

; __device__ __forceinline__ float bf_lo(unsigned w) { return __uint_as_float(w << 16); }
; __device__ __forceinline__ float bf_hi(unsigned w) { return __uint_as_float(w & 0xffff0000u); }
; __device__ __forceinline__ u32x4 pack8(const f32x4 a, const f32x4 b) { u32x4 w; w.x = cvt_pk_bf16(a[0], a[1]); w.y = cvt_pk_bf16(a[2], a[3]); w.z = cvt_pk_bf16(b[0], b[1]); w.w = cvt_pk_bf16(b[2], b[3]); return w; }
;     __device__ __forceinline__ void operator()(EPI_ARGS) const {
;     ...
;                 for (int m = 0; m < 4; ++m) { const int j = row0 + ai * HALF + m * 16;
;                     uw[m] = (j < NJ) ? *(const u32x4*)(AB + ((size_t)((g >> 1) * NJP + j) * ABP + (g & 1) * 384 + n)) : (u32x4){0u, 0u, 0u, 0u}; }
; #pragma unroll
;                 for (int m = 0; m < 4; ++m) { const int j = row0 + ai * HALF + m * 16;
;                     if (j < NJ) {
;                         const u32x4 w = uw[m];
;                         f32x4 u0 = {bf_lo(w.x), bf_hi(w.x), bf_lo(w.y), bf_hi(w.y)}, u1 = {bf_lo(w.z), bf_hi(w.z), bf_lo(w.w), bf_hi(w.w)};
;                         f32x4 y0 = acc[ai][bj][m][0] + d0 * u0, y1 = acc[ai][bj][m][1] + d1 * u1;
; #pragma unroll
;                         for (int e = 0; e < 4; ++e) {
;                             { const float y = y0[e], q = 1.5957691216f * (y + 0.044715f * y * y * y); y0[e] = y * __builtin_amdgcn_rcpf(1.0f + __expf(-q)); }
;                             { const float y = y1[e], q = 1.5957691216f * (y + 0.044715f * y * y * y); y1[e] = y * __builtin_amdgcn_rcpf(1.0f + __expf(-q)); }
;                         }
;                         *(u32x4*)(Z + (size_t)(j * TS + t) * WA + g * 16 + c) = pack8(y0, y1);
.LBB0_421:
	v_lshlrev_b32_e32 v24, 16, v40
	v_and_b32_e32 v25, 0xffff0000, v40
	v_lshlrev_b32_e32 v28, 16, v42
	v_and_b32_e32 v29, 0xffff0000, v42
	v_lshlrev_b32_e32 v26, 16, v41
	v_and_b32_e32 v27, 0xffff0000, v41
	v_pk_fma_f32 v[20:21], v[68:69], v[24:25], v[20:21]
	v_pk_fma_f32 v[16:17], v[64:65], v[28:29], v[16:17]
	v_mul_f32_e32 v24, 0x3d372713, v20
	v_pk_fma_f32 v[22:23], v[70:71], v[26:27], v[22:23]
	v_mul_f32_e32 v25, 0x3d372713, v16
	v_mul_f32_e32 v26, 0x3d372713, v21
	v_mul_f32_e32 v24, v20, v24
	v_mul_f32_e32 v25, v16, v25
	v_mul_f32_e32 v26, v21, v26
	v_fma_f32 v24, v20, v24, v20
	v_fma_f32 v25, v16, v25, v16
	v_fma_f32 v26, v21, v26, v21
	v_mul_f32_e32 v24, 0xbfcc422a, v24
	v_mul_f32_e32 v25, 0xbfcc422a, v25
	v_mul_f32_e32 v26, 0xbfcc422a, v26
	v_mul_f32_e32 v24, 0x3fb8aa3b, v24
	v_mul_f32_e32 v25, 0x3fb8aa3b, v25
	v_mul_f32_e32 v26, 0x3fb8aa3b, v26
	v_exp_f32_e32 v24, v24
	v_exp_f32_e32 v25, v25
	v_exp_f32_e32 v26, v26
	v_mul_f32_e32 v27, 0x3d372713, v17
	v_add_f32_e32 v24, 1.0, v24
	v_add_f32_e32 v25, 1.0, v25
	v_add_f32_e32 v26, 1.0, v26
	v_rcp_f32_e32 v24, v24
	v_rcp_f32_e32 v25, v25
	v_rcp_f32_e32 v26, v26
	v_mul_f32_e32 v27, v17, v27
	v_fma_f32 v27, v17, v27, v17
	v_lshlrev_b32_e32 v30, 16, v43
	v_and_b32_e32 v31, 0xffff0000, v43
	v_mul_f32_e32 v27, 0xbfcc422a, v27
	v_pk_fma_f32 v[18:19], v[66:67], v[30:31], v[18:19]
	v_mul_f32_e32 v27, 0x3fb8aa3b, v27
	v_exp_f32_e32 v27, v27
	v_mul_f32_e32 v20, v20, v24
	v_mul_f32_e32 v24, v16, v25
	v_mul_f32_e32 v16, v21, v26
	v_mul_f32_e32 v25, 0x3d372713, v22
	v_mul_f32_e32 v26, 0x3d372713, v18
	v_mul_f32_e32 v25, v22, v25
	v_mul_f32_e32 v26, v18, v26
	v_fma_f32 v25, v22, v25, v22
	v_fma_f32 v26, v18, v26, v18
	v_mul_f32_e32 v25, 0xbfcc422a, v25
	v_mul_f32_e32 v26, 0xbfcc422a, v26
	v_add_f32_e32 v21, 1.0, v27
	v_mul_f32_e32 v25, 0x3fb8aa3b, v25
	v_mul_f32_e32 v26, 0x3fb8aa3b, v26
	v_rcp_f32_e32 v21, v21
	v_exp_f32_e32 v25, v25
	v_exp_f32_e32 v26, v26
	v_mul_f32_e32 v27, 0x3d372713, v19
	v_mul_f32_e32 v21, v17, v21
	v_add_f32_e32 v17, 1.0, v25
	v_add_f32_e32 v25, 1.0, v26
	v_mul_f32_e32 v26, 0x3d372713, v23
	v_mul_f32_e32 v26, v23, v26
	v_fma_f32 v26, v23, v26, v23
	v_mul_f32_e32 v26, 0xbfcc422a, v26
	v_mul_f32_e32 v26, 0x3fb8aa3b, v26
	v_exp_f32_e32 v26, v26
	v_mul_f32_e32 v27, v19, v27
	v_fma_f32 v27, v19, v27, v19
	v_mul_f32_e32 v27, 0xbfcc422a, v27
	v_mul_f32_e32 v27, 0x3fb8aa3b, v27
	v_add_f32_e32 v26, 1.0, v26
	v_rcp_f32_e32 v17, v17
	v_exp_f32_e32 v27, v27
	v_rcp_f32_e32 v25, v25
	v_rcp_f32_e32 v26, v26
	v_mul_f32_e32 v17, v22, v17
	v_add_f32_e32 v27, 1.0, v27
	v_mul_f32_e32 v22, v18, v25
	v_mul_f32_e32 v18, v23, v26
	v_cvt_pk_bf16_f32 v16, v20, v16
	v_lshl_add_u32 v20, v122, 4, v88
	v_rcp_f32_e32 v27, v27
	v_cvt_pk_bf16_f32 v17, v17, v18
	v_cvt_pk_bf16_f32 v18, v24, v21
	v_ashrrev_i32_e32 v21, 31, v20
	v_lshlrev_b64 v[20:21], 10, v[20:21]
	v_lshl_add_u64 v[20:21], v[174:175], 0, v[20:21]
	v_lshl_add_u64 v[20:21], s[56:57], 1, v[20:21]
	v_mov_b32_e32 v183, v153
	v_mul_f32_e32 v19, v19, v27
	v_lshl_add_u64 v[20:21], v[20:21], 0, v[182:183]
	v_cvt_pk_bf16_f32 v19, v22, v19
	global_store_dwordx4 v[20:21], v[16:19], off
	s_or_b64 exec, exec, s[8:9]
	s_and_saveexec_b64 s[8:9], s[10:11]
	s_cbranch_execnz .LBB0_427

; __device__ __forceinline__ float bf_lo(unsigned w) { return __uint_as_float(w << 16); }
; __device__ __forceinline__ float bf_hi(unsigned w) { return __uint_as_float(w & 0xffff0000u); }
; __device__ __forceinline__ u32x4 pack8(const f32x4 a, const f32x4 b) { u32x4 w; w.x = cvt_pk_bf16(a[0], a[1]); w.y = cvt_pk_bf16(a[2], a[3]); w.z = cvt_pk_bf16(b[0], b[1]); w.w = cvt_pk_bf16(b[2], b[3]); return w; }
;     __device__ __forceinline__ void operator()(EPI_ARGS) const {
;     ...
;                 for (int m = 0; m < 4; ++m) { const int j = row0 + ai * HALF + m * 16;
;                     uw[m] = (j < NJ) ? *(const u32x4*)(AB + ((size_t)((g >> 1) * NJP + j) * ABP + (g & 1) * 384 + n)) : (u32x4){0u, 0u, 0u, 0u}; }
; #pragma unroll
;                 for (int m = 0; m < 4; ++m) { const int j = row0 + ai * HALF + m * 16;
;                     if (j < NJ) {
;                         const u32x4 w = uw[m];
;                         f32x4 u0 = {bf_lo(w.x), bf_hi(w.x), bf_lo(w.y), bf_hi(w.y)}, u1 = {bf_lo(w.z), bf_hi(w.z), bf_lo(w.w), bf_hi(w.w)};
;                         f32x4 y0 = acc[ai][bj][m][0] + d0 * u0, y1 = acc[ai][bj][m][1] + d1 * u1;
; #pragma unroll
;                         for (int e = 0; e < 4; ++e) {
;                             { const float y = y0[e], q = 1.5957691216f * (y + 0.044715f * y * y * y); y0[e] = y * __builtin_amdgcn_rcpf(1.0f + __expf(-q)); }
;                             { const float y = y1[e], q = 1.5957691216f * (y + 0.044715f * y * y * y); y1[e] = y * __builtin_amdgcn_rcpf(1.0f + __expf(-q)); }
;                         }
;                         *(u32x4*)(Z + (size_t)(j * TS + t) * WA + g * 16 + c) = pack8(y0, y1);
.LBB0_423:
	v_lshlrev_b32_e32 v8, 16, v32
	v_and_b32_e32 v9, 0xffff0000, v32
	v_lshlrev_b32_e32 v12, 16, v34
	v_and_b32_e32 v13, 0xffff0000, v34
	v_lshlrev_b32_e32 v10, 16, v33
	v_and_b32_e32 v11, 0xffff0000, v33
	v_pk_fma_f32 v[4:5], v[68:69], v[8:9], v[4:5]
	v_pk_fma_f32 v[0:1], v[64:65], v[12:13], v[0:1]
	v_mul_f32_e32 v8, 0x3d372713, v4
	v_pk_fma_f32 v[6:7], v[70:71], v[10:11], v[6:7]
	v_mul_f32_e32 v9, 0x3d372713, v0
	v_mul_f32_e32 v10, 0x3d372713, v5
	v_mul_f32_e32 v8, v4, v8
	v_mul_f32_e32 v9, v0, v9
	v_mul_f32_e32 v10, v5, v10
	v_fma_f32 v8, v4, v8, v4
	v_fma_f32 v9, v0, v9, v0
	v_fma_f32 v10, v5, v10, v5
	v_mul_f32_e32 v8, 0xbfcc422a, v8
	v_mul_f32_e32 v9, 0xbfcc422a, v9
	v_mul_f32_e32 v10, 0xbfcc422a, v10
	v_mul_f32_e32 v8, 0x3fb8aa3b, v8
	v_mul_f32_e32 v9, 0x3fb8aa3b, v9
	v_mul_f32_e32 v10, 0x3fb8aa3b, v10
	v_exp_f32_e32 v8, v8
	v_exp_f32_e32 v9, v9
	v_exp_f32_e32 v10, v10
	v_mul_f32_e32 v11, 0x3d372713, v1
	v_add_f32_e32 v8, 1.0, v8
	v_add_f32_e32 v9, 1.0, v9
	v_add_f32_e32 v10, 1.0, v10
	v_rcp_f32_e32 v8, v8
	v_rcp_f32_e32 v9, v9
	v_rcp_f32_e32 v10, v10
	v_mul_f32_e32 v11, v1, v11
	v_fma_f32 v11, v1, v11, v1
	v_lshlrev_b32_e32 v14, 16, v35
	v_and_b32_e32 v15, 0xffff0000, v35
	v_mul_f32_e32 v11, 0xbfcc422a, v11
	v_pk_fma_f32 v[2:3], v[66:67], v[14:15], v[2:3]
	v_mul_f32_e32 v11, 0x3fb8aa3b, v11
	v_exp_f32_e32 v11, v11
	v_mul_f32_e32 v4, v4, v8
	v_mul_f32_e32 v8, v0, v9
	v_mul_f32_e32 v0, v5, v10
	v_mul_f32_e32 v9, 0x3d372713, v6
	v_mul_f32_e32 v10, 0x3d372713, v2
	v_mul_f32_e32 v9, v6, v9
	v_mul_f32_e32 v10, v2, v10
	v_fma_f32 v9, v6, v9, v6
	v_fma_f32 v10, v2, v10, v2
	v_mul_f32_e32 v9, 0xbfcc422a, v9
	v_mul_f32_e32 v10, 0xbfcc422a, v10
	v_add_f32_e32 v5, 1.0, v11
	v_mul_f32_e32 v9, 0x3fb8aa3b, v9
	v_mul_f32_e32 v10, 0x3fb8aa3b, v10
	v_rcp_f32_e32 v5, v5
	v_exp_f32_e32 v9, v9
	v_exp_f32_e32 v10, v10
	v_mul_f32_e32 v11, 0x3d372713, v3
	v_mul_f32_e32 v5, v1, v5
	v_add_f32_e32 v1, 1.0, v9
	v_add_f32_e32 v9, 1.0, v10
	v_mul_f32_e32 v10, 0x3d372713, v7
	v_mul_f32_e32 v10, v7, v10
	v_fma_f32 v10, v7, v10, v7
	v_mul_f32_e32 v10, 0xbfcc422a, v10
	v_mul_f32_e32 v10, 0x3fb8aa3b, v10
	v_exp_f32_e32 v10, v10
	v_mul_f32_e32 v11, v3, v11
	v_fma_f32 v11, v3, v11, v3
	v_mul_f32_e32 v11, 0xbfcc422a, v11
	v_mul_f32_e32 v11, 0x3fb8aa3b, v11
	v_add_f32_e32 v10, 1.0, v10
	v_rcp_f32_e32 v1, v1
	v_exp_f32_e32 v11, v11
	v_rcp_f32_e32 v9, v9
	v_rcp_f32_e32 v10, v10
	v_mul_f32_e32 v1, v6, v1
	v_add_f32_e32 v11, 1.0, v11
	v_mul_f32_e32 v6, v2, v9
	v_mul_f32_e32 v2, v7, v10
	v_cvt_pk_bf16_f32 v0, v4, v0
	v_lshl_add_u32 v4, v120, 4, v88
	v_rcp_f32_e32 v11, v11
	v_cvt_pk_bf16_f32 v1, v1, v2
	v_cvt_pk_bf16_f32 v2, v8, v5
	v_ashrrev_i32_e32 v5, 31, v4
	v_lshlrev_b64 v[4:5], 10, v[4:5]
	v_lshl_add_u64 v[4:5], v[174:175], 0, v[4:5]
	v_lshl_add_u64 v[4:5], s[56:57], 1, v[4:5]
	v_mov_b32_e32 v183, v153
	v_mul_f32_e32 v3, v3, v11
	v_lshl_add_u64 v[4:5], v[4:5], 0, v[182:183]
	v_cvt_pk_bf16_f32 v3, v6, v3
	global_store_dwordx4 v[4:5], v[0:3], off
	s_or_b64 exec, exec, s[8:9]
	s_and_b64 vcc, exec, s[4:5]
	s_mov_b64 s[4:5], -1
	s_cbranch_vccnz .LBB0_349
	s_branch .LBB0_429

; __device__ __forceinline__ float bf_lo(unsigned w) { return __uint_as_float(w << 16); }
; __device__ __forceinline__ float bf_hi(unsigned w) { return __uint_as_float(w & 0xffff0000u); }
; __device__ __forceinline__ u32x4 pack8(const f32x4 a, const f32x4 b) { u32x4 w; w.x = cvt_pk_bf16(a[0], a[1]); w.y = cvt_pk_bf16(a[2], a[3]); w.z = cvt_pk_bf16(b[0], b[1]); w.w = cvt_pk_bf16(b[2], b[3]); return w; }
;     __device__ __forceinline__ void operator()(EPI_ARGS) const {
;     ...
;                 for (int m = 0; m < 4; ++m) { const int j = row0 + ai * HALF + m * 16;
;                     uw[m] = (j < NJ) ? *(const u32x4*)(AB + ((size_t)((g >> 1) * NJP + j) * ABP + (g & 1) * 384 + n)) : (u32x4){0u, 0u, 0u, 0u}; }
; #pragma unroll
;                 for (int m = 0; m < 4; ++m) { const int j = row0 + ai * HALF + m * 16;
;                     if (j < NJ) {
;                         const u32x4 w = uw[m];
;                         f32x4 u0 = {bf_lo(w.x), bf_hi(w.x), bf_lo(w.y), bf_hi(w.y)}, u1 = {bf_lo(w.z), bf_hi(w.z), bf_lo(w.w), bf_hi(w.w)};
;                         f32x4 y0 = acc[ai][bj][m][0] + d0 * u0, y1 = acc[ai][bj][m][1] + d1 * u1;
; #pragma unroll
;                         for (int e = 0; e < 4; ++e) {
;                             { const float y = y0[e], q = 1.5957691216f * (y + 0.044715f * y * y * y); y0[e] = y * __builtin_amdgcn_rcpf(1.0f + __expf(-q)); }
;                             { const float y = y1[e], q = 1.5957691216f * (y + 0.044715f * y * y * y); y1[e] = y * __builtin_amdgcn_rcpf(1.0f + __expf(-q)); }
;                         }
;                         *(u32x4*)(Z + (size_t)(j * TS + t) * WA + g * 16 + c) = pack8(y0, y1);
.LBB0_427:
	v_lshlrev_b32_e32 v16, 16, v36
	v_and_b32_e32 v17, 0xffff0000, v36
	v_lshlrev_b32_e32 v20, 16, v38
	v_and_b32_e32 v21, 0xffff0000, v38
	v_lshlrev_b32_e32 v18, 16, v37
	v_and_b32_e32 v19, 0xffff0000, v37
	v_pk_fma_f32 v[12:13], v[68:69], v[16:17], v[12:13]
	v_pk_fma_f32 v[8:9], v[64:65], v[20:21], v[8:9]
	v_mul_f32_e32 v16, 0x3d372713, v12
	v_pk_fma_f32 v[14:15], v[70:71], v[18:19], v[14:15]
	v_mul_f32_e32 v17, 0x3d372713, v8
	v_mul_f32_e32 v18, 0x3d372713, v13
	v_mul_f32_e32 v16, v12, v16
	v_mul_f32_e32 v17, v8, v17
	v_mul_f32_e32 v18, v13, v18
	v_fma_f32 v16, v12, v16, v12
	v_fma_f32 v17, v8, v17, v8
	v_fma_f32 v18, v13, v18, v13
	v_mul_f32_e32 v16, 0xbfcc422a, v16
	v_mul_f32_e32 v17, 0xbfcc422a, v17
	v_mul_f32_e32 v18, 0xbfcc422a, v18
	v_mul_f32_e32 v16, 0x3fb8aa3b, v16
	v_mul_f32_e32 v17, 0x3fb8aa3b, v17
	v_mul_f32_e32 v18, 0x3fb8aa3b, v18
	v_exp_f32_e32 v16, v16
	v_exp_f32_e32 v17, v17
	v_exp_f32_e32 v18, v18
	v_mul_f32_e32 v19, 0x3d372713, v9
	v_add_f32_e32 v16, 1.0, v16
	v_add_f32_e32 v17, 1.0, v17
	v_add_f32_e32 v18, 1.0, v18
	v_rcp_f32_e32 v16, v16
	v_rcp_f32_e32 v17, v17
	v_rcp_f32_e32 v18, v18
	v_mul_f32_e32 v19, v9, v19
	v_fma_f32 v19, v9, v19, v9
	v_lshlrev_b32_e32 v22, 16, v39
	v_and_b32_e32 v23, 0xffff0000, v39
	v_mul_f32_e32 v19, 0xbfcc422a, v19
	v_pk_fma_f32 v[10:11], v[66:67], v[22:23], v[10:11]
	v_mul_f32_e32 v19, 0x3fb8aa3b, v19
	v_exp_f32_e32 v19, v19
	v_mul_f32_e32 v12, v12, v16
	v_mul_f32_e32 v16, v8, v17
	v_mul_f32_e32 v8, v13, v18
	v_mul_f32_e32 v17, 0x3d372713, v14
	v_mul_f32_e32 v18, 0x3d372713, v10
	v_mul_f32_e32 v17, v14, v17
	v_mul_f32_e32 v18, v10, v18
	v_fma_f32 v17, v14, v17, v14
	v_fma_f32 v18, v10, v18, v10
	v_mul_f32_e32 v17, 0xbfcc422a, v17
	v_mul_f32_e32 v18, 0xbfcc422a, v18
	v_add_f32_e32 v13, 1.0, v19
	v_mul_f32_e32 v17, 0x3fb8aa3b, v17
	v_mul_f32_e32 v18, 0x3fb8aa3b, v18
	v_rcp_f32_e32 v13, v13
	v_exp_f32_e32 v17, v17
	v_exp_f32_e32 v18, v18
	v_mul_f32_e32 v19, 0x3d372713, v11
	v_mul_f32_e32 v13, v9, v13
	v_add_f32_e32 v9, 1.0, v17
	v_add_f32_e32 v17, 1.0, v18
	v_mul_f32_e32 v18, 0x3d372713, v15
	v_mul_f32_e32 v18, v15, v18
	v_fma_f32 v18, v15, v18, v15
	v_mul_f32_e32 v18, 0xbfcc422a, v18
	v_mul_f32_e32 v18, 0x3fb8aa3b, v18
	v_exp_f32_e32 v18, v18
	v_mul_f32_e32 v19, v11, v19
	v_fma_f32 v19, v11, v19, v11
	v_mul_f32_e32 v19, 0xbfcc422a, v19
	v_mul_f32_e32 v19, 0x3fb8aa3b, v19
	v_add_f32_e32 v18, 1.0, v18
	v_rcp_f32_e32 v9, v9
	v_exp_f32_e32 v19, v19
	v_rcp_f32_e32 v17, v17
	v_rcp_f32_e32 v18, v18
	v_mul_f32_e32 v9, v14, v9
	v_add_f32_e32 v19, 1.0, v19
	v_mul_f32_e32 v14, v10, v17
	v_mul_f32_e32 v10, v15, v18
	v_cvt_pk_bf16_f32 v8, v12, v8
	v_lshl_add_u32 v12, v121, 4, v88
	v_rcp_f32_e32 v19, v19
	v_cvt_pk_bf16_f32 v9, v9, v10
	v_cvt_pk_bf16_f32 v10, v16, v13
	v_ashrrev_i32_e32 v13, 31, v12
	v_lshlrev_b64 v[12:13], 10, v[12:13]
	v_lshl_add_u64 v[12:13], v[174:175], 0, v[12:13]
	v_lshl_add_u64 v[12:13], s[56:57], 1, v[12:13]
	v_mov_b32_e32 v183, v153
	v_mul_f32_e32 v11, v11, v19
	v_lshl_add_u64 v[12:13], v[12:13], 0, v[182:183]
	v_cvt_pk_bf16_f32 v11, v14, v11
	global_store_dwordx4 v[12:13], v[8:11], off
	s_or_b64 exec, exec, s[8:9]
	s_and_saveexec_b64 s[8:9], s[6:7]
	s_cbranch_execnz .LBB0_423

; #define PG8_STAGE(bufoff, gbase, voff) do { _Pragma("unroll") for (int _i = 0; _i < 2; ++_i) \
;         __builtin_amdgcn_global_load_lds((const unsigned*)((const char*)(gbase) + (voff)[_i]), (LAS unsigned*)(lds + (bufoff) + ldsw + _i * 8192), 16, 0, 0); } while (0)
; #define PG8_LDA(dst, b, h) do { _Pragma("unroll") for (int m = 0; m < 4; ++m) _Pragma("unroll") for (int k = 0; k < 2; ++k) dst[m][k] = *(const LAS bf16x8*)(lds + PG8_SA(b, h) + aoff + m * 2048 + k * 1024); } while (0)
; #define PG8_LDB(dst, b, h) do { _Pragma("unroll") for (int n = 0; n < 2; ++n) _Pragma("unroll") for (int k = 0; k < 2; ++k) dst[n][k] = *(const LAS bf16x8*)(lds + PG8_SB(b, h) + boff + n * 2048 + k * 1024); } while (0)
; #define PG8_MMA(ai, bj, At, Bt) do { __builtin_amdgcn_s_setprio(1); _Pragma("unroll") for (int m = 0; m < 4; ++m) _Pragma("unroll") for (int n = 0; n < 2; ++n) _Pragma("unroll") for (int k = 0; k < 2; ++k) \
;         acc[ai][bj][m][n] = __builtin_amdgcn_mfma_f32_16x16x32_bf16(Bt[n][k], At[m][k], acc[ai][bj][m][n], 0, 0, 0); __builtin_amdgcn_s_setprio(0); } while (0)
; #define PG8_WAIT_V(n) asm volatile("s_waitcnt vmcnt(" #n ")" ::: "memory")
; #define PG8_WAIT_L(n) asm volatile("s_waitcnt lgkmcnt(" #n ")" ::: "memory")
; #define PG8_BAR __builtin_amdgcn_s_barrier()
; #define PG8_SCHED __builtin_amdgcn_sched_barrier(0)
; template <class Epi>
; __device__ __forceinline__ void gemm_phase(LAS unsigned char* lds, const Gemm g, const int G, const int cidx, const int tid, const Epi& E) {
;     ...
;         for (int t = 0; t < nt; t += 2) {
;             const bool last = (t == nt - 2);
;             const char* a1 = cA + (size_t)(t + 1) * kstep;
;             const char* a2 = last ? nA : cA + (size_t)(t + 2) * kstep; const char* b2 = last ? nB : cB + (size_t)(t + 2) * kstep;
;             const char* a3 = a2 + kstep; const char* b3 = b2 + kstep;
;             PG8_LDB(B0, 0, 0); PG8_LDB(B1, 0, 1); PG8_SCHED; PG8_LDA(At, 0, 0); PG8_STAGE(PG8_SA(1, 1), a1 + hstepA, voffA);
;             PG8_WAIT_V(8); PG8_WAIT_L(0); PG8_BAR; PG8_MMA(0, 0, At, B0); PG8_MMA(0, 1, At, B1); PG8_BAR; PG8_SCHED;
;             PG8_LDA(At, 0, 1); PG8_STAGE(PG8_SB(0, 0), b2, voffB); PG8_STAGE(PG8_SB(0, 1), b2 + hstepB, voffB); PG8_STAGE(PG8_SA(0, 0), a2, voffA);
;             PG8_WAIT_V(8); PG8_WAIT_L(0); PG8_BAR; PG8_MMA(1, 0, At, B0); PG8_MMA(1, 1, At, B1); PG8_BAR; PG8_SCHED;
.LBB0_509:
	s_cmp_eq_u32 s92, 0
	s_cselect_b32 s66, 1, 0
	s_lshl_b32 s66, s66, 8
	s_add_i32 s66, s66, 0x100
	s_add_u32 s16, s14, s66
	s_addc_u32 s17, s15, 0
	s_add_i32 s66, 0, 0x10000
	s_cmp_eq_u32 s92, 4
	s_cselect_b32 s53, s1, s17
	s_cselect_b32 s52, s0, s16
	v_add_u32_e32 v150, s66, v144
	s_cselect_b32 s19, s13, s65
	s_cselect_b32 s18, s12, s64
	s_add_i32 s67, 0, 0x14000
	ds_read_b128 v[138:141], v150
	ds_read_b128 v[146:149], v150 offset:1024
	ds_read_b128 v[164:167], v150 offset:2048
	ds_read_b128 v[168:171], v150 offset:3072
	v_add_u32_e32 v150, s67, v144
	ds_read_b128 v[172:175], v150
	ds_read_b128 v[176:179], v150 offset:1024
	ds_read_b128 v[180:183], v150 offset:2048
	ds_read_b128 v[184:187], v150 offset:3072
	v_lshl_add_u64 v[150:151], s[14:15], 0, v[134:135]
	s_add_i32 m0, s25, 0xc000
	ds_read_b128 v[188:191], v145
	ds_read_b128 v[210:213], v145 offset:1024
	ds_read_b128 v[214:217], v145 offset:2048
	ds_read_b128 v[218:221], v145 offset:3072
	ds_read_b128 v[222:225], v145 offset:4096
	ds_read_b128 v[226:229], v145 offset:5120
	ds_read_b128 v[230:233], v145 offset:6144
	ds_read_b128 v[234:237], v145 offset:7168
	global_load_lds_dwordx4 v[150:151], off
	v_lshl_add_u64 v[150:151], s[14:15], 0, v[136:137]
	s_add_i32 m0, s25, 0xe000
	s_nop 0
	global_load_lds_dwordx4 v[150:151], off
	s_waitcnt vmcnt(8)
	s_waitcnt lgkmcnt(0)
	s_barrier
	s_setprio 1
	s_waitcnt lgkmcnt(0)
	v_mfma_f32_16x16x32_bf16 v[124:127], v[138:141], v[188:191], v[124:127]
	v_mfma_f32_16x16x32_bf16 v[120:123], v[164:167], v[188:191], v[120:123]
	v_mfma_f32_16x16x32_bf16 v[108:111], v[138:141], v[214:217], v[108:111]
	v_mfma_f32_16x16x32_bf16 v[104:107], v[164:167], v[214:217], v[104:107]
	v_mfma_f32_16x16x32_bf16 v[92:95], v[138:141], v[222:225], v[92:95]
	v_mfma_f32_16x16x32_bf16 v[88:91], v[164:167], v[222:225], v[88:91]
	v_mfma_f32_16x16x32_bf16 v[76:79], v[138:141], v[230:233], v[76:79]
	v_mfma_f32_16x16x32_bf16 v[72:75], v[164:167], v[230:233], v[72:75]
	v_mfma_f32_16x16x32_bf16 v[124:127], v[146:149], v[210:213], v[124:127]
	v_mfma_f32_16x16x32_bf16 v[120:123], v[168:171], v[210:213], v[120:123]
	v_mfma_f32_16x16x32_bf16 v[108:111], v[146:149], v[218:221], v[108:111]
	v_mfma_f32_16x16x32_bf16 v[104:107], v[168:171], v[218:221], v[104:107]
	v_mfma_f32_16x16x32_bf16 v[92:95], v[146:149], v[226:229], v[92:95]
	v_mfma_f32_16x16x32_bf16 v[88:91], v[168:171], v[226:229], v[88:91]
	v_mfma_f32_16x16x32_bf16 v[76:79], v[146:149], v[234:237], v[76:79]
	v_mfma_f32_16x16x32_bf16 v[72:75], v[168:171], v[234:237], v[72:75]
	s_setprio 0
	s_setprio 1
	v_mfma_f32_16x16x32_bf16 v[116:119], v[172:175], v[188:191], v[116:119]
	v_mfma_f32_16x16x32_bf16 v[112:115], v[180:183], v[188:191], v[112:115]
	v_mfma_f32_16x16x32_bf16 v[100:103], v[172:175], v[214:217], v[100:103]
	v_mfma_f32_16x16x32_bf16 v[96:99], v[180:183], v[214:217], v[96:99]
	v_mfma_f32_16x16x32_bf16 v[84:87], v[172:175], v[222:225], v[84:87]
	v_mfma_f32_16x16x32_bf16 v[80:83], v[180:183], v[222:225], v[80:83]
	v_mfma_f32_16x16x32_bf16 v[68:71], v[172:175], v[230:233], v[68:71]
	v_mfma_f32_16x16x32_bf16 v[64:67], v[180:183], v[230:233], v[64:67]
	v_mfma_f32_16x16x32_bf16 v[116:119], v[176:179], v[210:213], v[116:119]
	v_mfma_f32_16x16x32_bf16 v[112:115], v[184:187], v[210:213], v[112:115]
	v_mfma_f32_16x16x32_bf16 v[100:103], v[176:179], v[218:221], v[100:103]
	v_mfma_f32_16x16x32_bf16 v[96:99], v[184:187], v[218:221], v[96:99]
	v_mfma_f32_16x16x32_bf16 v[84:87], v[176:179], v[226:229], v[84:87]
	v_mfma_f32_16x16x32_bf16 v[80:83], v[184:187], v[226:229], v[80:83]
	v_mfma_f32_16x16x32_bf16 v[68:71], v[176:179], v[234:237], v[68:71]
	v_mfma_f32_16x16x32_bf16 v[64:67], v[184:187], v[234:237], v[64:67]
	s_setprio 0
	s_barrier
	s_add_i32 s14, s66, s24
	v_lshl_add_u64 v[150:151], s[18:19], 0, v[152:153]
	s_mov_b32 m0, s14
	ds_read_b128 v[188:191], v145 offset:16384
	ds_read_b128 v[210:213], v145 offset:17408
	ds_read_b128 v[214:217], v145 offset:18432
	ds_read_b128 v[218:221], v145 offset:19456
	ds_read_b128 v[222:225], v145 offset:20480
	ds_read_b128 v[226:229], v145 offset:21504
	ds_read_b128 v[230:233], v145 offset:22528
	ds_read_b128 v[234:237], v145 offset:23552
	global_load_lds_dwordx4 v[150:151], off
	s_add_i32 m0, s14, 0x2000
	s_add_u32 s14, s18, 0x30000
	v_lshl_add_u64 v[192:193], s[18:19], 0, v[132:133]
	s_addc_u32 s15, s19, 0
	s_add_i32 s66, s67, s24
	global_load_lds_dwordx4 v[192:193], off
	v_lshl_add_u64 v[238:239], s[14:15], 0, v[152:153]
	s_mov_b32 m0, s66
	v_lshl_add_u64 v[240:241], s[52:53], 0, v[130:131]
	global_load_lds_dwordx4 v[238:239], off
	v_lshl_add_u64 v[238:239], s[14:15], 0, v[132:133]
	s_add_i32 m0, s66, 0x2000
	s_nop 0
	global_load_lds_dwordx4 v[238:239], off
	v_lshl_add_u64 v[238:239], s[52:53], 0, v[128:129]
	s_mov_b32 m0, s25
	s_nop 0
	global_load_lds_dwordx4 v[238:239], off
	s_mov_b32 m0, s29
	s_nop 0
	global_load_lds_dwordx4 v[240:241], off
	s_waitcnt vmcnt(8)
	s_waitcnt lgkmcnt(0)
	s_barrier
; #define PG8_STAGE(bufoff, gbase, voff) do { _Pragma("unroll") for (int _i = 0; _i < 2; ++_i) \
;         __builtin_amdgcn_global_load_lds((const unsigned*)((const char*)(gbase) + (voff)[_i]), (LAS unsigned*)(lds + (bufoff) + ldsw + _i * 8192), 16, 0, 0); } while (0)
; #define PG8_LDA(dst, b, h) do { _Pragma("unroll") for (int m = 0; m < 4; ++m) _Pragma("unroll") for (int k = 0; k < 2; ++k) dst[m][k] = *(const LAS bf16x8*)(lds + PG8_SA(b, h) + aoff + m * 2048 + k * 1024); } while (0)
; #define PG8_LDB(dst, b, h) do { _Pragma("unroll") for (int n = 0; n < 2; ++n) _Pragma("unroll") for (int k = 0; k < 2; ++k) dst[n][k] = *(const LAS bf16x8*)(lds + PG8_SB(b, h) + boff + n * 2048 + k * 1024); } while (0)
; #define PG8_MMA(ai, bj, At, Bt) do { __builtin_amdgcn_s_setprio(1); _Pragma("unroll") for (int m = 0; m < 4; ++m) _Pragma("unroll") for (int n = 0; n < 2; ++n) _Pragma("unroll") for (int k = 0; k < 2; ++k) \
;         acc[ai][bj][m][n] = __builtin_amdgcn_mfma_f32_16x16x32_bf16(Bt[n][k], At[m][k], acc[ai][bj][m][n], 0, 0, 0); __builtin_amdgcn_s_setprio(0); } while (0)
; #define PG8_WAIT_V(n) asm volatile("s_waitcnt vmcnt(" #n ")" ::: "memory")
; #define PG8_WAIT_L(n) asm volatile("s_waitcnt lgkmcnt(" #n ")" ::: "memory")
; #define PG8_BAR __builtin_amdgcn_s_barrier()
; #define PG8_SCHED __builtin_amdgcn_sched_barrier(0)
; template <class Epi>
; __device__ __forceinline__ void gemm_phase(LAS unsigned char* lds, const Gemm g, const int G, const int cidx, const int tid, const Epi& E) {
;     ...
;             PG8_WAIT_V(8); PG8_WAIT_L(0); PG8_BAR; PG8_MMA(1, 0, At, B0); PG8_MMA(1, 1, At, B1); PG8_BAR; PG8_SCHED;
;             PG8_LDB(B0, 1, 0); PG8_LDB(B1, 1, 1); PG8_SCHED; PG8_LDA(At, 1, 0); PG8_STAGE(PG8_SA(0, 1), a2 + hstepA, voffA);
;             PG8_WAIT_V(8); PG8_WAIT_L(0); PG8_BAR; PG8_MMA(0, 0, At, B0); PG8_MMA(0, 1, At, B1); PG8_BAR; PG8_SCHED;
	s_setprio 1
	s_waitcnt lgkmcnt(0)
	v_mfma_f32_16x16x32_bf16 v[60:63], v[138:141], v[188:191], v[60:63]
	v_mfma_f32_16x16x32_bf16 v[56:59], v[164:167], v[188:191], v[56:59]
	v_mfma_f32_16x16x32_bf16 v[44:47], v[138:141], v[214:217], v[44:47]
	v_mfma_f32_16x16x32_bf16 v[40:43], v[164:167], v[214:217], v[40:43]
	v_mfma_f32_16x16x32_bf16 v[28:31], v[138:141], v[222:225], v[28:31]
	v_mfma_f32_16x16x32_bf16 v[24:27], v[164:167], v[222:225], v[24:27]
	v_mfma_f32_16x16x32_bf16 v[12:15], v[138:141], v[230:233], v[12:15]
	v_mfma_f32_16x16x32_bf16 v[8:11], v[164:167], v[230:233], v[8:11]
	v_mfma_f32_16x16x32_bf16 v[60:63], v[146:149], v[210:213], v[60:63]
	v_mfma_f32_16x16x32_bf16 v[56:59], v[168:171], v[210:213], v[56:59]
	v_mfma_f32_16x16x32_bf16 v[44:47], v[146:149], v[218:221], v[44:47]
	v_mfma_f32_16x16x32_bf16 v[40:43], v[168:171], v[218:221], v[40:43]
	v_mfma_f32_16x16x32_bf16 v[28:31], v[146:149], v[226:229], v[28:31]
	v_mfma_f32_16x16x32_bf16 v[24:27], v[168:171], v[226:229], v[24:27]
	v_mfma_f32_16x16x32_bf16 v[12:15], v[146:149], v[234:237], v[12:15]
	v_mfma_f32_16x16x32_bf16 v[8:11], v[168:171], v[234:237], v[8:11]
	s_setprio 0
	s_setprio 1
	v_mfma_f32_16x16x32_bf16 v[52:55], v[172:175], v[188:191], v[52:55]
	v_mfma_f32_16x16x32_bf16 v[48:51], v[180:183], v[188:191], v[48:51]
	v_mfma_f32_16x16x32_bf16 v[36:39], v[172:175], v[214:217], v[36:39]
	v_mfma_f32_16x16x32_bf16 v[32:35], v[180:183], v[214:217], v[32:35]
	v_mfma_f32_16x16x32_bf16 v[20:23], v[172:175], v[222:225], v[20:23]
	v_mfma_f32_16x16x32_bf16 v[16:19], v[180:183], v[222:225], v[16:19]
	v_mfma_f32_16x16x32_bf16 v[4:7], v[172:175], v[230:233], v[4:7]
	v_mfma_f32_16x16x32_bf16 v[0:3], v[180:183], v[230:233], v[0:3]
	v_mfma_f32_16x16x32_bf16 v[52:55], v[176:179], v[210:213], v[52:55]
	v_mfma_f32_16x16x32_bf16 v[48:51], v[184:187], v[210:213], v[48:51]
	v_mfma_f32_16x16x32_bf16 v[36:39], v[176:179], v[218:221], v[36:39]
	v_mfma_f32_16x16x32_bf16 v[32:35], v[184:187], v[218:221], v[32:35]
	v_mfma_f32_16x16x32_bf16 v[20:23], v[176:179], v[226:229], v[20:23]
	v_mfma_f32_16x16x32_bf16 v[16:19], v[184:187], v[226:229], v[16:19]
	v_mfma_f32_16x16x32_bf16 v[4:7], v[176:179], v[234:237], v[4:7]
	v_mfma_f32_16x16x32_bf16 v[0:3], v[184:187], v[234:237], v[0:3]
	s_setprio 0
	s_barrier
	s_add_i32 s66, 0, 0x18000
	v_add_u32_e32 v158, s66, v144
	s_add_i32 s67, 0, 0x1c000
	ds_read_b128 v[138:141], v158
	ds_read_b128 v[146:149], v158 offset:1024
	ds_read_b128 v[164:167], v158 offset:2048
	ds_read_b128 v[168:171], v158 offset:3072
	v_add_u32_e32 v158, s67, v144
	ds_read_b128 v[172:175], v158
	ds_read_b128 v[176:179], v158 offset:1024
	ds_read_b128 v[180:183], v158 offset:2048
	ds_read_b128 v[184:187], v158 offset:3072
	s_add_u32 s14, s52, 0x30000
	s_addc_u32 s15, s53, 0
	s_mov_b32 m0, s31
	v_lshl_add_u64 v[242:243], s[14:15], 0, v[128:129]
	ds_read_b128 v[188:191], v145 offset:32768
	ds_read_b128 v[210:213], v145 offset:33792
	ds_read_b128 v[214:217], v145 offset:34816
	ds_read_b128 v[218:221], v145 offset:35840
	ds_read_b128 v[222:225], v145 offset:36864
	ds_read_b128 v[226:229], v145 offset:37888
	ds_read_b128 v[230:233], v145 offset:38912
	ds_read_b128 v[234:237], v145 offset:39936
	global_load_lds_dwordx4 v[242:243], off
	v_lshl_add_u64 v[242:243], s[14:15], 0, v[130:131]
	s_mov_b32 m0, s54
	s_nop 0
	global_load_lds_dwordx4 v[242:243], off
	s_waitcnt vmcnt(8)
	s_waitcnt lgkmcnt(0)
	s_barrier
	s_setprio 1
	s_waitcnt lgkmcnt(0)
	v_mfma_f32_16x16x32_bf16 v[124:127], v[138:141], v[188:191], v[124:127]
	v_mfma_f32_16x16x32_bf16 v[120:123], v[164:167], v[188:191], v[120:123]
	v_mfma_f32_16x16x32_bf16 v[108:111], v[138:141], v[214:217], v[108:111]
	v_mfma_f32_16x16x32_bf16 v[104:107], v[164:167], v[214:217], v[104:107]
	v_mfma_f32_16x16x32_bf16 v[92:95], v[138:141], v[222:225], v[92:95]
	v_mfma_f32_16x16x32_bf16 v[88:91], v[164:167], v[222:225], v[88:91]
	v_mfma_f32_16x16x32_bf16 v[76:79], v[138:141], v[230:233], v[76:79]
	v_mfma_f32_16x16x32_bf16 v[72:75], v[164:167], v[230:233], v[72:75]
	v_mfma_f32_16x16x32_bf16 v[124:127], v[146:149], v[210:213], v[124:127]
	v_mfma_f32_16x16x32_bf16 v[120:123], v[168:171], v[210:213], v[120:123]
	v_mfma_f32_16x16x32_bf16 v[108:111], v[146:149], v[218:221], v[108:111]
	v_mfma_f32_16x16x32_bf16 v[104:107], v[168:171], v[218:221], v[104:107]
	v_mfma_f32_16x16x32_bf16 v[92:95], v[146:149], v[226:229], v[92:95]
	v_mfma_f32_16x16x32_bf16 v[88:91], v[168:171], v[226:229], v[88:91]
	v_mfma_f32_16x16x32_bf16 v[76:79], v[146:149], v[234:237], v[76:79]
	v_mfma_f32_16x16x32_bf16 v[72:75], v[168:171], v[234:237], v[72:75]
	s_setprio 0
	s_setprio 1
	v_mfma_f32_16x16x32_bf16 v[116:119], v[172:175], v[188:191], v[116:119]
	v_mfma_f32_16x16x32_bf16 v[112:115], v[180:183], v[188:191], v[112:115]
	v_mfma_f32_16x16x32_bf16 v[100:103], v[172:175], v[214:217], v[100:103]
	v_mfma_f32_16x16x32_bf16 v[96:99], v[180:183], v[214:217], v[96:99]
	v_mfma_f32_16x16x32_bf16 v[84:87], v[172:175], v[222:225], v[84:87]
	v_mfma_f32_16x16x32_bf16 v[80:83], v[180:183], v[222:225], v[80:83]
	v_mfma_f32_16x16x32_bf16 v[68:71], v[172:175], v[230:233], v[68:71]
	v_mfma_f32_16x16x32_bf16 v[64:67], v[180:183], v[230:233], v[64:67]
	v_mfma_f32_16x16x32_bf16 v[116:119], v[176:179], v[210:213], v[116:119]
	v_mfma_f32_16x16x32_bf16 v[112:115], v[184:187], v[210:213], v[112:115]
	v_mfma_f32_16x16x32_bf16 v[100:103], v[176:179], v[218:221], v[100:103]
	v_mfma_f32_16x16x32_bf16 v[96:99], v[184:187], v[218:221], v[96:99]
	v_mfma_f32_16x16x32_bf16 v[84:87], v[176:179], v[226:229], v[84:87]
	v_mfma_f32_16x16x32_bf16 v[80:83], v[184:187], v[226:229], v[80:83]
	v_mfma_f32_16x16x32_bf16 v[68:71], v[176:179], v[234:237], v[68:71]
	v_mfma_f32_16x16x32_bf16 v[64:67], v[184:187], v[234:237], v[64:67]
	s_setprio 0
	s_barrier
; #define PG8_STAGE(bufoff, gbase, voff) do { _Pragma("unroll") for (int _i = 0; _i < 2; ++_i) \
;         __builtin_amdgcn_global_load_lds((const unsigned*)((const char*)(gbase) + (voff)[_i]), (LAS unsigned*)(lds + (bufoff) + ldsw + _i * 8192), 16, 0, 0); } while (0)
; #define PG8_LDA(dst, b, h) do { _Pragma("unroll") for (int m = 0; m < 4; ++m) _Pragma("unroll") for (int k = 0; k < 2; ++k) dst[m][k] = *(const LAS bf16x8*)(lds + PG8_SA(b, h) + aoff + m * 2048 + k * 1024); } while (0)
; #define PG8_MMA(ai, bj, At, Bt) do { __builtin_amdgcn_s_setprio(1); _Pragma("unroll") for (int m = 0; m < 4; ++m) _Pragma("unroll") for (int n = 0; n < 2; ++n) _Pragma("unroll") for (int k = 0; k < 2; ++k) \
;         acc[ai][bj][m][n] = __builtin_amdgcn_mfma_f32_16x16x32_bf16(Bt[n][k], At[m][k], acc[ai][bj][m][n], 0, 0, 0); __builtin_amdgcn_s_setprio(0); } while (0)
; #define PG8_WAIT_V(n) asm volatile("s_waitcnt vmcnt(" #n ")" ::: "memory")
; #define PG8_WAIT_L(n) asm volatile("s_waitcnt lgkmcnt(" #n ")" ::: "memory")
; #define PG8_BAR __builtin_amdgcn_s_barrier()
; #define PG8_SCHED __builtin_amdgcn_sched_barrier(0)
; template <class Epi>
; __device__ __forceinline__ void gemm_phase(LAS unsigned char* lds, const Gemm g, const int G, const int cidx, const int tid, const Epi& E) {
;     ...
;         for (int t = 0; t < nt; t += 2) {
;             const bool last = (t == nt - 2);
;             const char* a1 = cA + (size_t)(t + 1) * kstep;
;             const char* a2 = last ? nA : cA + (size_t)(t + 2) * kstep; const char* b2 = last ? nB : cB + (size_t)(t + 2) * kstep;
;             const char* a3 = a2 + kstep; const char* b3 = b2 + kstep;
;     ...
;             PG8_LDA(At, 1, 1); PG8_STAGE(PG8_SB(1, 0), b3, voffB); PG8_STAGE(PG8_SB(1, 1), b3 + hstepB, voffB); PG8_STAGE(PG8_SA(1, 0), a3, voffA);
;             PG8_WAIT_V(8); PG8_WAIT_L(0); PG8_BAR; PG8_MMA(1, 0, At, B0); PG8_MMA(1, 1, At, B1); PG8_BAR; PG8_SCHED;
;         }
	s_add_i32 s14, s66, s24
	v_lshl_add_u64 v[150:151], v[150:151], 0, s[96:97]
	s_mov_b32 m0, s14
	ds_read_b128 v[188:191], v145 offset:49152
	ds_read_b128 v[210:213], v145 offset:50176
	ds_read_b128 v[214:217], v145 offset:51200
	ds_read_b128 v[218:221], v145 offset:52224
	ds_read_b128 v[222:225], v145 offset:53248
	ds_read_b128 v[226:229], v145 offset:54272
	ds_read_b128 v[230:233], v145 offset:55296
	ds_read_b128 v[234:237], v145 offset:56320
	global_load_lds_dwordx4 v[150:151], off
	s_add_i32 m0, s14, 0x2000
	s_add_u32 s14, s18, 0x30080
	v_lshl_add_u64 v[150:151], v[192:193], 0, s[96:97]
	s_addc_u32 s15, s19, 0
	s_add_i32 s18, s67, s24
	global_load_lds_dwordx4 v[150:151], off
	v_lshl_add_u64 v[150:151], s[14:15], 0, v[152:153]
	s_mov_b32 m0, s18
	s_nop 0
	global_load_lds_dwordx4 v[150:151], off
	v_lshl_add_u64 v[150:151], s[14:15], 0, v[132:133]
	s_add_i32 m0, s18, 0x2000
	s_nop 0
	global_load_lds_dwordx4 v[150:151], off
	v_lshl_add_u64 v[150:151], v[238:239], 0, s[96:97]
	s_mov_b32 m0, s58
	s_nop 0
	global_load_lds_dwordx4 v[150:151], off
	v_lshl_add_u64 v[150:151], v[240:241], 0, s[96:97]
	s_mov_b32 m0, s59
	s_nop 0
	global_load_lds_dwordx4 v[150:151], off
	s_waitcnt vmcnt(8)
	s_waitcnt lgkmcnt(0)
	s_barrier
	s_setprio 1
	s_waitcnt lgkmcnt(0)
	v_mfma_f32_16x16x32_bf16 v[60:63], v[138:141], v[188:191], v[60:63]
	v_mfma_f32_16x16x32_bf16 v[56:59], v[164:167], v[188:191], v[56:59]
	v_mfma_f32_16x16x32_bf16 v[44:47], v[138:141], v[214:217], v[44:47]
	v_mfma_f32_16x16x32_bf16 v[40:43], v[164:167], v[214:217], v[40:43]
	v_mfma_f32_16x16x32_bf16 v[28:31], v[138:141], v[222:225], v[28:31]
	v_mfma_f32_16x16x32_bf16 v[24:27], v[164:167], v[222:225], v[24:27]
	v_mfma_f32_16x16x32_bf16 v[12:15], v[138:141], v[230:233], v[12:15]
	v_mfma_f32_16x16x32_bf16 v[8:11], v[164:167], v[230:233], v[8:11]
	v_mfma_f32_16x16x32_bf16 v[60:63], v[146:149], v[210:213], v[60:63]
	v_mfma_f32_16x16x32_bf16 v[56:59], v[168:171], v[210:213], v[56:59]
	v_mfma_f32_16x16x32_bf16 v[44:47], v[146:149], v[218:221], v[44:47]
	v_mfma_f32_16x16x32_bf16 v[40:43], v[168:171], v[218:221], v[40:43]
	v_mfma_f32_16x16x32_bf16 v[28:31], v[146:149], v[226:229], v[28:31]
	v_mfma_f32_16x16x32_bf16 v[24:27], v[168:171], v[226:229], v[24:27]
	v_mfma_f32_16x16x32_bf16 v[12:15], v[146:149], v[234:237], v[12:15]
	v_mfma_f32_16x16x32_bf16 v[8:11], v[168:171], v[234:237], v[8:11]
	s_setprio 0
	s_setprio 1
	v_mfma_f32_16x16x32_bf16 v[52:55], v[172:175], v[188:191], v[52:55]
	v_mfma_f32_16x16x32_bf16 v[48:51], v[180:183], v[188:191], v[48:51]
	v_mfma_f32_16x16x32_bf16 v[36:39], v[172:175], v[214:217], v[36:39]
	v_mfma_f32_16x16x32_bf16 v[32:35], v[180:183], v[214:217], v[32:35]
	v_mfma_f32_16x16x32_bf16 v[20:23], v[172:175], v[222:225], v[20:23]
	v_mfma_f32_16x16x32_bf16 v[16:19], v[180:183], v[222:225], v[16:19]
	v_mfma_f32_16x16x32_bf16 v[4:7], v[172:175], v[230:233], v[4:7]
	v_mfma_f32_16x16x32_bf16 v[0:3], v[180:183], v[230:233], v[0:3]
	v_mfma_f32_16x16x32_bf16 v[52:55], v[176:179], v[210:213], v[52:55]
	v_mfma_f32_16x16x32_bf16 v[48:51], v[184:187], v[210:213], v[48:51]
	v_mfma_f32_16x16x32_bf16 v[36:39], v[176:179], v[218:221], v[36:39]
	v_mfma_f32_16x16x32_bf16 v[32:35], v[184:187], v[218:221], v[32:35]
	v_mfma_f32_16x16x32_bf16 v[20:23], v[176:179], v[226:229], v[20:23]
	v_mfma_f32_16x16x32_bf16 v[16:19], v[184:187], v[226:229], v[16:19]
	v_mfma_f32_16x16x32_bf16 v[4:7], v[176:179], v[234:237], v[4:7]
	v_mfma_f32_16x16x32_bf16 v[0:3], v[184:187], v[234:237], v[0:3]
	s_setprio 0
	s_barrier
	s_add_i32 s92, s92, 2
	s_cmp_eq_u32 s92, 0
	s_cselect_b32 s66, 1, 0
	s_lshl_b32 s66, s66, 8
	s_add_i32 s66, s66, 0x100
	s_add_u32 s64, s64, s66
	s_addc_u32 s65, s65, 0
	s_cmp_gt_u32 s92, 5
	s_mov_b64 s[14:15], s[16:17]
	s_cbranch_scc0 .LBB0_509
	s_and_b64 vcc, exec, s[10:11]
	s_cbranch_vccz .LBB0_512
	s_barrier
